# v99 plus store-only vmcnt(0) waits removed in the phase-F loops and the layer-0 phase-J loop
# speedup vs baseline: 1.0141x; 1.0074x over previous
.LBB0_1218:
	v_pk_add_f32 v[2:3], v[58:59], v[68:69]
	v_pk_add_f32 v[4:5], v[60:61], v[66:67]
	v_pk_add_f32 v[6:7], v[64:65], v[56:57]
	v_pk_add_f32 v[2:3], v[2:3], v[4:5]
	v_add_f32_e32 v14, v20, v21
	v_add_f32_e32 v18, v22, v23
	v_and_b32_e32 v26, 64, v249
	v_pk_add_f32 v[4:5], v[6:7], v[6:7] op_sel:[0,1] op_sel_hi:[1,0]
	v_add_f32_e32 v2, 0, v2
	v_add_f32_e32 v28, v36, v37
	v_add_f32_e32 v32, v40, v41
	v_pk_add_f32 v[34:35], v[14:15], v[18:19]
	v_add_u32_e32 v14, 64, v26
	v_mov_b32_e32 v5, v31
	v_add_f32_e32 v26, v2, v3
	v_pk_add_f32 v[6:7], v[28:29], v[32:33]
	v_pk_add_f32 v[2:3], v[26:27], v[4:5]
	v_pk_add_f32 v[8:9], v[62:63], v[24:25]
	v_pk_add_f32 v[2:3], v[2:3], v[6:7]
	v_pk_add_f32 v[8:9], v[8:9], v[8:9] op_sel:[0,1] op_sel_hi:[1,0]
	v_pk_add_f32 v[2:3], v[2:3], v[2:3] op_sel:[0,1] op_sel_hi:[1,0]
	v_xor_b32_e32 v30, 1, v249
	v_mov_b32_e32 v9, v17
	v_mov_b32_e32 v3, v16
	v_cmp_lt_i32_e32 vcc, v30, v14
	v_pk_add_f32 v[2:3], v[2:3], v[8:9]
	v_xor_b32_e32 v38, 2, v249
	v_cndmask_b32_e32 v18, v249, v30, vcc
	v_pk_add_f32 v[2:3], v[2:3], v[34:35]
	v_lshlrev_b32_e32 v82, 2, v18
	v_add_f32_e32 v26, v2, v3
	s_nop 1
	v_mov_b32_dpp v84, v26 quad_perm:[1,0,3,2] row_mask:0xf bank_mask:0xf
	v_cmp_lt_i32_e32 vcc, v38, v14
	v_xor_b32_e32 v39, 4, v249
	v_xor_b32_e32 v42, 8, v249
	v_cndmask_b32_e32 v28, v249, v38, vcc
	v_lshlrev_b32_e32 v32, 2, v28
	s_waitcnt lgkmcnt(0)
	v_add_f32_e32 v26, v26, v84
	s_nop 1
	v_mov_b32_dpp v84, v26 quad_perm:[2,3,0,1] row_mask:0xf bank_mask:0xf
	v_cmp_lt_i32_e32 vcc, v39, v14
	v_xor_b32_e32 v43, 16, v249
	s_add_i32 s28, s8, s60
	v_cndmask_b32_e32 v30, v249, v39, vcc
	v_lshlrev_b32_e32 v30, 2, v30
	s_waitcnt lgkmcnt(0)
	v_add_f32_e32 v26, v26, v84
	s_nop 1
	v_mov_b32_dpp v84, v26 row_half_mirror row_mask:0xf bank_mask:0xf
	v_cmp_lt_i32_e32 vcc, v42, v14
	s_cmpk_lt_i32 s28, 0x2000
	v_xor_b32_e32 v44, 32, v249
	v_cndmask_b32_e32 v38, v249, v42, vcc
	v_lshlrev_b32_e32 v28, 2, v38
	s_waitcnt lgkmcnt(0)
	v_add_f32_e32 v26, v26, v84
	s_nop 1
	v_mov_b32_dpp v84, v26 row_mirror row_mask:0xf bank_mask:0xf
	v_cmp_lt_i32_e32 vcc, v43, v14
	s_cselect_b32 s8, s28, s8
	s_ashr_i32 s9, s8, 31
	v_cndmask_b32_e32 v39, v249, v43, vcc
	v_lshlrev_b32_e32 v18, 2, v39
	s_waitcnt lgkmcnt(0)
	v_add_f32_e32 v26, v26, v84
	v_mov_b32_e32 v84, v26
	v_mov_b32_e32 v107, v26
	s_nop 1
	v_permlane16_swap_b32_e32 v84, v107
	v_cmp_lt_i32_e32 vcc, v44, v14
	s_lshl_b64 s[8:9], s[8:9], 12
	s_add_u32 s30, s14, s20
	v_cndmask_b32_e32 v14, v249, v44, vcc
	v_lshlrev_b32_e32 v14, 2, v14
	s_waitcnt lgkmcnt(0)
	s_nop 1
	v_add_f32_e32 v26, v84, v107
	v_mov_b32_e32 v70, v1
	v_lshl_add_u64 v[4:5], v[12:13], 0, s[8:9]
	s_addc_u32 s31, s15, s21
	v_mov_b32_e32 v84, v26
	v_mov_b32_e32 v107, v26
	s_nop 1
	v_permlane32_swap_b32_e32 v84, v107
	global_load_dwordx2 v[54:55], v[4:5], off
	global_load_dwordx2 v[52:53], v[4:5], off offset:512
	global_load_dwordx2 v[50:51], v[4:5], off offset:1024
	global_load_dwordx2 v[48:49], v[4:5], off offset:1536
	global_load_dwordx2 v[46:47], v[4:5], off offset:2048
	global_load_dwordx2 v[44:45], v[4:5], off offset:2560
	global_load_dwordx2 v[42:43], v[4:5], off offset:3072
	global_load_dwordx2 v[38:39], v[4:5], off offset:3584
	s_add_u32 s8, s14, s18
	v_lshlrev_b32_e32 v4, 2, v70
	s_addc_u32 s9, s15, s19
	v_ashrrev_i32_e32 v5, 31, v4
	v_lshlrev_b64 v[6:7], 2, v[4:5]
	v_lshl_add_u64 v[4:5], v[4:5], 1, s[8:9]
	v_lshl_add_u64 v[76:77], s[16:17], 0, v[6:7]
	v_add_co_u32_e32 v34, vcc, s61, v4
	v_lshl_add_u64 v[74:75], s[10:11], 0, v[6:7]
	v_lshl_add_u64 v[78:79], s[30:31], 0, v[6:7]
	v_lshl_add_u64 v[72:73], s[24:25], 0, v[6:7]
	v_lshl_add_u64 v[70:71], s[22:23], 0, v[6:7]
	v_addc_co_u32_e32 v35, vcc, 0, v5, vcc
	s_nop 1
	v_mov_b64_e32 v[2:3], v[180:181]
	v_mov_b64_e32 v[4:5], v[182:183]
	s_nop 1
	v_mov_b64_e32 v[6:7], v[212:213]
	v_mov_b64_e32 v[8:9], v[214:215]
	s_waitcnt lgkmcnt(0)
	s_nop 1
	v_add_f32_e32 v26, v84, v107
	v_fmac_f32_e32 v66, 0xba000000, v26
	v_fmac_f32_e32 v68, 0xba000000, v26
	v_fmac_f32_e32 v67, 0xba000000, v26
	v_fmac_f32_e32 v69, 0xba000000, v26
	v_fmac_f32_e32 v64, 0xba000000, v26
	v_fmac_f32_e32 v57, 0xba000000, v26
	v_fmac_f32_e32 v65, 0xba000000, v26
	v_fmac_f32_e32 v60, 0xba000000, v26
	v_fmac_f32_e32 v58, 0xba000000, v26
	v_fmac_f32_e32 v61, 0xba000000, v26
	v_fmac_f32_e32 v59, 0xba000000, v26
	v_fmac_f32_e32 v56, 0xba000000, v26
	v_mov_b32_e32 v85, v69
	v_mov_b32_e32 v87, v68
	v_pk_mul_f32 v[68:69], v[68:69], v[68:69]
	v_mov_b32_e32 v89, v67
	v_mov_b32_e32 v91, v66
	v_pk_mul_f32 v[66:67], v[66:67], v[66:67]
	v_mov_b32_e32 v92, v65
	v_mov_b32_e32 v93, v57
	v_mov_b32_e32 v57, v64
	v_mov_b32_e32 v84, v59
	v_mov_b32_e32 v86, v58
	v_mov_b32_e32 v88, v61
	v_mov_b32_e32 v90, v60
	v_pk_fma_f32 v[58:59], v[58:59], v[58:59], v[68:69]
	v_pk_fma_f32 v[60:61], v[60:61], v[60:61], v[66:67]
	v_pk_mul_f32 v[66:67], v[92:93], v[92:93]
	v_pk_mul_f32 v[68:69], v[56:57], v[56:57]
	v_fmac_f32_e32 v36, 0xba000000, v26
	v_fmac_f32_e32 v40, 0xba000000, v26
	v_pk_add_f32 v[58:59], v[58:59], v[60:61]
	v_pk_mov_b32 v[60:61], v[68:69], v[66:67] op_sel:[1,0]
	v_mov_b32_e32 v69, v67
	v_fmac_f32_e32 v37, 0xba000000, v26
	v_fmac_f32_e32 v41, 0xba000000, v26
	v_fmac_f32_e32 v33, 0xba000000, v26
	v_fmac_f32_e32 v29, 0xba000000, v26
	v_fmac_f32_e32 v31, 0xba000000, v26
	v_fmac_f32_e32 v27, 0xba000000, v26
	v_fmac_f32_e32 v62, 0xba000000, v26
	v_fmac_f32_e32 v24, 0xba000000, v26
	v_fmac_f32_e32 v25, 0xba000000, v26
	v_fmac_f32_e32 v63, 0xba000000, v26
	v_fmac_f32_e32 v21, 0xba000000, v26
	v_fmac_f32_e32 v20, 0xba000000, v26
	v_fmac_f32_e32 v23, 0xba000000, v26
	v_fmac_f32_e32 v22, 0xba000000, v26
	v_fmac_f32_e32 v19, 0xba000000, v26
	v_fmac_f32_e32 v15, 0xba000000, v26
	v_fmac_f32_e32 v17, 0xba000000, v26
	v_fmac_f32_e32 v16, 0xba000000, v26
	v_mul_f32_e32 v26, v36, v36
	v_mul_f32_e32 v94, v40, v40
	v_pk_add_f32 v[60:61], v[60:61], v[68:69]
	v_mov_b32_e32 v64, v63
	v_mov_b32_e32 v65, v25
	v_mov_b32_e32 v25, v62
	v_pk_fma_f32 v[98:99], v[36:37], v[36:37], v[26:27] op_sel_hi:[1,1,0]
	v_pk_fma_f32 v[94:95], v[40:41], v[40:41], v[94:95] op_sel_hi:[1,1,0]
	v_pk_add_f32 v[58:59], v[58:59], v[58:59] op_sel_hi:[0,1]
	v_pk_add_f32 v[60:61], v[60:61], v[60:61] op_sel_hi:[0,1]
	v_pk_mul_f32 v[100:101], v[64:65], v[64:65]
	v_pk_mul_f32 v[102:103], v[24:25], v[24:25]
	v_mul_f32_e32 v98, v27, v27
	v_mul_f32_e32 v94, v31, v31
	v_mul_f32_e32 v58, v33, v33
	v_mul_f32_e32 v60, v29, v29
	v_pk_mov_b32 v[66:67], v[102:103], v[100:101] op_sel:[1,0]
	v_mov_b32_e32 v103, v101
	v_pk_add_f32 v[68:69], v[98:99], v[94:95]
	v_pk_add_f32 v[58:59], v[60:61], v[58:59]
	v_mul_f32_e32 v62, v20, v20
	v_mul_f32_e32 v96, v22, v22
	v_pk_add_f32 v[66:67], v[66:67], v[102:103]
	v_pk_add_f32 v[58:59], v[68:69], v[58:59]
	v_pk_fma_f32 v[62:63], v[20:21], v[20:21], v[62:63] op_sel_hi:[1,1,0]
	v_pk_fma_f32 v[96:97], v[22:23], v[22:23], v[96:97] op_sel_hi:[1,1,0]
	v_pk_add_f32 v[66:67], v[66:67], v[66:67] op_sel_hi:[0,1]
	v_pk_add_f32 v[58:59], v[58:59], v[58:59] op_sel_hi:[0,1]
	v_mul_f32_e32 v62, v16, v16
	v_mul_f32_e32 v96, v17, v17
	v_mul_f32_e32 v66, v15, v15
	v_mul_f32_e32 v58, v19, v19
	v_pk_add_f32 v[62:63], v[62:63], v[96:97]
	v_pk_add_f32 v[58:59], v[66:67], v[58:59]
	s_mov_b32 s8, 0x21b1e000
	v_pk_add_f32 v[58:59], v[62:63], v[58:59]
	v_add_co_u32_e32 v80, vcc, s8, v78
	v_add_f32_e32 v26, v58, v59
	s_nop 1
	v_mov_b32_dpp v58, v26 quad_perm:[1,0,3,2] row_mask:0xf bank_mask:0xf
	v_addc_co_u32_e32 v81, vcc, 0, v79, vcc
	v_add_co_u32_e32 v78, vcc, s70, v78
	s_waitcnt lgkmcnt(0)
	v_add_f32_e32 v26, v26, v58
	s_nop 1
	v_mov_b32_dpp v32, v26 quad_perm:[2,3,0,1] row_mask:0xf bank_mask:0xf
	v_addc_co_u32_e32 v79, vcc, 0, v79, vcc
	s_add_u32 s20, s20, s36
	s_addc_u32 s21, s21, s37
	s_waitcnt lgkmcnt(0)
	v_add_f32_e32 v26, v26, v32
	s_nop 1
	v_mov_b32_dpp v30, v26 row_half_mirror row_mask:0xf bank_mask:0xf
	s_add_u32 s18, s18, s38
	s_addc_u32 s19, s19, s39
	s_cmpk_gt_i32 s28, 0x1fff
	s_waitcnt vmcnt(7)
	v_and_b32_e32 v68, 0xffff0000, v54
	s_waitcnt lgkmcnt(0)
	v_add_f32_e32 v26, v26, v30
	s_nop 1
	v_mov_b32_dpp v28, v26 row_mirror row_mask:0xf bank_mask:0xf
	s_waitcnt vmcnt(6)
	v_and_b32_e32 v69, 0xffff0000, v52
	s_waitcnt lgkmcnt(0)
	v_add_f32_e32 v26, v26, v28
	v_mov_b32_e32 v18, v26
	v_mov_b32_e32 v107, v26
	s_nop 1
	v_permlane16_swap_b32_e32 v18, v107
	s_waitcnt lgkmcnt(0)
	s_nop 1
	v_add_f32_e32 v18, v18, v107
	v_mov_b32_e32 v14, v18
	v_mov_b32_e32 v107, v18
	s_nop 1
	v_permlane32_swap_b32_e32 v14, v107
	s_waitcnt lgkmcnt(0)
	s_nop 1
	v_add_f32_e32 v14, v14, v107
	v_fmamk_f32 v14, v14, 0x3a000000, v250
	v_mul_f32_e32 v18, 0x4f800000, v14
	v_cmp_gt_f32_e32 vcc, s96, v14
	s_nop 1
	v_cndmask_b32_e32 v14, v14, v18, vcc
	v_sqrt_f32_e32 v18, v14
	s_nop 0
	v_add_u32_e32 v26, -1, v18
	v_add_u32_e32 v28, 1, v18
	v_fma_f32 v30, -v26, v18, v14
	v_fma_f32 v32, -v28, v18, v14
	v_cmp_ge_f32_e64 s[8:9], 0, v30
	s_nop 1
	v_cndmask_b32_e64 v18, v18, v26, s[8:9]
	v_cmp_lt_f32_e64 s[8:9], 0, v32
	s_nop 1
	v_cndmask_b32_e64 v18, v18, v28, s[8:9]
	v_mul_f32_e32 v26, 0x37800000, v18
	v_cndmask_b32_e32 v18, v18, v26, vcc
	v_cmp_class_f32_e32 vcc, v14, v251
	s_nop 1
	v_cndmask_b32_e32 v14, v18, v14, vcc
	v_div_scale_f32 v18, s[8:9], v14, v14, 1.0
	v_rcp_f32_e32 v28, v18
	v_div_scale_f32 v26, vcc, 1.0, v14, 1.0
	s_mov_b32 s8, s28
	v_fma_f32 v30, -v18, v28, 1.0
	v_fmac_f32_e32 v28, v30, v28
	v_mul_f32_e32 v30, v26, v28
	v_fma_f32 v32, -v18, v30, v26
	v_fmac_f32_e32 v30, v32, v28
	v_fma_f32 v18, -v18, v30, v26
	v_div_fmas_f32 v18, v18, v28, v30
	v_div_fixup_f32 v14, v18, v14, 1.0
	v_pk_mul_f32 v[58:59], v[86:87], v[14:15] op_sel_hi:[1,0]
	v_pk_mul_f32 v[60:61], v[90:91], v[14:15] op_sel_hi:[1,0]
	s_waitcnt vmcnt(0)
	v_pk_fma_f32 v[2:3], v[2:3], v[58:59], v[6:7]
	v_pk_fma_f32 v[4:5], v[4:5], v[60:61], v[8:9]
	global_store_dwordx4 v[78:79], v[2:5], off offset:-4096
	ds_read_b128 v[6:9], v144
	ds_read_b128 v[58:61], v144 offset:8192
	v_pk_mul_f32 v[62:63], v[88:89], v[14:15] op_sel_hi:[1,0]
	v_pk_mul_f32 v[66:67], v[84:85], v[14:15] op_sel_hi:[1,0]
	v_pk_mul_f32 v[56:57], v[56:57], v[14:15] op_sel_hi:[1,0]
	v_pk_mul_f32 v[40:41], v[40:41], v[14:15] op_sel_hi:[1,0]
	v_pk_mul_f32 v[36:37], v[36:37], v[14:15] op_sel_hi:[1,0]
	v_mov_b32_e32 v32, v29
	v_mov_b32_e32 v30, v27
	v_pk_mul_f32 v[26:27], v[32:33], v[14:15] op_sel_hi:[1,0]
	v_pk_mul_f32 v[28:29], v[30:31], v[14:15] op_sel_hi:[1,0]
	v_pk_mul_f32 v[24:25], v[24:25], v[14:15] op_sel_hi:[1,0]
	v_pk_mul_f32 v[22:23], v[22:23], v[14:15] op_sel_hi:[1,0]
	v_pk_mul_f32 v[20:21], v[20:21], v[14:15] op_sel_hi:[1,0]
	v_mov_b32_e32 v18, v15
	v_pk_mul_f32 v[18:19], v[18:19], v[14:15] op_sel_hi:[1,0]
	v_lshlrev_b32_e32 v30, 16, v49
	v_and_b32_e32 v32, 0xffff0000, v46
	v_and_b32_e32 v33, 0xffff0000, v47
	v_mov_b32_e32 v31, v32
	s_waitcnt lgkmcnt(1)
	v_pk_add_f32 v[8:9], v[8:9], 1.0 op_sel_hi:[1,0]
	v_pk_add_f32 v[6:7], v[6:7], 1.0 op_sel_hi:[1,0]
	s_waitcnt lgkmcnt(0)
	v_pk_fma_f32 v[4:5], v[8:9], v[4:5], v[60:61]
	v_pk_fma_f32 v[2:3], v[6:7], v[2:3], v[58:59]
	v_cvt_pk_bf16_f32 v2, v2, v3
	v_cvt_pk_bf16_f32 v3, v4, v5
	global_store_dwordx2 v[34:35], v[2:3], off
	s_nop 1
	v_mov_b64_e32 v[2:3], v[184:185]
	v_mov_b64_e32 v[4:5], v[186:187]
	s_nop 0
	s_nop 1
	v_mov_b64_e32 v[6:7], v[216:217]
	v_mov_b64_e32 v[8:9], v[218:219]
	v_pk_fma_f32 v[2:3], v[2:3], v[66:67], v[6:7]
	v_pk_fma_f32 v[4:5], v[4:5], v[62:63], v[8:9]
	global_store_dwordx4 v[80:81], v[2:5], off offset:1024
	ds_read_b128 v[6:9], v144 offset:1024
	ds_read_b128 v[58:61], v144 offset:9216
	v_and_b32_e32 v62, 0xffff0000, v44
	v_lshlrev_b32_e32 v63, 16, v45
	v_and_b32_e32 v66, 0xffff0000, v55
	v_and_b32_e32 v67, 0xffff0000, v53
	s_waitcnt lgkmcnt(1)
	v_pk_add_f32 v[8:9], v[8:9], 1.0 op_sel_hi:[1,0]
	v_pk_add_f32 v[6:7], v[6:7], 1.0 op_sel_hi:[1,0]
	s_waitcnt lgkmcnt(0)
	v_pk_fma_f32 v[4:5], v[8:9], v[4:5], v[60:61]
	v_pk_fma_f32 v[2:3], v[6:7], v[2:3], v[58:59]
	v_cvt_pk_bf16_f32 v2, v2, v3
	v_cvt_pk_bf16_f32 v3, v4, v5
	global_store_dwordx2 v[34:35], v[2:3], off offset:512
	s_nop 1
	v_mov_b64_e32 v[2:3], v[188:189]
	v_mov_b64_e32 v[4:5], v[190:191]
	s_nop 0
	s_nop 1
	v_mov_b64_e32 v[6:7], v[220:221]
	v_mov_b64_e32 v[8:9], v[222:223]
	v_pk_mul_f32 v[58:59], v[92:93], v[14:15] op_sel_hi:[1,0]
	v_lshlrev_b32_e32 v60, 16, v55
	v_lshlrev_b32_e32 v61, 16, v53
	v_pk_fma_f32 v[2:3], v[2:3], v[56:57], v[6:7]
	v_pk_fma_f32 v[4:5], v[4:5], v[58:59], v[8:9]
	global_store_dwordx4 v[80:81], v[2:5], off offset:2048
	ds_read_b128 v[6:9], v144 offset:2048
	ds_read_b128 v[56:59], v144 offset:10240
	s_waitcnt lgkmcnt(1)
	v_pk_add_f32 v[8:9], v[8:9], 1.0 op_sel_hi:[1,0]
	v_pk_add_f32 v[6:7], v[6:7], 1.0 op_sel_hi:[1,0]
	s_waitcnt lgkmcnt(0)
	v_pk_fma_f32 v[4:5], v[4:5], v[8:9], v[58:59]
	v_pk_fma_f32 v[2:3], v[2:3], v[6:7], v[56:57]
	v_cvt_pk_bf16_f32 v2, v2, v3
	v_cvt_pk_bf16_f32 v3, v4, v5
	global_store_dwordx2 v[34:35], v[2:3], off offset:1024
	s_nop 1
	v_mov_b64_e32 v[2:3], v[192:193]
	v_mov_b64_e32 v[4:5], v[194:195]
	s_nop 0
	s_nop 1
	v_mov_b64_e32 v[6:7], v[236:237]
	v_mov_b64_e32 v[8:9], v[238:239]
	v_pk_fma_f32 v[2:3], v[36:37], v[2:3], v[6:7]
	v_pk_fma_f32 v[4:5], v[40:41], v[4:5], v[8:9]
	global_store_dwordx4 v[80:81], v[2:5], off offset:3072
	ds_read_b128 v[6:9], v144 offset:3072
	ds_read_b128 v[56:59], v144 offset:11264
	v_add_co_u32_e32 v36, vcc, s82, v76
	s_waitcnt lgkmcnt(1)
	v_pk_add_f32 v[8:9], v[8:9], 1.0 op_sel_hi:[1,0]
	v_pk_add_f32 v[6:7], v[6:7], 1.0 op_sel_hi:[1,0]
	s_waitcnt lgkmcnt(0)
	v_pk_fma_f32 v[4:5], v[4:5], v[8:9], v[58:59]
	v_pk_fma_f32 v[2:3], v[2:3], v[6:7], v[56:57]
	s_nop 0
	s_nop 0
	s_nop 0
	s_nop 0
	s_nop 0
	s_nop 0
	s_nop 0
	s_nop 0
	s_nop 0
	s_nop 0
	v_addc_co_u32_e32 v37, vcc, 0, v77, vcc
	v_cvt_pk_bf16_f32 v2, v2, v3
	v_cvt_pk_bf16_f32 v3, v4, v5
	v_add_co_u32_e32 v40, vcc, s82, v74
	global_store_dwordx2 v[34:35], v[2:3], off offset:1536
	s_nop 0
	v_addc_co_u32_e32 v41, vcc, 0, v75, vcc
	s_nop 1
	v_mov_b64_e32 v[2:3], v[196:197]
	v_mov_b64_e32 v[4:5], v[198:199]
	s_nop 1
	v_mov_b64_e32 v[6:7], v[240:241]
	v_mov_b64_e32 v[8:9], v[242:243]
	v_add_co_u32_e32 v56, vcc, s82, v72
	v_pk_fma_f32 v[2:3], v[28:29], v[2:3], v[6:7]
	v_addc_co_u32_e32 v57, vcc, 0, v73, vcc
	v_pk_fma_f32 v[4:5], v[26:27], v[4:5], v[8:9]
	v_add_co_u32_e32 v58, vcc, s82, v70
	global_store_dwordx4 v[78:79], v[2:5], off
	s_nop 0
	v_addc_co_u32_e32 v59, vcc, 0, v71, vcc
	ds_read_b128 v[6:9], v144 offset:4096
	ds_read_b128 v[26:29], v144 offset:12288
	s_waitcnt lgkmcnt(1)
	v_pk_add_f32 v[8:9], v[8:9], 1.0 op_sel_hi:[1,0]
	v_pk_add_f32 v[6:7], v[6:7], 1.0 op_sel_hi:[1,0]
	s_waitcnt lgkmcnt(0)
	v_pk_fma_f32 v[4:5], v[4:5], v[8:9], v[28:29]
	v_pk_fma_f32 v[2:3], v[2:3], v[6:7], v[26:27]
	v_cvt_pk_bf16_f32 v2, v2, v3
	v_cvt_pk_bf16_f32 v3, v4, v5
	global_store_dwordx2 v[34:35], v[2:3], off offset:2048
	s_nop 1
	v_mov_b64_e32 v[2:3], v[200:201]
	v_mov_b64_e32 v[4:5], v[202:203]
	s_nop 0
	s_nop 1
	v_mov_b64_e32 v[6:7], v[128:129]
	v_mov_b64_e32 v[8:9], v[130:131]
	v_pk_mul_f32 v[26:27], v[64:65], v[14:15] op_sel_hi:[1,0]
	v_pk_mul_f32 v[14:15], v[16:17], v[14:15] op_sel_hi:[1,0]
	v_and_b32_e32 v28, 0xffff0000, v48
	v_lshlrev_b32_e32 v29, 16, v47
	v_lshlrev_b32_e32 v47, 16, v43
	v_and_b32_e32 v43, 0xffff0000, v43
	v_and_b32_e32 v64, 0xffff0000, v50
	v_lshlrev_b32_e32 v65, 16, v51
	v_pk_fma_f32 v[2:3], v[24:25], v[2:3], v[6:7]
	v_pk_fma_f32 v[4:5], v[26:27], v[4:5], v[8:9]
	global_store_dwordx4 v[78:79], v[2:5], off offset:1024
	ds_read_b128 v[6:9], v144 offset:5120
	ds_read_b128 v[24:27], v144 offset:13312
	s_waitcnt lgkmcnt(1)
	v_pk_add_f32 v[8:9], v[8:9], 1.0 op_sel_hi:[1,0]
	v_pk_add_f32 v[6:7], v[6:7], 1.0 op_sel_hi:[1,0]
	s_waitcnt lgkmcnt(0)
	v_pk_fma_f32 v[4:5], v[4:5], v[8:9], v[26:27]
	v_pk_fma_f32 v[2:3], v[2:3], v[6:7], v[24:25]
	v_cvt_pk_bf16_f32 v2, v2, v3
	v_cvt_pk_bf16_f32 v3, v4, v5
	global_store_dwordx2 v[34:35], v[2:3], off offset:2560
	s_nop 1
	v_mov_b64_e32 v[2:3], v[204:205]
	v_mov_b64_e32 v[4:5], v[206:207]
	s_nop 0
	s_nop 1
	v_mov_b64_e32 v[6:7], v[132:133]
	v_mov_b64_e32 v[8:9], v[134:135]
	v_lshlrev_b32_e32 v26, 16, v48
	v_lshlrev_b32_e32 v27, 16, v46
	v_lshlrev_b32_e32 v46, 16, v44
	v_and_b32_e32 v44, 0xffff0000, v45
	v_lshlrev_b32_e32 v45, 16, v42
	v_and_b32_e32 v42, 0xffff0000, v42
	v_lshlrev_b32_e32 v48, 16, v38
	v_and_b32_e32 v38, 0xffff0000, v38
	v_mov_b32_e32 v24, v46
	v_mov_b32_e32 v25, v44
	v_mov_b32_e32 v16, v48
	v_mov_b32_e32 v17, v38
	v_pk_fma_f32 v[2:3], v[20:21], v[2:3], v[6:7]
	v_pk_fma_f32 v[4:5], v[22:23], v[4:5], v[8:9]
	global_store_dwordx4 v[78:79], v[2:5], off offset:2048
	ds_read_b128 v[6:9], v144 offset:6144
	ds_read_b128 v[20:23], v144 offset:14336
	s_waitcnt lgkmcnt(1)
	v_pk_add_f32 v[8:9], v[8:9], 1.0 op_sel_hi:[1,0]
	v_pk_add_f32 v[6:7], v[6:7], 1.0 op_sel_hi:[1,0]
	s_waitcnt lgkmcnt(0)
	v_pk_fma_f32 v[4:5], v[4:5], v[8:9], v[22:23]
	v_pk_fma_f32 v[2:3], v[2:3], v[6:7], v[20:21]
	v_cvt_pk_bf16_f32 v2, v2, v3
	v_cvt_pk_bf16_f32 v3, v4, v5
	global_store_dwordx2 v[34:35], v[2:3], off offset:3072
	s_nop 1
	v_mov_b64_e32 v[2:3], v[208:209]
	v_mov_b64_e32 v[4:5], v[210:211]
	s_nop 0
	s_nop 1
	v_mov_b64_e32 v[6:7], v[140:141]
	v_mov_b64_e32 v[8:9], v[142:143]
	v_lshlrev_b32_e32 v40, 16, v39
	v_and_b32_e32 v39, 0xffff0000, v39
	v_and_b32_e32 v41, 0xffff0000, v49
	v_mov_b32_e32 v36, v26
	v_mov_b32_e32 v37, v28
	v_mov_b32_e32 v20, v45
	v_mov_b32_e32 v21, v42
	v_mov_b32_e32 v22, v47
	v_mov_b32_e32 v23, v43
	v_pk_fma_f32 v[2:3], v[14:15], v[2:3], v[6:7]
	v_pk_fma_f32 v[4:5], v[18:19], v[4:5], v[8:9]
	global_store_dwordx4 v[78:79], v[2:5], off offset:3072
	ds_read_b128 v[6:9], v144 offset:7168
	ds_read_b128 v[70:73], v144 offset:15360
	v_lshlrev_b32_e32 v58, 16, v54
	v_lshlrev_b32_e32 v59, 16, v52
	v_lshlrev_b32_e32 v56, 16, v50
	v_and_b32_e32 v57, 0xffff0000, v51
	v_mov_b32_e32 v15, v40
	v_mov_b32_e32 v40, v30
	v_mov_b32_e32 v19, v39
	s_waitcnt lgkmcnt(1)
	v_pk_add_f32 v[8:9], v[8:9], 1.0 op_sel_hi:[1,0]
	v_pk_add_f32 v[6:7], v[6:7], 1.0 op_sel_hi:[1,0]
	s_waitcnt lgkmcnt(0)
	v_pk_fma_f32 v[4:5], v[4:5], v[8:9], v[72:73]
	v_pk_fma_f32 v[2:3], v[2:3], v[6:7], v[70:71]
	v_bfe_u32 v8, v4, 16, 1
	v_bfe_u32 v6, v2, 16, 1
	v_bfe_u32 v7, v3, 16, 1
	v_bfe_u32 v9, v5, 16, 1
	v_add3_u32 v2, v2, v6, s73
	v_add3_u32 v4, v4, v8, s73
	v_add3_u32 v3, v3, v7, s73
	v_add3_u32 v5, v5, v9, s73
	v_lshrrev_b32_e32 v2, 16, v2
	v_lshrrev_b32_e32 v4, 16, v4
	v_and_or_b32 v2, v3, s33, v2
	v_and_or_b32 v3, v5, s33, v4
	global_store_dwordx2 v[34:35], v[2:3], off offset:3584
	s_cbranch_scc0 .LBB0_1218

.LBB0_1222:
	s_abs_i32 s10, s8
	v_readlane_b32 s11, v253, 56
	s_mul_hi_u32 s11, s10, s11
	v_readlane_b32 s18, v253, 57
	s_mul_i32 s16, s11, s18
	s_ashr_i32 s9, s8, 31
	s_sub_i32 s10, s10, s16
	s_xor_b32 s9, s9, s43
	s_add_i32 s16, s11, 1
	s_sub_i32 s17, s10, s18
	s_cmp_ge_u32 s10, s18
	s_cselect_b32 s11, s16, s11
	s_cselect_b32 s10, s17, s10
	s_add_i32 s16, s11, 1
	s_cmp_ge_u32 s10, s18
	s_cselect_b32 s10, s16, s11
	s_xor_b32 s10, s10, s9
	s_sub_i32 s9, s10, s9
	s_add_i32 s9, s8, s9
	s_and_b32 s9, s9, 7
	v_readlane_b32 s10, v253, 15
	s_cmp_lg_u32 s10, s9
	s_cbranch_scc1 .LBB0_1221
	s_lshr_b32 s9, s8, 3
	s_add_i32 s16, s8, 0x2000
	s_add_i32 s9, s9, 1
	s_cmp_gt_i32 s8, -1
	s_cselect_b32 s9, s9, 0
	s_add_i32 s9, s9, s97
	s_mul_hi_u32 s11, s9, 0xc000
	s_mul_i32 s9, s9, 0xc000
	s_add_u32 s10, s26, s9
	v_lshl_add_u64 v[2:3], s[14:15], 0, v[12:13]
	s_mov_b32 s9, 0x3af5e000
	v_add_co_u32_e32 v8, vcc, s9, v2
	s_mov_b32 s9, 0x3af5f000
	s_nop 0
	v_addc_co_u32_e32 v9, vcc, 0, v3, vcc
	v_add_co_u32_e32 v62, vcc, s9, v2
	s_mov_b32 s9, 0x3b15e000
	s_nop 0
	v_addc_co_u32_e32 v63, vcc, 0, v3, vcc
	global_load_dwordx4 v[4:7], v[62:63], off offset:-4096
	global_load_dwordx4 v[38:41], v[8:9], off offset:1024
	global_load_dwordx4 v[42:45], v[8:9], off offset:2048
	global_load_dwordx4 v[46:49], v[8:9], off offset:3072
	global_load_dwordx4 v[50:53], v[62:63], off
	global_load_dwordx4 v[54:57], v[62:63], off offset:1024
	global_load_dwordx4 v[58:61], v[62:63], off offset:2048
	s_nop 0
	global_load_dwordx4 v[62:65], v[62:63], off offset:3072
	v_add_co_u32_e32 v8, vcc, s9, v2
	s_mov_b32 s9, 0x3b15f000
	s_nop 0
	v_addc_co_u32_e32 v9, vcc, 0, v3, vcc
	v_add_co_u32_e32 v96, vcc, s9, v2
	s_mov_b32 s9, 0x3b35e000
	s_nop 0
	v_addc_co_u32_e32 v97, vcc, 0, v3, vcc
	global_load_dwordx4 v[66:69], v[96:97], off offset:-4096
	global_load_dwordx4 v[70:73], v[8:9], off offset:1024
	global_load_dwordx4 v[74:77], v[8:9], off offset:2048
	global_load_dwordx4 v[78:81], v[8:9], off offset:3072
	global_load_dwordx4 v[84:87], v[96:97], off
	global_load_dwordx4 v[88:91], v[96:97], off offset:1024
	global_load_dwordx4 v[92:95], v[96:97], off offset:2048
	s_nop 0
	global_load_dwordx4 v[96:99], v[96:97], off offset:3072
	v_add_co_u32_e32 v8, vcc, s9, v2
	s_mov_b32 s9, 0x3b35f000
	s_nop 0
	v_addc_co_u32_e32 v9, vcc, 0, v3, vcc
	v_add_co_u32_e32 v128, vcc, s9, v2
	s_mov_b32 s9, 0x3b55e000
	s_nop 0
	v_addc_co_u32_e32 v129, vcc, 0, v3, vcc
	global_load_dwordx4 v[100:103], v[128:129], off offset:-4096
	global_load_dwordx4 v[104:107], v[8:9], off offset:1024
	global_load_dwordx4 v[108:111], v[8:9], off offset:2048
	global_load_dwordx4 v[112:115], v[8:9], off offset:3072
	global_load_dwordx4 v[116:119], v[128:129], off
	global_load_dwordx4 v[120:123], v[128:129], off offset:1024
	global_load_dwordx4 v[124:127], v[128:129], off offset:2048
	s_nop 0
	global_load_dwordx4 v[128:131], v[128:129], off offset:3072
	s_addc_u32 s11, s27, s11
	s_ashr_i32 s17, s16, 31
	s_waitcnt vmcnt(15)
	v_pk_add_f32 v[6:7], v[6:7], v[68:69]
	s_waitcnt vmcnt(14)
	v_pk_add_f32 v[8:9], v[40:41], v[72:73]
	s_waitcnt vmcnt(13)
	v_pk_add_f32 v[42:43], v[42:43], v[74:75]
	v_pk_add_f32 v[40:41], v[44:45], v[76:77]
	s_waitcnt vmcnt(12)
	v_pk_add_f32 v[44:45], v[48:49], v[80:81]
	s_waitcnt vmcnt(11)
	v_pk_add_f32 v[48:49], v[52:53], v[86:87]
	s_waitcnt vmcnt(10)
	v_pk_add_f32 v[52:53], v[56:57], v[90:91]
	s_waitcnt vmcnt(9)
	v_pk_add_f32 v[56:57], v[60:61], v[94:95]
	s_waitcnt vmcnt(8)
	v_pk_add_f32 v[60:61], v[64:65], v[98:99]
	v_pk_add_f32 v[58:59], v[58:59], v[92:93]
	v_pk_add_f32 v[4:5], v[4:5], v[66:67]
	v_pk_add_f32 v[38:39], v[38:39], v[70:71]
	v_pk_add_f32 v[50:51], v[50:51], v[84:85]
	s_waitcnt vmcnt(5)
	v_pk_add_f32 v[74:75], v[42:43], v[108:109]
	v_add_co_u32_e32 v42, vcc, s9, v2
	s_mov_b32 s9, 0x3b55f000
	s_nop 0
	v_addc_co_u32_e32 v43, vcc, 0, v3, vcc
	s_waitcnt vmcnt(0)
	v_pk_add_f32 v[92:93], v[60:61], v[130:131]
	v_add_co_u32_e32 v60, vcc, s9, v2
	v_pk_add_f32 v[54:55], v[54:55], v[88:89]
	v_pk_add_f32 v[62:63], v[62:63], v[96:97]
	v_addc_co_u32_e32 v61, vcc, 0, v3, vcc
	v_pk_add_f32 v[46:47], v[46:47], v[78:79]
	v_pk_add_f32 v[64:65], v[6:7], v[102:103]
	v_pk_add_f32 v[66:67], v[4:5], v[100:101]
	v_pk_add_f32 v[68:69], v[8:9], v[106:107]
	v_pk_add_f32 v[70:71], v[38:39], v[104:105]
	v_pk_add_f32 v[72:73], v[40:41], v[110:111]
	v_pk_add_f32 v[76:77], v[44:45], v[114:115]
	v_pk_add_f32 v[78:79], v[48:49], v[118:119]
	v_pk_add_f32 v[80:81], v[50:51], v[116:117]
	v_pk_add_f32 v[84:85], v[52:53], v[122:123]
	v_pk_add_f32 v[86:87], v[54:55], v[120:121]
	v_pk_add_f32 v[88:89], v[56:57], v[126:127]
	v_pk_add_f32 v[90:91], v[58:59], v[124:125]
	v_pk_add_f32 v[94:95], v[62:63], v[128:129]
	global_load_dwordx4 v[2:5], v[60:61], off offset:-4096
	global_load_dwordx4 v[6:9], v[42:43], off offset:1024
	global_load_dwordx4 v[38:41], v[42:43], off offset:2048
	s_nop 0
	global_load_dwordx4 v[42:45], v[42:43], off offset:3072
	s_nop 0
	global_load_dwordx4 v[48:51], v[60:61], off
	global_load_dwordx4 v[52:55], v[60:61], off offset:1024
	global_load_dwordx4 v[56:59], v[60:61], off offset:2048
	s_nop 0
	global_load_dwordx4 v[60:63], v[60:61], off offset:3072
	s_movk_i32 s9, 0x5000
	v_pk_add_f32 v[46:47], v[46:47], v[112:113]
	s_waitcnt vmcnt(7)
	v_pk_add_f32 v[64:65], v[4:5], v[64:65]
	s_waitcnt vmcnt(6)
	v_pk_add_f32 v[96:97], v[8:9], v[68:69]
	v_pk_add_f32 v[98:99], v[6:7], v[70:71]
	v_pk_add_f32 v[66:67], v[2:3], v[66:67]
	s_waitcnt vmcnt(4)
	v_pk_add_f32 v[44:45], v[44:45], v[76:77]
	s_waitcnt vmcnt(2)
	v_pk_add_f32 v[8:9], v[54:55], v[84:85]
	v_lshl_add_u64 v[54:55], v[10:11], 2, s[10:11]
	v_add_co_u32_e32 v6, vcc, s9, v54
	s_waitcnt vmcnt(1)
	v_pk_add_f32 v[2:3], v[58:59], v[88:89]
	v_addc_co_u32_e32 v7, vcc, 0, v55, vcc
	v_pk_add_f32 v[4:5], v[56:57], v[90:91]
	global_load_dwordx4 v[56:59], v[6:7], off offset:-4096
	v_lshl_add_u64 v[76:77], s[12:13], 0, v[12:13]
	v_pk_add_f32 v[72:73], v[40:41], v[72:73]
	v_pk_add_f32 v[46:47], v[42:43], v[46:47]
	v_pk_add_f32 v[40:41], v[50:51], v[78:79]
	v_pk_add_f32 v[42:43], v[48:49], v[80:81]
	global_load_dwordx4 v[48:51], v[76:77], off
	v_mov_b32_e32 v146, 0x1000
	v_mov_b32_e32 v147, 0
	v_lshl_add_u64 v[144:145], v[76:77], 0, v[146:147]
	global_load_dwordx4 v[180:183], v[76:77], off offset:1024
	global_load_dwordx4 v[184:187], v[6:7], off offset:-3072
	global_load_dwordx4 v[188:191], v[76:77], off offset:2048
	global_load_dwordx4 v[192:195], v[6:7], off offset:-2048
	global_load_dwordx4 v[196:199], v[76:77], off offset:3072
	global_load_dwordx4 v[200:203], v[6:7], off offset:-1024
	global_load_dwordx4 v[204:207], v[144:145], off
	global_load_dwordx4 v[208:211], v[6:7], off
	global_load_dwordx4 v[212:215], v[144:145], off offset:1024
	global_load_dwordx4 v[216:219], v[6:7], off offset:1024
	global_load_dwordx4 v[220:223], v[144:145], off offset:2048
	global_load_dwordx4 v[236:239], v[6:7], off offset:2048
	global_load_dwordx4 v[240:243], v[144:145], off offset:3072
	global_load_dwordx4 v[140:143], v[6:7], off offset:3072
	s_mov_b64 s[10:11], 0x4000
	v_pk_add_f32 v[74:75], v[38:39], v[74:75]
	v_pk_add_f32 v[38:39], v[52:53], v[86:87]
	v_lshl_add_u64 v[52:53], v[54:55], 0, s[10:11]
	s_waitcnt vmcnt(2)
	v_pk_add_f32 v[68:69], v[62:63], v[92:93]
	v_pk_add_f32 v[70:71], v[60:61], v[94:95]
	s_mov_b32 s9, 0x9000
	s_waitcnt vmcnt(1)
	v_pk_add_f32 v[58:59], v[58:59], 1.0 op_sel_hi:[1,0]
	v_pk_add_f32 v[56:57], v[56:57], 1.0 op_sel_hi:[1,0]
	v_pk_mul_f32 v[58:59], v[58:59], v[64:65]
	v_pk_mul_f32 v[56:57], v[56:57], v[66:67]
	s_waitcnt vmcnt(0)
	v_pk_fma_f32 v[64:65], v[50:51], s[92:93], v[58:59] op_sel_hi:[1,0,1]
	v_pk_fma_f32 v[66:67], v[48:49], s[92:93], v[56:57] op_sel_hi:[1,0,1]
	v_mov_b64_e32 v[48:49], v[180:181]
	v_mov_b64_e32 v[50:51], v[182:183]
	v_mov_b64_e32 v[56:57], v[184:185]
	v_mov_b64_e32 v[58:59], v[186:187]
	v_pk_add_f32 v[58:59], v[58:59], 1.0 op_sel_hi:[1,0]
	v_pk_add_f32 v[56:57], v[56:57], 1.0 op_sel_hi:[1,0]
	v_pk_mul_f32 v[58:59], v[96:97], v[58:59]
	v_pk_mul_f32 v[56:57], v[98:99], v[56:57]
	v_pk_fma_f32 v[60:61], v[50:51], s[92:93], v[58:59] op_sel_hi:[1,0,1]
	v_pk_fma_f32 v[62:63], v[48:49], s[92:93], v[56:57] op_sel_hi:[1,0,1]
	v_mov_b64_e32 v[48:49], v[188:189]
	v_mov_b64_e32 v[50:51], v[190:191]
	v_mov_b64_e32 v[56:57], v[192:193]
	v_mov_b64_e32 v[58:59], v[194:195]
	v_pk_add_f32 v[58:59], v[58:59], 1.0 op_sel_hi:[1,0]
	v_pk_add_f32 v[56:57], v[56:57], 1.0 op_sel_hi:[1,0]
	v_pk_mul_f32 v[58:59], v[58:59], v[72:73]
	v_pk_mul_f32 v[56:57], v[56:57], v[74:75]
	v_pk_fma_f32 v[58:59], v[50:51], s[92:93], v[58:59] op_sel_hi:[1,0,1]
	v_pk_fma_f32 v[56:57], v[48:49], s[92:93], v[56:57] op_sel_hi:[1,0,1]
	v_mov_b64_e32 v[48:49], v[196:197]
	v_mov_b64_e32 v[50:51], v[198:199]
	v_mov_b64_e32 v[72:73], v[200:201]
	v_mov_b64_e32 v[74:75], v[202:203]
	v_add_co_u32_e32 v76, vcc, s82, v76
	v_pk_add_f32 v[52:53], v[74:75], 1.0 op_sel_hi:[1,0]
	v_pk_add_f32 v[72:73], v[72:73], 1.0 op_sel_hi:[1,0]
	v_pk_mul_f32 v[44:45], v[44:45], v[52:53]
	v_pk_mul_f32 v[46:47], v[46:47], v[72:73]
	v_addc_co_u32_e32 v77, vcc, 0, v77, vcc
	v_pk_fma_f32 v[52:53], v[50:51], s[92:93], v[44:45] op_sel_hi:[1,0,1]
	v_pk_fma_f32 v[50:51], v[48:49], s[92:93], v[46:47] op_sel_hi:[1,0,1]
	v_mov_b64_e32 v[44:45], v[204:205]
	v_mov_b64_e32 v[46:47], v[206:207]
	v_mov_b64_e32 v[72:73], v[208:209]
	v_mov_b64_e32 v[74:75], v[210:211]
	v_pk_add_f32 v[48:49], v[74:75], 1.0 op_sel_hi:[1,0]
	v_pk_add_f32 v[72:73], v[72:73], 1.0 op_sel_hi:[1,0]
	v_pk_mul_f32 v[40:41], v[48:49], v[40:41]
	v_pk_mul_f32 v[42:43], v[72:73], v[42:43]
	v_pk_fma_f32 v[48:49], v[46:47], s[92:93], v[40:41] op_sel_hi:[1,0,1]
	v_pk_fma_f32 v[46:47], v[44:45], s[92:93], v[42:43] op_sel_hi:[1,0,1]
	v_mov_b64_e32 v[40:41], v[212:213]
	v_mov_b64_e32 v[42:43], v[214:215]
	v_mov_b64_e32 v[72:73], v[216:217]
	v_mov_b64_e32 v[74:75], v[218:219]
	v_pk_add_f32 v[44:45], v[74:75], 1.0 op_sel_hi:[1,0]
	v_pk_add_f32 v[72:73], v[72:73], 1.0 op_sel_hi:[1,0]
	v_pk_mul_f32 v[8:9], v[8:9], v[44:45]
	v_pk_mul_f32 v[38:39], v[38:39], v[72:73]
	v_pk_fma_f32 v[44:45], v[42:43], s[92:93], v[8:9] op_sel_hi:[1,0,1]
	v_pk_fma_f32 v[42:43], v[40:41], s[92:93], v[38:39] op_sel_hi:[1,0,1]
	v_mov_b64_e32 v[38:39], v[220:221]
	v_mov_b64_e32 v[40:41], v[222:223]
	v_mov_b64_e32 v[72:73], v[236:237]
	v_mov_b64_e32 v[74:75], v[238:239]
	v_pk_add_f32 v[8:9], v[74:75], 1.0 op_sel_hi:[1,0]
	v_pk_add_f32 v[72:73], v[72:73], 1.0 op_sel_hi:[1,0]
	v_pk_mul_f32 v[2:3], v[8:9], v[2:3]
	v_pk_mul_f32 v[4:5], v[72:73], v[4:5]
	v_pk_fma_f32 v[40:41], v[40:41], s[92:93], v[2:3] op_sel_hi:[1,0,1]
	v_pk_fma_f32 v[38:39], v[38:39], s[92:93], v[4:5] op_sel_hi:[1,0,1]
	v_mov_b64_e32 v[2:3], v[240:241]
	v_mov_b64_e32 v[4:5], v[242:243]
	s_nop 0
	v_mov_b64_e32 v[6:7], v[140:141]
	v_mov_b64_e32 v[8:9], v[142:143]
	v_pk_add_f32 v[8:9], v[8:9], 1.0 op_sel_hi:[1,0]
	v_pk_add_f32 v[6:7], v[6:7], 1.0 op_sel_hi:[1,0]
	v_pk_mul_f32 v[8:9], v[68:69], v[8:9]
	v_pk_mul_f32 v[6:7], v[70:71], v[6:7]
	v_pk_fma_f32 v[4:5], v[4:5], s[92:93], v[8:9] op_sel_hi:[1,0,1]
	v_pk_fma_f32 v[2:3], v[2:3], s[92:93], v[6:7] op_sel_hi:[1,0,1]
	v_mov_b32_e32 v6, v66
	v_mov_b32_e32 v7, v62
	v_mov_b32_e32 v8, v67
	v_mov_b32_e32 v9, v63
	v_pk_add_f32 v[6:7], v[6:7], v[8:9]
	v_mov_b32_e32 v8, v64
	v_mov_b32_e32 v9, v60
	v_mov_b32_e32 v68, v65
	v_mov_b32_e32 v69, v61
	v_pk_add_f32 v[8:9], v[8:9], v[68:69]
	v_mov_b32_e32 v68, v56
	v_pk_add_f32 v[6:7], v[6:7], v[8:9]
	v_pk_mov_b32 v[8:9], v[56:57], v[58:59] op_sel:[1,0]
	v_mov_b32_e32 v69, v59
	v_pk_add_f32 v[8:9], v[8:9], v[68:69]
	v_add_f32_e32 v1, 0, v6
	v_pk_add_f32 v[8:9], v[8:9], v[8:9] op_sel:[0,1] op_sel_hi:[1,0]
	v_add_f32_e32 v6, v1, v7
	v_add_f32_e32 v68, v50, v51
	v_add_f32_e32 v70, v52, v53
	v_mov_b32_e32 v7, v46
	v_mov_b32_e32 v9, v47
	v_mov_b32_e32 v69, v48
	v_mov_b32_e32 v71, v49
	v_pk_add_f32 v[6:7], v[6:7], v[8:9]
	v_pk_add_f32 v[8:9], v[68:69], v[70:71]
	v_mov_b32_e32 v68, v42
	v_pk_add_f32 v[6:7], v[6:7], v[8:9]
	v_pk_mov_b32 v[8:9], v[42:43], v[44:45] op_sel:[1,0]
	v_mov_b32_e32 v69, v45
	v_pk_add_f32 v[8:9], v[8:9], v[68:69]
	v_pk_add_f32 v[6:7], v[6:7], v[6:7] op_sel:[0,1] op_sel_hi:[1,0]
	v_pk_add_f32 v[8:9], v[8:9], v[8:9] op_sel:[0,1] op_sel_hi:[1,0]
	v_add_f32_e32 v68, v38, v39
	v_add_f32_e32 v70, v40, v41
	v_mov_b32_e32 v7, v2
	v_mov_b32_e32 v9, v3
	v_mov_b32_e32 v69, v4
	v_mov_b32_e32 v71, v5
	v_pk_add_f32 v[6:7], v[6:7], v[8:9]
	v_pk_add_f32 v[8:9], v[68:69], v[70:71]
	s_nop 0
	v_pk_add_f32 v[6:7], v[6:7], v[8:9]
	s_nop 0
	v_add_f32_e32 v1, v6, v7
	v_and_b32_e32 v6, 64, v249
	v_add_u32_e32 v6, 64, v6
	v_xor_b32_e32 v7, 1, v249
	v_cmp_lt_i32_e32 vcc, v7, v6
	s_nop 1
	v_cndmask_b32_e32 v7, v249, v7, vcc
	v_lshlrev_b32_e32 v72, 2, v7
	ds_bpermute_b32 v7, v72, v1
	s_waitcnt lgkmcnt(0)
	v_add_f32_e32 v1, v1, v7
	v_xor_b32_e32 v7, 2, v249
	v_cmp_lt_i32_e32 vcc, v7, v6
	s_nop 1
	v_cndmask_b32_e32 v7, v249, v7, vcc
	v_lshlrev_b32_e32 v73, 2, v7
	ds_bpermute_b32 v7, v73, v1
	s_waitcnt lgkmcnt(0)
	v_add_f32_e32 v1, v1, v7
	v_xor_b32_e32 v7, 4, v249
	v_cmp_lt_i32_e32 vcc, v7, v6
	s_nop 1
	v_cndmask_b32_e32 v7, v249, v7, vcc
	v_lshlrev_b32_e32 v74, 2, v7
	ds_bpermute_b32 v7, v74, v1
	s_waitcnt lgkmcnt(0)
	v_add_f32_e32 v1, v1, v7
	v_xor_b32_e32 v7, 8, v249
	v_cmp_lt_i32_e32 vcc, v7, v6
	s_nop 1
	v_cndmask_b32_e32 v7, v249, v7, vcc
	v_lshlrev_b32_e32 v75, 2, v7
	ds_bpermute_b32 v7, v75, v1
	s_waitcnt lgkmcnt(0)
	v_add_f32_e32 v1, v1, v7
	v_xor_b32_e32 v7, 16, v249
	v_cmp_lt_i32_e32 vcc, v7, v6
	s_nop 1
	v_cndmask_b32_e32 v7, v249, v7, vcc
	v_lshlrev_b32_e32 v76, 2, v7
	ds_bpermute_b32 v7, v76, v1
	s_waitcnt lgkmcnt(0)
	v_add_f32_e32 v1, v1, v7
	v_xor_b32_e32 v7, 32, v249
	v_cmp_lt_i32_e32 vcc, v7, v6
	s_nop 1
	v_cndmask_b32_e32 v6, v249, v7, vcc
	v_lshlrev_b32_e32 v77, 2, v6
	ds_bpermute_b32 v6, v77, v1
	s_waitcnt lgkmcnt(0)
	v_add_f32_e32 v1, v1, v6
	v_fmamk_f32 v67, v1, 0xba000000, v67
	v_fmamk_f32 v63, v1, 0xba000000, v63
	v_fmamk_f32 v65, v1, 0xba000000, v65
	v_fmac_f32_e32 v66, 0xba000000, v1
	v_fmamk_f32 v61, v1, 0xba000000, v61
	v_fmac_f32_e32 v62, 0xba000000, v1
	v_mov_b32_e32 v8, v67
	v_mov_b32_e32 v9, v63
	v_fmac_f32_e32 v64, 0xba000000, v1
	v_fmac_f32_e32 v60, 0xba000000, v1
	v_mov_b32_e32 v6, v66
	v_mov_b32_e32 v7, v62
	v_pk_mul_f32 v[8:9], v[8:9], v[8:9]
	v_mov_b32_e32 v68, v65
	v_mov_b32_e32 v69, v61
	v_pk_fma_f32 v[6:7], v[6:7], v[6:7], v[8:9]
	v_mov_b32_e32 v8, v64
	v_mov_b32_e32 v9, v60
	v_pk_mul_f32 v[68:69], v[68:69], v[68:69]
	v_fmamk_f32 v57, v1, 0xba000000, v57
	v_pk_fma_f32 v[8:9], v[8:9], v[8:9], v[68:69]
	v_fmac_f32_e32 v56, 0xba000000, v1
	v_pk_add_f32 v[6:7], v[6:7], v[8:9]
	v_fmamk_f32 v59, v1, 0xba000000, v59
	v_fmac_f32_e32 v58, 0xba000000, v1
	v_pk_add_f32 v[6:7], v[6:7], v[6:7] op_sel_hi:[0,1]
	v_pk_mul_f32 v[8:9], v[58:59], v[58:59]
	v_pk_mul_f32 v[68:69], v[56:57], v[56:57]
	v_fmac_f32_e32 v50, 0xba000000, v1
	v_pk_mov_b32 v[70:71], v[68:69], v[8:9] op_sel:[1,0]
	v_mov_b32_e32 v69, v9
	v_fmamk_f32 v51, v1, 0xba000000, v51
	v_fmac_f32_e32 v52, 0xba000000, v1
	v_mul_f32_e32 v6, v50, v50
	v_pk_add_f32 v[8:9], v[70:71], v[68:69]
	v_fmamk_f32 v53, v1, 0xba000000, v53
	v_pk_fma_f32 v[68:69], v[50:51], v[50:51], v[6:7] op_sel_hi:[1,1,0]
	v_mul_f32_e32 v6, v52, v52
	v_pk_add_f32 v[8:9], v[8:9], v[8:9] op_sel_hi:[0,1]
	v_pk_fma_f32 v[70:71], v[52:53], v[52:53], v[6:7] op_sel_hi:[1,1,0]
	v_fmamk_f32 v49, v1, 0xba000000, v49
	v_fmac_f32_e32 v48, 0xba000000, v1
	v_fmamk_f32 v47, v1, 0xba000000, v47
	v_fmac_f32_e32 v46, 0xba000000, v1
	v_mul_f32_e32 v68, v46, v46
	v_mul_f32_e32 v70, v47, v47
	v_mul_f32_e32 v8, v48, v48
	v_mul_f32_e32 v6, v49, v49
	v_pk_add_f32 v[68:69], v[68:69], v[70:71]
	v_pk_add_f32 v[6:7], v[8:9], v[6:7]
	v_fmamk_f32 v43, v1, 0xba000000, v43
	v_pk_add_f32 v[6:7], v[68:69], v[6:7]
	v_fmac_f32_e32 v42, 0xba000000, v1
	v_fmamk_f32 v45, v1, 0xba000000, v45
	v_fmac_f32_e32 v44, 0xba000000, v1
	v_pk_add_f32 v[6:7], v[6:7], v[6:7] op_sel_hi:[0,1]
	v_pk_mul_f32 v[8:9], v[44:45], v[44:45]
	v_pk_mul_f32 v[68:69], v[42:43], v[42:43]
	v_fmac_f32_e32 v38, 0xba000000, v1
	v_pk_mov_b32 v[70:71], v[68:69], v[8:9] op_sel:[1,0]
	v_mov_b32_e32 v69, v9
	v_fmamk_f32 v39, v1, 0xba000000, v39
	v_fmac_f32_e32 v40, 0xba000000, v1
	v_mul_f32_e32 v6, v38, v38
	v_pk_add_f32 v[8:9], v[70:71], v[68:69]
	v_fmamk_f32 v41, v1, 0xba000000, v41
	v_pk_fma_f32 v[68:69], v[38:39], v[38:39], v[6:7] op_sel_hi:[1,1,0]
	v_mul_f32_e32 v6, v40, v40
	v_pk_add_f32 v[8:9], v[8:9], v[8:9] op_sel_hi:[0,1]
	v_pk_fma_f32 v[70:71], v[40:41], v[40:41], v[6:7] op_sel_hi:[1,1,0]
	v_fmamk_f32 v5, v1, 0xba000000, v5
	v_fmac_f32_e32 v4, 0xba000000, v1
	v_fmamk_f32 v3, v1, 0xba000000, v3
	v_fmac_f32_e32 v2, 0xba000000, v1
	v_mul_f32_e32 v68, v2, v2
	v_mul_f32_e32 v70, v3, v3
	v_mul_f32_e32 v8, v4, v4
	v_mul_f32_e32 v6, v5, v5
	v_pk_add_f32 v[68:69], v[68:69], v[70:71]
	v_pk_add_f32 v[6:7], v[8:9], v[6:7]
	s_nop 0
	v_pk_add_f32 v[6:7], v[68:69], v[6:7]
	s_nop 0
	v_add_f32_e32 v1, v6, v7
	ds_bpermute_b32 v6, v72, v1
	s_waitcnt lgkmcnt(0)
	v_add_f32_e32 v1, v1, v6
	ds_bpermute_b32 v6, v73, v1
	s_waitcnt lgkmcnt(0)
	v_add_f32_e32 v1, v1, v6
	ds_bpermute_b32 v6, v74, v1
	s_waitcnt lgkmcnt(0)
	v_add_f32_e32 v1, v1, v6
	ds_bpermute_b32 v6, v75, v1
	s_waitcnt lgkmcnt(0)
	v_add_f32_e32 v1, v1, v6
	ds_bpermute_b32 v6, v76, v1
	s_waitcnt lgkmcnt(0)
	v_add_f32_e32 v1, v1, v6
	ds_bpermute_b32 v6, v77, v1
	s_waitcnt lgkmcnt(0)
	v_add_f32_e32 v1, v1, v6
	v_fmamk_f32 v1, v1, 0x3a000000, v250
	v_cmp_gt_f32_e32 vcc, s96, v1
	v_mul_f32_e32 v6, 0x4f800000, v1
	s_nop 0
	v_cndmask_b32_e32 v1, v1, v6, vcc
	v_sqrt_f32_e32 v6, v1
	s_nop 0
	v_add_u32_e32 v7, -1, v6
	v_fma_f32 v8, -v7, v6, v1
	v_cmp_ge_f32_e64 s[10:11], 0, v8
	v_add_u32_e32 v8, 1, v6
	s_nop 0
	v_cndmask_b32_e64 v7, v6, v7, s[10:11]
	v_fma_f32 v6, -v8, v6, v1
	v_cmp_lt_f32_e64 s[10:11], 0, v6
	s_nop 1
	v_cndmask_b32_e64 v6, v7, v8, s[10:11]
	v_mul_f32_e32 v7, 0x37800000, v6
	v_cndmask_b32_e32 v6, v6, v7, vcc
	v_cmp_class_f32_e32 vcc, v1, v251
	s_nop 1
	v_cndmask_b32_e32 v1, v6, v1, vcc
	v_div_scale_f32 v6, s[10:11], v1, v1, 1.0
	v_rcp_f32_e32 v7, v6
	s_lshl_b64 s[10:11], s[16:17], 13
	v_fma_f32 v8, -v6, v7, 1.0
	v_fmac_f32_e32 v7, v8, v7
	v_div_scale_f32 v8, vcc, 1.0, v1, 1.0
	v_mul_f32_e32 v9, v8, v7
	v_fma_f32 v68, -v6, v9, v8
	v_fmac_f32_e32 v9, v68, v7
	global_load_dwordx4 v[180:183], v[14:15], off
	global_load_dwordx4 v[184:187], v[16:17], off
	s_waitcnt vmcnt(0)
	s_nop 1
	v_mov_b64_e32 v[68:69], v[180:181]
	v_mov_b64_e32 v[70:71], v[182:183]
	s_nop 1
	v_mov_b64_e32 v[72:73], v[184:185]
	v_mov_b64_e32 v[74:75], v[186:187]
	v_fma_f32 v6, -v6, v9, v8
	v_div_fmas_f32 v6, v6, v7, v9
	v_div_fixup_f32 v6, v6, v1, 1.0
	v_pk_mul_f32 v[64:65], v[64:65], v[6:7] op_sel_hi:[1,0]
	v_pk_mul_f32 v[8:9], v[66:67], v[6:7] op_sel_hi:[1,0]
	v_lshl_add_u64 v[66:67], v[34:35], 0, s[10:11]
	s_mov_b64 s[10:11], 0x8000
	v_lshl_add_u64 v[80:81], v[54:55], 0, s[10:11]
	s_mov_b64 s[10:11], 0x6000
	v_lshl_add_u64 v[84:85], v[54:55], 0, s[10:11]
	s_lshl_b64 s[10:11], s[16:17], 12
	s_nop 0
	v_pk_fma_f32 v[70:71], v[70:71], v[64:65], v[74:75]
	v_add_co_u32_e32 v64, vcc, s9, v54
	v_pk_fma_f32 v[68:69], v[68:69], v[8:9], v[72:73]
	s_nop 0
	v_addc_co_u32_e32 v65, vcc, 0, v55, vcc
	s_movk_i32 s9, 0x7000
	global_store_dwordx4 v[66:67], v[68:71], off
	v_add_co_u32_e32 v54, vcc, s9, v54
	global_load_dwordx4 v[180:183], v[64:65], off offset:-4096
	s_waitcnt vmcnt(0)
	s_nop 1
	v_mov_b64_e32 v[72:73], v[180:181]
	v_mov_b64_e32 v[74:75], v[182:183]
	s_nop 0
	v_addc_co_u32_e32 v55, vcc, 0, v55, vcc
	global_load_dwordx4 v[180:183], v[54:55], off offset:-4096
	global_load_dwordx4 v[184:187], v[14:15], off offset:1024
	global_load_dwordx4 v[188:191], v[16:17], off offset:1024
	global_load_dwordx4 v[192:195], v[80:81], off offset:1024
	global_load_dwordx4 v[196:199], v[84:85], off offset:1024
	global_load_dwordx4 v[200:203], v[14:15], off offset:2048
	global_load_dwordx4 v[204:207], v[16:17], off offset:2048
	global_load_dwordx4 v[208:211], v[80:81], off offset:2048
	global_load_dwordx4 v[212:215], v[84:85], off offset:2048
	global_load_dwordx4 v[216:219], v[14:15], off offset:3072
	global_load_dwordx4 v[220:223], v[16:17], off offset:3072
	s_waitcnt vmcnt(0)
	s_nop 1
	v_mov_b64_e32 v[76:77], v[180:181]
	v_mov_b64_e32 v[78:79], v[182:183]
	s_nop 0
	v_pk_add_f32 v[72:73], v[72:73], 1.0 op_sel_hi:[1,0]
	v_pk_add_f32 v[8:9], v[74:75], 1.0 op_sel_hi:[1,0]
	s_nop 0
	v_pk_fma_f32 v[68:69], v[72:73], v[68:69], v[76:77]
	s_nop 0
	s_nop 0
	s_nop 0
	s_nop 0
	v_pk_fma_f32 v[8:9], v[8:9], v[70:71], v[78:79]
	s_nop 0
	s_nop 0
	v_cvt_pk_bf16_f32 v68, v68, v69
	v_bfe_u32 v1, v8, 16, 1
	v_add3_u32 v1, v8, v1, s73
	v_bfe_u32 v7, v9, 16, 1
	v_lshrrev_b32_e32 v1, 16, v1
	v_add3_u32 v7, v9, v7, s73
	v_and_or_b32 v69, v7, s33, v1
	v_lshl_add_u64 v[8:9], v[36:37], 0, s[10:11]
	global_store_dwordx2 v[8:9], v[68:69], off
	s_nop 1
	v_mov_b64_e32 v[68:69], v[184:185]
	v_mov_b64_e32 v[70:71], v[186:187]
	s_nop 0
	s_nop 1
	v_mov_b64_e32 v[72:73], v[188:189]
	v_mov_b64_e32 v[74:75], v[190:191]
	v_pk_mul_f32 v[76:77], v[60:61], v[6:7] op_sel_hi:[1,0]
	v_pk_mul_f32 v[60:61], v[62:63], v[6:7] op_sel_hi:[1,0]
	s_nop 0
	v_pk_fma_f32 v[62:63], v[70:71], v[76:77], v[74:75]
	v_pk_fma_f32 v[60:61], v[68:69], v[60:61], v[72:73]
	global_store_dwordx4 v[66:67], v[60:63], off offset:1024
	s_nop 1
	v_mov_b64_e32 v[68:69], v[192:193]
	v_mov_b64_e32 v[70:71], v[194:195]
	s_nop 1
	v_mov_b64_e32 v[72:73], v[196:197]
	v_mov_b64_e32 v[74:75], v[198:199]
	s_nop 0
	v_pk_add_f32 v[68:69], v[68:69], 1.0 op_sel_hi:[1,0]
	s_nop 0
	v_pk_fma_f32 v[60:61], v[68:69], v[60:61], v[72:73]
	v_pk_add_f32 v[70:71], v[70:71], 1.0 op_sel_hi:[1,0]
	v_pk_fma_f32 v[62:63], v[70:71], v[62:63], v[74:75]
	v_cvt_pk_bf16_f32 v60, v60, v61
	v_bfe_u32 v1, v62, 16, 1
	v_add3_u32 v1, v62, v1, s73
	v_bfe_u32 v7, v63, 16, 1
	v_lshrrev_b32_e32 v1, 16, v1
	v_add3_u32 v7, v63, v7, s73
	v_and_or_b32 v61, v7, s33, v1
	global_store_dwordx2 v[8:9], v[60:61], off offset:512
	s_nop 1
	v_mov_b64_e32 v[60:61], v[200:201]
	v_mov_b64_e32 v[62:63], v[202:203]
	s_nop 0
	s_nop 1
	v_mov_b64_e32 v[68:69], v[204:205]
	v_mov_b64_e32 v[70:71], v[206:207]
	v_pk_mul_f32 v[58:59], v[58:59], v[6:7] op_sel_hi:[1,0]
	v_pk_mul_f32 v[56:57], v[56:57], v[6:7] op_sel_hi:[1,0]
	s_nop 0
	v_pk_fma_f32 v[58:59], v[62:63], v[58:59], v[70:71]
	v_pk_fma_f32 v[56:57], v[60:61], v[56:57], v[68:69]
	global_store_dwordx4 v[66:67], v[56:59], off offset:2048
	s_nop 1
	v_mov_b64_e32 v[60:61], v[208:209]
	v_mov_b64_e32 v[62:63], v[210:211]
	s_nop 1
	v_mov_b64_e32 v[68:69], v[212:213]
	v_mov_b64_e32 v[70:71], v[214:215]
	s_nop 0
	v_pk_add_f32 v[60:61], v[60:61], 1.0 op_sel_hi:[1,0]
	s_nop 0
	v_pk_fma_f32 v[56:57], v[56:57], v[60:61], v[68:69]
	v_pk_add_f32 v[62:63], v[62:63], 1.0 op_sel_hi:[1,0]
	v_pk_fma_f32 v[58:59], v[58:59], v[62:63], v[70:71]
	v_cvt_pk_bf16_f32 v56, v56, v57
	v_bfe_u32 v1, v58, 16, 1
	v_add3_u32 v1, v58, v1, s73
	v_bfe_u32 v7, v59, 16, 1
	v_lshrrev_b32_e32 v1, 16, v1
	v_add3_u32 v7, v59, v7, s73
	v_and_or_b32 v57, v7, s33, v1
	global_store_dwordx2 v[8:9], v[56:57], off offset:1024
	s_nop 1
	v_mov_b64_e32 v[56:57], v[216:217]
	v_mov_b64_e32 v[58:59], v[218:219]
	s_nop 0
	s_nop 1
	v_mov_b64_e32 v[60:61], v[220:221]
	v_mov_b64_e32 v[62:63], v[222:223]
	v_pk_mul_f32 v[52:53], v[52:53], v[6:7] op_sel_hi:[1,0]
	v_pk_mul_f32 v[50:51], v[50:51], v[6:7] op_sel_hi:[1,0]
	s_nop 0
	v_pk_fma_f32 v[52:53], v[52:53], v[58:59], v[62:63]
	v_pk_fma_f32 v[50:51], v[50:51], v[56:57], v[60:61]
	global_store_dwordx4 v[66:67], v[50:53], off offset:3072
	global_load_dwordx4 v[180:183], v[80:81], off offset:3072
	global_load_dwordx4 v[184:187], v[84:85], off offset:3072
	global_load_dwordx4 v[188:191], v[18:19], off
	global_load_dwordx4 v[192:195], v[20:21], off
	global_load_dwordx4 v[196:199], v[64:65], off
	global_load_dwordx4 v[200:203], v[54:55], off
	global_load_dwordx4 v[204:207], v[22:23], off
	global_load_dwordx4 v[208:211], v[24:25], off
	global_load_dwordx4 v[212:215], v[64:65], off offset:1024
	global_load_dwordx4 v[216:219], v[54:55], off offset:1024
	global_load_dwordx4 v[220:223], v[26:27], off
	s_waitcnt vmcnt(0)
	s_nop 1
	v_mov_b64_e32 v[56:57], v[180:181]
	v_mov_b64_e32 v[58:59], v[182:183]
	s_nop 1
	v_mov_b64_e32 v[60:61], v[184:185]
	v_mov_b64_e32 v[62:63], v[186:187]
	s_nop 0
	v_pk_add_f32 v[56:57], v[56:57], 1.0 op_sel_hi:[1,0]
	s_nop 0
	v_pk_fma_f32 v[50:51], v[50:51], v[56:57], v[60:61]
	v_pk_add_f32 v[58:59], v[58:59], 1.0 op_sel_hi:[1,0]
	v_pk_fma_f32 v[52:53], v[52:53], v[58:59], v[62:63]
	v_cvt_pk_bf16_f32 v50, v50, v51
	v_bfe_u32 v1, v52, 16, 1
	v_add3_u32 v1, v52, v1, s73
	v_bfe_u32 v7, v53, 16, 1
	v_lshrrev_b32_e32 v1, 16, v1
	v_add3_u32 v7, v53, v7, s73
	v_and_or_b32 v51, v7, s33, v1
	global_store_dwordx2 v[8:9], v[50:51], off offset:1536
	s_nop 1
	v_mov_b64_e32 v[50:51], v[188:189]
	v_mov_b64_e32 v[52:53], v[190:191]
	s_nop 0
	s_nop 1
	v_mov_b64_e32 v[56:57], v[192:193]
	v_mov_b64_e32 v[58:59], v[194:195]
	v_pk_mul_f32 v[46:47], v[46:47], v[6:7] op_sel_hi:[1,0]
	v_pk_mul_f32 v[60:61], v[48:49], v[6:7] op_sel_hi:[1,0]
	s_nop 0
	v_pk_fma_f32 v[48:49], v[46:47], v[50:51], v[56:57]
	v_add_co_u32_e32 v46, vcc, s82, v66
	v_pk_fma_f32 v[50:51], v[60:61], v[52:53], v[58:59]
	s_nop 0
	v_addc_co_u32_e32 v47, vcc, 0, v67, vcc
	global_store_dwordx4 v[46:47], v[48:51], off
	s_nop 1
	v_mov_b64_e32 v[56:57], v[196:197]
	v_mov_b64_e32 v[58:59], v[198:199]
	s_nop 1
	v_mov_b64_e32 v[60:61], v[200:201]
	v_mov_b64_e32 v[62:63], v[202:203]
	s_nop 0
	v_pk_add_f32 v[56:57], v[56:57], 1.0 op_sel_hi:[1,0]
	s_nop 0
	v_pk_fma_f32 v[48:49], v[48:49], v[56:57], v[60:61]
	v_pk_add_f32 v[52:53], v[58:59], 1.0 op_sel_hi:[1,0]
	v_pk_fma_f32 v[50:51], v[50:51], v[52:53], v[62:63]
	v_cvt_pk_bf16_f32 v48, v48, v49
	v_bfe_u32 v1, v50, 16, 1
	v_add3_u32 v1, v50, v1, s73
	v_bfe_u32 v7, v51, 16, 1
	v_lshrrev_b32_e32 v1, 16, v1
	v_add3_u32 v7, v51, v7, s73
	v_and_or_b32 v49, v7, s33, v1
	global_store_dwordx2 v[8:9], v[48:49], off offset:2048
	s_nop 1
	v_mov_b64_e32 v[48:49], v[204:205]
	v_mov_b64_e32 v[50:51], v[206:207]
	s_nop 0
	s_nop 1
	v_mov_b64_e32 v[56:57], v[208:209]
	v_mov_b64_e32 v[58:59], v[210:211]
	v_pk_mul_f32 v[44:45], v[44:45], v[6:7] op_sel_hi:[1,0]
	v_pk_mul_f32 v[42:43], v[42:43], v[6:7] op_sel_hi:[1,0]
	s_nop 0
	v_pk_fma_f32 v[44:45], v[44:45], v[50:51], v[58:59]
	v_pk_fma_f32 v[42:43], v[42:43], v[48:49], v[56:57]
	global_store_dwordx4 v[46:47], v[42:45], off offset:1024
	s_nop 1
	v_mov_b64_e32 v[48:49], v[212:213]
	v_mov_b64_e32 v[50:51], v[214:215]
	s_nop 1
	v_mov_b64_e32 v[56:57], v[216:217]
	v_mov_b64_e32 v[58:59], v[218:219]
	s_nop 0
	v_pk_add_f32 v[48:49], v[48:49], 1.0 op_sel_hi:[1,0]
	s_nop 0
	v_pk_fma_f32 v[42:43], v[42:43], v[48:49], v[56:57]
	v_pk_add_f32 v[50:51], v[50:51], 1.0 op_sel_hi:[1,0]
	v_pk_fma_f32 v[44:45], v[44:45], v[50:51], v[58:59]
	v_cvt_pk_bf16_f32 v42, v42, v43
	v_bfe_u32 v1, v44, 16, 1
	v_add3_u32 v1, v44, v1, s73
	v_bfe_u32 v7, v45, 16, 1
	v_lshrrev_b32_e32 v1, 16, v1
	v_add3_u32 v7, v45, v7, s73
	v_and_or_b32 v43, v7, s33, v1
	global_store_dwordx2 v[8:9], v[42:43], off offset:2560
	s_nop 1
	v_mov_b64_e32 v[42:43], v[220:221]
	v_mov_b64_e32 v[44:45], v[222:223]
	s_nop 0
	global_load_dwordx4 v[180:183], v[28:29], off
	global_load_dwordx4 v[184:187], v[64:65], off offset:2048
	global_load_dwordx4 v[188:191], v[54:55], off offset:2048
	global_load_dwordx4 v[192:195], v[30:31], off
	global_load_dwordx4 v[196:199], v[32:33], off
	global_load_dwordx4 v[200:203], v[64:65], off offset:3072
	global_load_dwordx4 v[204:207], v[54:55], off offset:3072
	s_waitcnt vmcnt(0)
	s_nop 1
	v_mov_b64_e32 v[48:49], v[180:181]
	v_mov_b64_e32 v[50:51], v[182:183]
	v_pk_mul_f32 v[40:41], v[40:41], v[6:7] op_sel_hi:[1,0]
	v_pk_mul_f32 v[38:39], v[38:39], v[6:7] op_sel_hi:[1,0]
	s_nop 0
	v_pk_fma_f32 v[40:41], v[40:41], v[44:45], v[50:51]
	v_pk_fma_f32 v[38:39], v[38:39], v[42:43], v[48:49]
	global_store_dwordx4 v[46:47], v[38:41], off offset:2048
	s_nop 1
	v_mov_b64_e32 v[42:43], v[184:185]
	v_mov_b64_e32 v[44:45], v[186:187]
	s_nop 1
	v_mov_b64_e32 v[48:49], v[188:189]
	v_mov_b64_e32 v[50:51], v[190:191]
	s_nop 0
	v_pk_add_f32 v[42:43], v[42:43], 1.0 op_sel_hi:[1,0]
	s_nop 0
	v_pk_fma_f32 v[38:39], v[38:39], v[42:43], v[48:49]
	v_pk_add_f32 v[44:45], v[44:45], 1.0 op_sel_hi:[1,0]
	v_pk_fma_f32 v[40:41], v[40:41], v[44:45], v[50:51]
	v_cvt_pk_bf16_f32 v38, v38, v39
	v_bfe_u32 v1, v40, 16, 1
	v_add3_u32 v1, v40, v1, s73
	v_bfe_u32 v7, v41, 16, 1
	v_lshrrev_b32_e32 v1, 16, v1
	v_add3_u32 v7, v41, v7, s73
	v_and_or_b32 v39, v7, s33, v1
	global_store_dwordx2 v[8:9], v[38:39], off offset:3072
	s_nop 1
	v_mov_b64_e32 v[38:39], v[192:193]
	v_mov_b64_e32 v[40:41], v[194:195]
	s_nop 0
	s_nop 1
	v_mov_b64_e32 v[42:43], v[196:197]
	v_mov_b64_e32 v[44:45], v[198:199]
	v_pk_mul_f32 v[4:5], v[4:5], v[6:7] op_sel_hi:[1,0]
	v_pk_mul_f32 v[2:3], v[2:3], v[6:7] op_sel_hi:[1,0]
	s_nop 0
	v_pk_fma_f32 v[4:5], v[4:5], v[40:41], v[44:45]
	v_pk_fma_f32 v[2:3], v[2:3], v[38:39], v[42:43]
	global_store_dwordx4 v[46:47], v[2:5], off offset:3072
	s_nop 1
	v_mov_b64_e32 v[38:39], v[200:201]
	v_mov_b64_e32 v[40:41], v[202:203]
	s_nop 1
	v_mov_b64_e32 v[42:43], v[204:205]
	v_mov_b64_e32 v[44:45], v[206:207]
	s_nop 0
	v_pk_add_f32 v[38:39], v[38:39], 1.0 op_sel_hi:[1,0]
	s_nop 0
	v_pk_fma_f32 v[2:3], v[2:3], v[38:39], v[42:43]
	v_pk_add_f32 v[6:7], v[40:41], 1.0 op_sel_hi:[1,0]
	v_pk_fma_f32 v[4:5], v[4:5], v[6:7], v[44:45]
	v_cvt_pk_bf16_f32 v2, v2, v3
	v_bfe_u32 v1, v4, 16, 1
	v_add3_u32 v1, v4, v1, s73
	v_bfe_u32 v3, v5, 16, 1
	v_lshrrev_b32_e32 v1, 16, v1
	v_add3_u32 v3, v5, v3, s73
	v_and_or_b32 v3, v3, s33, v1
	global_store_dwordx2 v[8:9], v[2:3], off offset:3584
	s_branch .LBB0_1221

.LBB0_1743:
	v_mov_b32_e32 v2, v0
	s_mov_b64 s[8:9], s[44:45]
	v_mov_b32_e32 v1, v232
	s_mov_b64 s[34:35], s[46:47]
	s_mov_b64 s[10:11], s[0:1]
	s_add_i32 s8, s60, s30
	v_lshlrev_b32_e32 v2, 2, v1
	s_waitcnt lgkmcnt(0)
	v_ashrrev_i32_e32 v3, 31, v2
	v_lshlrev_b64 v[4:5], 1, v[2:3]
	v_lshl_add_u64 v[6:7], s[34:35], 0, v[4:5]
	v_lshl_add_u64 v[32:33], v[6:7], 0, s[24:25]
	global_load_dwordx2 v[6:7], v[32:33], off offset:-3584
	global_load_dwordx2 v[34:35], v[32:33], off offset:-3072
	global_load_dwordx2 v[44:45], v[32:33], off offset:-2560
	global_load_dwordx2 v[8:9], v[32:33], off offset:-2048
	s_cmpk_lt_i32 s8, 0x2000
	s_cselect_b32 s36, s8, s30
	s_add_u32 s18, s34, 0x28c000
	s_addc_u32 s19, s35, 0
	s_ashr_i32 s37, s36, 31
	s_ashr_i32 s31, s30, 31
	s_lshl_b64 s[8:9], s[36:37], 12
	s_add_u32 s16, s34, s8
	s_addc_u32 s17, s35, s9
	v_lshl_add_u64 v[4:5], s[16:17], 0, v[4:5]
	s_mov_b64 s[8:9], 0x1d91e000
	v_lshl_add_u64 v[224:225], v[4:5], 0, s[8:9]
	global_load_dwordx2 v[118:119], v[224:225], off
	global_load_dwordx2 v[120:121], v[224:225], off offset:512
	global_load_dwordx2 v[122:123], v[224:225], off offset:1024
	global_load_dwordx2 v[144:145], v[224:225], off offset:1536
	global_load_dwordx2 v[146:147], v[224:225], off offset:2048
	global_load_dwordx2 v[152:153], v[224:225], off offset:2560
	global_load_dwordx2 v[154:155], v[224:225], off offset:3072
	global_load_dwordx2 v[234:235], v[224:225], off offset:3584
	v_and_b32_e32 v14, 64, v249
	v_add_u32_e32 v14, 64, v14
	v_xor_b32_e32 v20, 1, v249
	v_lshlrev_b64 v[86:87], 2, v[2:3]
	s_add_u32 s20, s34, 0x28e000
	s_addc_u32 s21, s35, 0
	v_lshl_add_u64 v[88:89], s[20:21], 0, v[86:87]
	s_add_u32 s58, s34, 0x1515b000
	s_addc_u32 s59, s35, 0
	s_waitcnt vmcnt(3)
	v_lshlrev_b32_e32 v68, 16, v6
	s_waitcnt vmcnt(2)
	v_lshlrev_b32_e32 v69, 16, v34
	v_and_b32_e32 v75, 0xffff0000, v34
	s_waitcnt vmcnt(0)
	v_lshlrev_b32_e32 v36, 16, v8
	v_and_b32_e32 v37, 0xffff0000, v8
	v_lshlrev_b32_e32 v38, 16, v9
	v_and_b32_e32 v39, 0xffff0000, v9
	global_load_dwordx2 v[8:9], v[32:33], off offset:-1536
	v_and_b32_e32 v74, 0xffff0000, v6
	v_and_b32_e32 v73, 0xffff0000, v35
	v_and_b32_e32 v72, 0xffff0000, v7
	v_lshlrev_b32_e32 v34, 16, v44
	v_add_f32_e32 v66, v36, v37
	v_add_f32_e32 v46, v38, v39
	s_waitcnt vmcnt(0)
	v_lshlrev_b32_e32 v43, 16, v8
	v_and_b32_e32 v41, 0xffff0000, v8
	v_lshlrev_b32_e32 v67, 16, v9
	v_and_b32_e32 v47, 0xffff0000, v9
	global_load_dwordx2 v[70:71], v[32:33], off offset:-1024
	global_load_dwordx2 v[8:9], v[32:33], off offset:-512
	s_waitcnt vmcnt(0)
	v_lshlrev_b32_e32 v48, 16, v8
	v_and_b32_e32 v49, 0xffff0000, v8
	v_lshlrev_b32_e32 v50, 16, v9
	v_and_b32_e32 v51, 0xffff0000, v9
	global_load_dwordx2 v[8:9], v[32:33], off
	v_add_f32_e32 v64, v48, v49
	v_add_f32_e32 v54, v50, v51
	s_waitcnt vmcnt(0)
	v_lshlrev_b32_e32 v52, 16, v8
	v_and_b32_e32 v53, 0xffff0000, v8
	v_lshlrev_b32_e32 v65, 16, v9
	v_and_b32_e32 v55, 0xffff0000, v9
	v_lshl_add_u64 v[8:9], v[4:5], 0, s[8:9]
	s_mov_b32 s8, 0x1d91e000
	v_add_co_u32_e32 v4, vcc, s8, v4
	s_nop 1
	v_addc_co_u32_e32 v5, vcc, 0, v5, vcc
	s_nop 1
	v_mov_b64_e32 v[60:61], v[118:119]
	s_nop 1
	v_mov_b64_e32 v[62:63], v[120:121]
	s_nop 1
	v_mov_b64_e32 v[58:59], v[122:123]
	s_nop 0
	s_nop 1
	v_mov_b64_e32 v[4:5], v[144:145]
	v_cmp_lt_i32_e32 vcc, v20, v14
	v_lshlrev_b32_e32 v28, 16, v4
	v_and_b32_e32 v29, 0xffff0000, v4
	v_lshlrev_b32_e32 v30, 16, v5
	v_and_b32_e32 v31, 0xffff0000, v5
	s_nop 1
	v_mov_b64_e32 v[4:5], v[146:147]
	v_cndmask_b32_e32 v20, v249, v20, vcc
	v_lshlrev_b32_e32 v90, 2, v20
	v_add_f32_e32 v26, v28, v29
	v_add_f32_e32 v24, v30, v31
	v_lshlrev_b32_e32 v23, 16, v4
	v_and_b32_e32 v21, 0xffff0000, v4
	v_lshlrev_b32_e32 v27, 16, v5
	v_and_b32_e32 v25, 0xffff0000, v5
	s_nop 1
	v_mov_b64_e32 v[56:57], v[152:153]
	s_nop 1
	v_mov_b64_e32 v[4:5], v[154:155]
	s_load_dwordx4 s[12:15], s[10:11], 0xb0
	s_load_dwordx2 s[38:39], s[10:11], 0x68
	s_waitcnt lgkmcnt(0)
	v_lshl_add_u64 v[84:85], s[12:13], 0, v[86:87]
	v_lshlrev_b32_e32 v16, 16, v4
	v_and_b32_e32 v17, 0xffff0000, v4
	v_lshlrev_b32_e32 v18, 16, v5
	v_and_b32_e32 v19, 0xffff0000, v5
	s_nop 1
	v_mov_b64_e32 v[4:5], v[234:235]
	v_lshlrev_b32_e32 v9, 16, v35
	v_lshlrev_b32_e32 v8, 16, v7
	v_pk_add_f32 v[6:7], v[8:9], v[72:73]
	v_lshlrev_b32_e32 v35, 16, v45
	v_lshlrev_b32_e32 v10, 16, v4
	v_and_b32_e32 v11, 0xffff0000, v4
	v_lshlrev_b32_e32 v15, 16, v5
	v_and_b32_e32 v13, 0xffff0000, v5
	v_pk_add_f32 v[4:5], v[68:69], v[74:75]
	s_nop 0
	v_pk_add_f32 v[4:5], v[4:5], v[6:7]
	v_and_b32_e32 v7, 0xffff0000, v45
	v_add_f32_e32 v4, 0, v4
	v_and_b32_e32 v6, 0xffff0000, v44
	v_add_f32_e32 v42, v4, v5
	v_pk_add_f32 v[4:5], v[34:35], v[6:7]
	v_pk_add_f32 v[44:45], v[66:67], v[46:47]
	v_pk_add_f32 v[4:5], v[4:5], v[4:5] op_sel:[0,1] op_sel_hi:[1,0]
	s_nop 0
	v_mov_b32_e32 v5, v41
	v_pk_add_f32 v[4:5], v[42:43], v[4:5]
	s_nop 0
	v_pk_add_f32 v[76:77], v[4:5], v[44:45]
	v_lshlrev_b32_e32 v45, 16, v71
	v_lshlrev_b32_e32 v44, 16, v70
	v_and_b32_e32 v5, 0xffff0000, v71
	v_and_b32_e32 v4, 0xffff0000, v70
	v_pk_add_f32 v[70:71], v[44:45], v[4:5]
	v_pk_add_f32 v[76:77], v[76:77], v[76:77] op_sel:[0,1] op_sel_hi:[1,0]
	v_pk_add_f32 v[70:71], v[70:71], v[70:71] op_sel:[0,1] op_sel_hi:[1,0]
	v_mov_b32_e32 v77, v52
	v_mov_b32_e32 v71, v53
	v_pk_add_f32 v[70:71], v[76:77], v[70:71]
	v_pk_add_f32 v[76:77], v[64:65], v[54:55]
	s_nop 0
	v_pk_add_f32 v[70:71], v[70:71], v[76:77]
	s_nop 0
	v_add_f32_e32 v12, v70, v71
	ds_bpermute_b32 v20, v90, v12
	s_waitcnt lgkmcnt(0)
	v_add_f32_e32 v12, v12, v20
	v_xor_b32_e32 v20, 2, v249
	v_cmp_lt_i32_e32 vcc, v20, v14
	s_nop 1
	v_cndmask_b32_e32 v20, v249, v20, vcc
	v_lshlrev_b32_e32 v91, 2, v20
	ds_bpermute_b32 v20, v91, v12
	s_waitcnt lgkmcnt(0)
	v_add_f32_e32 v12, v12, v20
	v_xor_b32_e32 v20, 4, v249
	v_cmp_lt_i32_e32 vcc, v20, v14
	s_nop 1
	v_cndmask_b32_e32 v20, v249, v20, vcc
	v_lshlrev_b32_e32 v92, 2, v20
	ds_bpermute_b32 v20, v92, v12
	s_waitcnt lgkmcnt(0)
	v_add_f32_e32 v12, v12, v20
	v_xor_b32_e32 v20, 8, v249
	v_cmp_lt_i32_e32 vcc, v20, v14
	s_nop 1
	v_cndmask_b32_e32 v20, v249, v20, vcc
	v_lshlrev_b32_e32 v93, 2, v20
	ds_bpermute_b32 v20, v93, v12
	s_waitcnt lgkmcnt(0)
	v_add_f32_e32 v12, v12, v20
	v_xor_b32_e32 v20, 16, v249
	v_cmp_lt_i32_e32 vcc, v20, v14
	s_nop 1
	v_cndmask_b32_e32 v20, v249, v20, vcc
	v_lshlrev_b32_e32 v94, 2, v20
	ds_bpermute_b32 v20, v94, v12
	s_waitcnt lgkmcnt(0)
	v_add_f32_e32 v12, v12, v20
	v_xor_b32_e32 v20, 32, v249
	v_cmp_lt_i32_e32 vcc, v20, v14
	s_nop 1
	v_cndmask_b32_e32 v14, v249, v20, vcc
	v_lshlrev_b32_e32 v95, 2, v14
	ds_bpermute_b32 v14, v95, v12
	s_waitcnt lgkmcnt(0)
	v_add_f32_e32 v12, v12, v14
	v_fmac_f32_e32 v74, 0xba000000, v12
	v_fmac_f32_e32 v75, 0xba000000, v12
	v_fmac_f32_e32 v72, 0xba000000, v12
	v_fmac_f32_e32 v68, 0xba000000, v12
	v_fmac_f32_e32 v73, 0xba000000, v12
	v_fmac_f32_e32 v69, 0xba000000, v12
	v_mov_b32_e32 v71, v75
	v_mov_b32_e32 v77, v74
	v_pk_mul_f32 v[74:75], v[74:75], v[74:75]
	v_fmac_f32_e32 v8, 0xba000000, v12
	v_fmac_f32_e32 v9, 0xba000000, v12
	v_mov_b32_e32 v70, v69
	v_mov_b32_e32 v76, v68
	v_pk_fma_f32 v[68:69], v[68:69], v[68:69], v[74:75]
	v_mov_b32_e32 v75, v73
	v_mov_b32_e32 v79, v72
	v_pk_mul_f32 v[72:73], v[72:73], v[72:73]
	v_fmac_f32_e32 v6, 0xba000000, v12
	v_fmac_f32_e32 v7, 0xba000000, v12
	v_fmac_f32_e32 v35, 0xba000000, v12
	v_mov_b32_e32 v74, v9
	v_mov_b32_e32 v78, v8
	v_pk_fma_f32 v[8:9], v[8:9], v[8:9], v[72:73]
	v_fmac_f32_e32 v34, 0xba000000, v12
	v_mov_b32_e32 v72, v35
	v_mov_b32_e32 v73, v7
	v_mov_b32_e32 v35, v6
	v_pk_add_f32 v[8:9], v[68:69], v[8:9]
	v_pk_mul_f32 v[68:69], v[72:73], v[72:73]
	v_pk_mul_f32 v[6:7], v[34:35], v[34:35]
	v_fmac_f32_e32 v36, 0xba000000, v12
	v_pk_mov_b32 v[80:81], v[6:7], v[68:69] op_sel:[1,0]
	v_mov_b32_e32 v7, v69
	v_pk_add_f32 v[6:7], v[80:81], v[6:7]
	v_fmac_f32_e32 v37, 0xba000000, v12
	v_pk_add_f32 v[6:7], v[6:7], v[6:7] op_sel_hi:[0,1]
	v_fmac_f32_e32 v38, 0xba000000, v12
	v_mul_f32_e32 v6, v36, v36
	v_fmac_f32_e32 v39, 0xba000000, v12
	v_pk_fma_f32 v[68:69], v[36:37], v[36:37], v[6:7] op_sel_hi:[1,1,0]
	v_mul_f32_e32 v6, v38, v38
	v_pk_add_f32 v[8:9], v[8:9], v[8:9] op_sel_hi:[0,1]
	v_pk_fma_f32 v[80:81], v[38:39], v[38:39], v[6:7] op_sel_hi:[1,1,0]
	v_fmac_f32_e32 v47, 0xba000000, v12
	v_fmac_f32_e32 v67, 0xba000000, v12
	v_fmac_f32_e32 v41, 0xba000000, v12
	v_fmac_f32_e32 v43, 0xba000000, v12
	v_mul_f32_e32 v68, v43, v43
	v_mul_f32_e32 v80, v41, v41
	v_mul_f32_e32 v6, v67, v67
	v_mul_f32_e32 v8, v47, v47
	v_pk_add_f32 v[68:69], v[68:69], v[80:81]
	v_pk_add_f32 v[6:7], v[6:7], v[8:9]
	v_fmac_f32_e32 v4, 0xba000000, v12
	v_fmac_f32_e32 v5, 0xba000000, v12
	v_fmac_f32_e32 v45, 0xba000000, v12
	v_pk_add_f32 v[6:7], v[68:69], v[6:7]
	v_fmac_f32_e32 v44, 0xba000000, v12
	v_mov_b32_e32 v68, v45
	v_mov_b32_e32 v69, v5
	v_mov_b32_e32 v45, v4
	v_pk_mul_f32 v[8:9], v[68:69], v[68:69]
	v_pk_mul_f32 v[4:5], v[44:45], v[44:45]
	v_fmac_f32_e32 v48, 0xba000000, v12
	v_pk_mov_b32 v[80:81], v[4:5], v[8:9] op_sel:[1,0]
	v_mov_b32_e32 v5, v9
	v_pk_add_f32 v[4:5], v[80:81], v[4:5]
	v_fmac_f32_e32 v49, 0xba000000, v12
	v_pk_add_f32 v[4:5], v[4:5], v[4:5] op_sel_hi:[0,1]
	v_fmac_f32_e32 v50, 0xba000000, v12
	v_mul_f32_e32 v4, v48, v48
	v_fmac_f32_e32 v51, 0xba000000, v12
	v_pk_fma_f32 v[8:9], v[48:49], v[48:49], v[4:5] op_sel_hi:[1,1,0]
	v_mul_f32_e32 v4, v50, v50
	v_pk_add_f32 v[6:7], v[6:7], v[6:7] op_sel_hi:[0,1]
	v_pk_fma_f32 v[80:81], v[50:51], v[50:51], v[4:5] op_sel_hi:[1,1,0]
	v_fmac_f32_e32 v55, 0xba000000, v12
	v_fmac_f32_e32 v65, 0xba000000, v12
	v_fmac_f32_e32 v53, 0xba000000, v12
	v_fmac_f32_e32 v52, 0xba000000, v12
	v_mul_f32_e32 v8, v52, v52
	v_mul_f32_e32 v80, v53, v53
	v_mul_f32_e32 v4, v65, v65
	v_mul_f32_e32 v6, v55, v55
	v_pk_add_f32 v[8:9], v[8:9], v[80:81]
	v_pk_add_f32 v[4:5], v[4:5], v[6:7]
	v_lshl_add_u64 v[80:81], s[14:15], 0, v[86:87]
	v_pk_add_f32 v[4:5], v[8:9], v[4:5]
	v_mov_b32_e32 v46, v67
	v_add_f32_e32 v4, v4, v5
	ds_bpermute_b32 v5, v90, v4
	v_mov_b32_e32 v40, v43
	v_mov_b32_e32 v54, v65
	s_waitcnt lgkmcnt(0)
	v_add_f32_e32 v4, v4, v5
	ds_bpermute_b32 v5, v91, v4
	s_waitcnt lgkmcnt(0)
	v_add_f32_e32 v4, v4, v5
	ds_bpermute_b32 v5, v92, v4
	s_waitcnt lgkmcnt(0)
	v_add_f32_e32 v4, v4, v5
	ds_bpermute_b32 v5, v93, v4
	s_waitcnt lgkmcnt(0)
	v_add_f32_e32 v4, v4, v5
	ds_bpermute_b32 v5, v94, v4
	s_waitcnt lgkmcnt(0)
	v_add_f32_e32 v4, v4, v5
	ds_bpermute_b32 v5, v95, v4
	s_waitcnt lgkmcnt(0)
	v_add_f32_e32 v4, v4, v5
	v_fmamk_f32 v4, v4, 0x3a000000, v250
	v_cmp_gt_f32_e32 vcc, s96, v4
	v_mul_f32_e32 v5, 0x4f800000, v4
	s_nop 0
	v_cndmask_b32_e32 v4, v4, v5, vcc
	v_sqrt_f32_e32 v5, v4
	s_nop 0
	v_add_u32_e32 v6, -1, v5
	v_fma_f32 v7, -v6, v5, v4
	v_cmp_ge_f32_e64 s[10:11], 0, v7
	v_add_u32_e32 v7, 1, v5
	s_nop 0
	v_cndmask_b32_e64 v6, v5, v6, s[10:11]
	v_fma_f32 v5, -v7, v5, v4
	v_cmp_lt_f32_e64 s[10:11], 0, v5
	s_nop 1
	v_cndmask_b32_e64 v5, v6, v7, s[10:11]
	v_mul_f32_e32 v6, 0x37800000, v5
	v_cndmask_b32_e32 v5, v5, v6, vcc
	v_cmp_class_f32_e32 vcc, v4, v251
	s_nop 1
	v_cndmask_b32_e32 v4, v5, v4, vcc
	v_div_scale_f32 v5, s[8:9], v4, v4, 1.0
	v_rcp_f32_e32 v6, v5
	s_movk_i32 s8, 0xf000
	v_fma_f32 v7, -v5, v6, 1.0
	v_fmac_f32_e32 v6, v7, v6
	v_div_scale_f32 v7, vcc, 1.0, v4, 1.0
	v_mul_f32_e32 v8, v7, v6
	v_fma_f32 v9, -v5, v8, v7
	v_fmac_f32_e32 v8, v9, v6
	v_fma_f32 v5, -v5, v8, v7
	v_div_fmas_f32 v5, v5, v6, v8
	v_div_fixup_f32 v12, v5, v4, 1.0
	s_nop 1
	v_mov_b64_e32 v[2:3], v[180:181]
	v_mov_b64_e32 v[4:5], v[182:183]
	s_nop 1
	v_mov_b64_e32 v[6:7], v[212:213]
	v_mov_b64_e32 v[8:9], v[214:215]
	v_pk_mul_f32 v[76:77], v[76:77], v[12:13] op_sel_hi:[1,0]
	v_pk_mul_f32 v[78:79], v[78:79], v[12:13] op_sel_hi:[1,0]
	v_pk_mul_f32 v[70:71], v[70:71], v[12:13] op_sel_hi:[1,0]
	v_pk_mul_f32 v[34:35], v[34:35], v[12:13] op_sel_hi:[1,0]
	v_pk_mul_f32 v[38:39], v[38:39], v[12:13] op_sel_hi:[1,0]
	v_pk_mul_f32 v[36:37], v[36:37], v[12:13] op_sel_hi:[1,0]
	v_pk_mul_f32 v[46:47], v[46:47], v[12:13] op_sel_hi:[1,0]
	v_pk_mul_f32 v[40:41], v[40:41], v[12:13] op_sel_hi:[1,0]
	v_pk_mul_f32 v[44:45], v[44:45], v[12:13] op_sel_hi:[1,0]
	v_pk_mul_f32 v[50:51], v[50:51], v[12:13] op_sel_hi:[1,0]
	v_pk_mul_f32 v[48:49], v[48:49], v[12:13] op_sel_hi:[1,0]
	v_pk_mul_f32 v[54:55], v[54:55], v[12:13] op_sel_hi:[1,0]
	v_pk_mul_f32 v[52:53], v[52:53], v[12:13] op_sel_hi:[1,0]
	v_pk_fma_f32 v[6:7], v[2:3], v[76:77], v[6:7]
	v_lshl_add_u64 v[2:3], s[34:35], 0, v[86:87]
	v_lshl_add_u64 v[76:77], v[2:3], 0, s[22:23]
	v_add_co_u32_e32 v104, vcc, s8, v76
	v_pk_fma_f32 v[8:9], v[4:5], v[78:79], v[8:9]
	s_nop 0
	v_addc_co_u32_e32 v105, vcc, -1, v77, vcc
	global_store_dwordx4 v[104:105], v[6:9], off offset:-3072
	ds_read_b128 v[2:5], v127
	v_lshl_add_u64 v[86:87], s[18:19], 0, v[86:87]
	ds_read_b128 v[96:99], v127 offset:8192
	s_mov_b32 s8, 0xef2fd000
	s_waitcnt lgkmcnt(0)
	v_pk_add_f32 v[4:5], v[4:5], 1.0 op_sel_hi:[1,0]
	v_pk_add_f32 v[78:79], v[2:3], 1.0 op_sel_hi:[1,0]
	s_nop 0
	v_pk_fma_f32 v[2:3], v[4:5], v[8:9], v[98:99]
	v_pk_fma_f32 v[4:5], v[78:79], v[6:7], v[96:97]
	s_nop 0
	s_nop 0
	s_nop 0
	s_nop 0
	s_nop 0
	s_nop 0
	v_cvt_pk_bf16_f32 v6, v4, v5
	s_nop 0
	s_nop 0
	s_nop 0
	s_nop 0
	v_add_co_u32_e32 v78, vcc, s8, v32
	v_cvt_pk_bf16_f32 v7, v2, v3
	s_nop 0
	v_addc_co_u32_e32 v79, vcc, -1, v33, vcc
	global_store_dwordx2 v[78:79], v[6:7], off offset:-3584
	s_nop 1
	v_mov_b64_e32 v[6:7], v[184:185]
	v_mov_b64_e32 v[8:9], v[186:187]
	s_nop 0
	s_nop 1
	v_mov_b64_e32 v[96:97], v[216:217]
	v_mov_b64_e32 v[98:99], v[218:219]
	v_pk_mul_f32 v[32:33], v[74:75], v[12:13] op_sel_hi:[1,0]
	s_lshl_b64 s[8:9], s[36:37], 13
	s_add_u32 s40, s34, s8
	s_addc_u32 s41, s35, s9
	v_pk_fma_f32 v[96:97], v[6:7], v[70:71], v[96:97]
	v_pk_fma_f32 v[98:99], v[8:9], v[32:33], v[98:99]
	global_store_dwordx4 v[104:105], v[96:99], off offset:-2048
	ds_read_b128 v[6:9], v127 offset:1024
	ds_read_b128 v[100:103], v127 offset:9216
	s_waitcnt lgkmcnt(0)
	v_pk_add_f32 v[8:9], v[8:9], 1.0 op_sel_hi:[1,0]
	v_pk_add_f32 v[32:33], v[6:7], 1.0 op_sel_hi:[1,0]
	s_nop 0
	v_pk_fma_f32 v[6:7], v[8:9], v[98:99], v[102:103]
	v_pk_fma_f32 v[8:9], v[32:33], v[96:97], v[100:101]
	s_nop 0
	s_nop 0
	s_nop 0
	s_nop 0
	s_nop 0
	s_nop 0
	v_cvt_pk_bf16_f32 v32, v8, v9
	s_nop 0
	s_nop 0
	s_nop 0
	s_nop 0
	s_nop 0
	v_cvt_pk_bf16_f32 v33, v6, v7
	global_store_dwordx2 v[78:79], v[32:33], off offset:-3072
	s_nop 1
	v_mov_b64_e32 v[96:97], v[188:189]
	v_mov_b64_e32 v[98:99], v[190:191]
	s_nop 1
	v_mov_b64_e32 v[100:101], v[220:221]
	v_mov_b64_e32 v[102:103], v[222:223]
	v_pk_mul_f32 v[32:33], v[72:73], v[12:13] op_sel_hi:[1,0]
	v_pk_fma_f32 v[70:71], v[96:97], v[34:35], v[100:101]
	v_pk_fma_f32 v[72:73], v[98:99], v[32:33], v[102:103]
	global_store_dwordx4 v[104:105], v[70:73], off offset:-1024
	ds_read_b128 v[32:35], v127 offset:2048
	ds_read_b128 v[96:99], v127 offset:10240
	s_waitcnt lgkmcnt(0)
	v_pk_add_f32 v[34:35], v[34:35], 1.0 op_sel_hi:[1,0]
	v_pk_add_f32 v[74:75], v[32:33], 1.0 op_sel_hi:[1,0]
	s_nop 0
	v_pk_fma_f32 v[32:33], v[34:35], v[72:73], v[98:99]
	v_pk_fma_f32 v[34:35], v[74:75], v[70:71], v[96:97]
	s_nop 0
	s_nop 0
	s_nop 0
	s_nop 0
	s_nop 0
	s_nop 0
	v_cvt_pk_bf16_f32 v70, v34, v35
	s_nop 0
	s_nop 0
	s_nop 0
	s_nop 0
	s_nop 0
	v_cvt_pk_bf16_f32 v71, v32, v33
	global_store_dwordx2 v[78:79], v[70:71], off offset:-2560
	s_nop 1
	v_mov_b64_e32 v[70:71], v[192:193]
	v_mov_b64_e32 v[72:73], v[194:195]
	s_nop 0
	s_nop 1
	v_mov_b64_e32 v[96:97], v[236:237]
	v_mov_b64_e32 v[98:99], v[238:239]
	v_pk_fma_f32 v[70:71], v[70:71], v[36:37], v[96:97]
	v_pk_fma_f32 v[72:73], v[72:73], v[38:39], v[98:99]
	global_store_dwordx4 v[76:77], v[70:73], off offset:-4096
	ds_read_b128 v[36:39], v127 offset:3072
	ds_read_b128 v[96:99], v127 offset:11264
	s_waitcnt lgkmcnt(0)
	v_pk_add_f32 v[38:39], v[38:39], 1.0 op_sel_hi:[1,0]
	v_pk_add_f32 v[74:75], v[36:37], 1.0 op_sel_hi:[1,0]
	s_nop 0
	v_pk_fma_f32 v[36:37], v[38:39], v[72:73], v[98:99]
	v_pk_fma_f32 v[38:39], v[74:75], v[70:71], v[96:97]
	s_nop 0
	s_nop 0
	s_nop 0
	s_nop 0
	s_nop 0
	s_nop 0
	v_cvt_pk_bf16_f32 v70, v38, v39
	s_nop 0
	s_nop 0
	s_nop 0
	s_nop 0
	s_nop 0
	v_cvt_pk_bf16_f32 v71, v36, v37
	global_store_dwordx2 v[78:79], v[70:71], off offset:-2048
	v_add_co_u32_e32 v70, vcc, s82, v84
	s_nop 1
	v_addc_co_u32_e32 v71, vcc, 0, v85, vcc
	v_add_co_u32_e32 v72, vcc, s82, v80
	s_nop 1
	v_mov_b64_e32 v[96:97], v[196:197]
	v_mov_b64_e32 v[98:99], v[198:199]
	s_nop 0
	v_addc_co_u32_e32 v73, vcc, 0, v81, vcc
	s_nop 1
	v_mov_b64_e32 v[100:101], v[240:241]
	v_mov_b64_e32 v[102:103], v[242:243]
	v_add_co_u32_e32 v66, vcc, s82, v88
	v_pk_fma_f32 v[96:97], v[40:41], v[96:97], v[100:101]
	v_pk_fma_f32 v[98:99], v[46:47], v[98:99], v[102:103]
	v_addc_co_u32_e32 v67, vcc, 0, v89, vcc
	global_store_dwordx4 v[76:77], v[96:99], off offset:-3072
	v_add_co_u32_e32 v80, vcc, s82, v86
	ds_read_b128 v[40:43], v127 offset:4096
	s_nop 0
	v_addc_co_u32_e32 v81, vcc, 0, v87, vcc
	ds_read_b128 v[84:87], v127 offset:12288
	s_waitcnt lgkmcnt(0)
	v_pk_add_f32 v[42:43], v[42:43], 1.0 op_sel_hi:[1,0]
	v_pk_add_f32 v[46:47], v[40:41], 1.0 op_sel_hi:[1,0]
	s_nop 0
	v_pk_fma_f32 v[40:41], v[98:99], v[42:43], v[86:87]
	v_pk_fma_f32 v[42:43], v[96:97], v[46:47], v[84:85]
	s_nop 0
	s_nop 0
	s_nop 0
	s_nop 0
	s_nop 0
	s_nop 0
	v_cvt_pk_bf16_f32 v46, v42, v43
	s_nop 0
	s_nop 0
	s_nop 0
	s_nop 0
	s_nop 0
	v_cvt_pk_bf16_f32 v47, v40, v41
	global_store_dwordx2 v[78:79], v[46:47], off offset:-1536
	s_nop 1
	v_mov_b64_e32 v[84:85], v[200:201]
	v_mov_b64_e32 v[86:87], v[202:203]
	s_nop 1
	v_mov_b64_e32 v[96:97], v[128:129]
	v_mov_b64_e32 v[98:99], v[130:131]
	v_pk_mul_f32 v[46:47], v[68:69], v[12:13] op_sel_hi:[1,0]
	v_pk_fma_f32 v[84:85], v[44:45], v[84:85], v[96:97]
	v_pk_fma_f32 v[86:87], v[46:47], v[86:87], v[98:99]
	global_store_dwordx4 v[76:77], v[84:87], off offset:-2048
	ds_read_b128 v[44:47], v127 offset:5120
	ds_read_b128 v[96:99], v127 offset:13312
	s_waitcnt lgkmcnt(0)
	v_pk_add_f32 v[46:47], v[46:47], 1.0 op_sel_hi:[1,0]
	v_pk_add_f32 v[68:69], v[44:45], 1.0 op_sel_hi:[1,0]
	s_nop 0
	v_pk_fma_f32 v[44:45], v[86:87], v[46:47], v[98:99]
	v_pk_fma_f32 v[46:47], v[84:85], v[68:69], v[96:97]
	s_nop 0
	s_nop 0
	s_nop 0
	s_nop 0
	s_nop 0
	s_nop 0
	v_cvt_pk_bf16_f32 v68, v46, v47
	s_nop 0
	s_nop 0
	s_nop 0
	s_nop 0
	s_nop 0
	v_cvt_pk_bf16_f32 v69, v44, v45
	global_store_dwordx2 v[78:79], v[68:69], off offset:-1024
	s_nop 1
	v_mov_b64_e32 v[84:85], v[204:205]
	v_mov_b64_e32 v[86:87], v[206:207]
	s_nop 1
	v_mov_b64_e32 v[96:97], v[132:133]
	v_mov_b64_e32 v[98:99], v[134:135]
	v_pk_fma_f32 v[84:85], v[48:49], v[84:85], v[96:97]
	v_pk_fma_f32 v[86:87], v[50:51], v[86:87], v[98:99]
	global_store_dwordx4 v[76:77], v[84:87], off offset:-1024
	ds_read_b128 v[48:51], v127 offset:6144
	ds_read_b128 v[96:99], v127 offset:14336
	s_waitcnt lgkmcnt(0)
	v_pk_add_f32 v[50:51], v[50:51], 1.0 op_sel_hi:[1,0]
	v_pk_add_f32 v[68:69], v[48:49], 1.0 op_sel_hi:[1,0]
	s_nop 0
	v_pk_fma_f32 v[48:49], v[86:87], v[50:51], v[98:99]
	v_pk_fma_f32 v[50:51], v[84:85], v[68:69], v[96:97]
	s_nop 0
	s_nop 0
	s_nop 0
	s_nop 0
	s_nop 0
	s_nop 0
	v_cvt_pk_bf16_f32 v68, v50, v51
	s_nop 0
	s_nop 0
	s_nop 0
	s_nop 0
	s_nop 0
	v_cvt_pk_bf16_f32 v69, v48, v49
	global_store_dwordx2 v[78:79], v[68:69], off offset:-512
	s_nop 1
	v_mov_b64_e32 v[68:69], v[208:209]
	v_mov_b64_e32 v[70:71], v[210:211]
	s_nop 0
	s_nop 1
	v_mov_b64_e32 v[72:73], v[140:141]
	v_mov_b64_e32 v[74:75], v[142:143]
	v_pk_fma_f32 v[68:69], v[52:53], v[68:69], v[72:73]
	v_pk_fma_f32 v[70:71], v[54:55], v[70:71], v[74:75]
	global_store_dwordx4 v[76:77], v[68:71], off
	ds_read_b128 v[52:55], v127 offset:7168
	s_nop 0
	global_load_dwordx4 v[64:67], v[80:81], off offset:3072
	v_and_b32_e32 v77, 0xffff0000, v63
	v_and_b32_e32 v76, 0xffff0000, v61
	v_and_b32_e32 v75, 0xffff0000, v59
	v_and_b32_e32 v74, 0xffff0000, v58
	s_waitcnt vmcnt(0) lgkmcnt(0)
	v_pk_add_f32 v[54:55], v[54:55], 1.0 op_sel_hi:[1,0]
	v_pk_add_f32 v[72:73], v[52:53], 1.0 op_sel_hi:[1,0]
	s_nop 0
	v_pk_fma_f32 v[52:53], v[70:71], v[54:55], v[66:67]
	v_pk_fma_f32 v[54:55], v[68:69], v[72:73], v[64:65]
	v_and_b32_e32 v67, 0xffff0000, v62
	v_cvt_pk_bf16_f32 v64, v54, v55
	v_cvt_pk_bf16_f32 v65, v52, v53
	global_store_dwordx2 v[78:79], v[64:65], off
	v_lshlrev_b32_e32 v64, 16, v60
	v_lshlrev_b32_e32 v65, 16, v62
	v_and_b32_e32 v66, 0xffff0000, v60
	v_lshlrev_b32_e32 v70, 16, v61
	v_lshlrev_b32_e32 v71, 16, v63
	v_pk_add_f32 v[60:61], v[64:65], v[66:67]
	v_pk_add_f32 v[62:63], v[70:71], v[76:77]
	v_lshlrev_b32_e32 v69, 16, v59
	v_lshlrev_b32_e32 v68, 16, v58
	v_pk_add_f32 v[60:61], v[60:61], v[62:63]
	v_pk_add_f32 v[58:59], v[68:69], v[74:75]
	v_add_f32_e32 v12, 0, v60
	v_pk_add_f32 v[58:59], v[58:59], v[58:59] op_sel:[0,1] op_sel_hi:[1,0]
	v_add_f32_e32 v22, v12, v61
	v_mov_b32_e32 v59, v21
	v_pk_add_f32 v[58:59], v[22:23], v[58:59]
	v_pk_add_f32 v[60:61], v[26:27], v[24:25]
	v_and_b32_e32 v73, 0xffff0000, v57
	v_pk_add_f32 v[58:59], v[58:59], v[60:61]
	v_lshlrev_b32_e32 v61, 16, v57
	v_lshlrev_b32_e32 v60, 16, v56
	v_and_b32_e32 v72, 0xffff0000, v56
	v_pk_add_f32 v[56:57], v[60:61], v[72:73]
	v_pk_add_f32 v[58:59], v[58:59], v[58:59] op_sel:[0,1] op_sel_hi:[1,0]
	v_pk_add_f32 v[56:57], v[56:57], v[56:57] op_sel:[0,1] op_sel_hi:[1,0]
	v_add_f32_e32 v14, v16, v17
	v_add_f32_e32 v12, v18, v19
	v_mov_b32_e32 v59, v10
	v_mov_b32_e32 v57, v11
	v_pk_add_f32 v[56:57], v[58:59], v[56:57]
	v_pk_add_f32 v[58:59], v[14:15], v[12:13]
	s_nop 0
	v_pk_add_f32 v[56:57], v[56:57], v[58:59]
	s_nop 0
	v_add_f32_e32 v12, v56, v57
	ds_bpermute_b32 v14, v90, v12
	s_waitcnt lgkmcnt(0)
	v_add_f32_e32 v12, v12, v14
	ds_bpermute_b32 v14, v91, v12
	s_waitcnt lgkmcnt(0)
	v_add_f32_e32 v12, v12, v14
	ds_bpermute_b32 v14, v92, v12
	s_waitcnt lgkmcnt(0)
	v_add_f32_e32 v12, v12, v14
	ds_bpermute_b32 v14, v93, v12
	s_waitcnt lgkmcnt(0)
	v_add_f32_e32 v12, v12, v14
	ds_bpermute_b32 v14, v94, v12
	s_waitcnt lgkmcnt(0)
	v_add_f32_e32 v12, v12, v14
	ds_bpermute_b32 v14, v95, v12
	s_waitcnt lgkmcnt(0)
	v_add_f32_e32 v14, v12, v14
	v_fmac_f32_e32 v66, 0xba000000, v14
	v_fmac_f32_e32 v67, 0xba000000, v14
	v_fmac_f32_e32 v76, 0xba000000, v14
	v_fmac_f32_e32 v64, 0xba000000, v14
	v_fmac_f32_e32 v77, 0xba000000, v14
	v_fmac_f32_e32 v65, 0xba000000, v14
	v_pk_mul_f32 v[58:59], v[66:67], v[66:67]
	v_fmac_f32_e32 v70, 0xba000000, v14
	v_fmac_f32_e32 v71, 0xba000000, v14
	v_mov_b32_e32 v62, v65
	v_mov_b32_e32 v63, v67
	v_mov_b32_e32 v56, v64
	v_pk_fma_f32 v[64:65], v[64:65], v[64:65], v[58:59]
	v_mov_b32_e32 v67, v77
	v_mov_b32_e32 v59, v76
	v_pk_mul_f32 v[76:77], v[76:77], v[76:77]
	v_mov_b32_e32 v57, v66
	v_mov_b32_e32 v66, v71
	v_mov_b32_e32 v58, v70
	v_pk_fma_f32 v[70:71], v[70:71], v[70:71], v[76:77]
	v_fmac_f32_e32 v74, 0xba000000, v14
	v_fmac_f32_e32 v75, 0xba000000, v14
	v_fmac_f32_e32 v69, 0xba000000, v14
	v_pk_add_f32 v[64:65], v[64:65], v[70:71]
	v_fmac_f32_e32 v68, 0xba000000, v14
	v_mov_b32_e32 v70, v69
	v_mov_b32_e32 v71, v75
	v_mov_b32_e32 v69, v74
	v_pk_mul_f32 v[76:77], v[70:71], v[70:71]
	v_pk_mul_f32 v[74:75], v[68:69], v[68:69]
	v_fmac_f32_e32 v28, 0xba000000, v14
	v_pk_mov_b32 v[78:79], v[74:75], v[76:77] op_sel:[1,0]
	v_mov_b32_e32 v75, v77
	v_fmac_f32_e32 v29, 0xba000000, v14
	v_fmac_f32_e32 v30, 0xba000000, v14
	v_mul_f32_e32 v12, v28, v28
	v_pk_add_f32 v[74:75], v[78:79], v[74:75]
	v_fmac_f32_e32 v31, 0xba000000, v14
	v_pk_fma_f32 v[76:77], v[28:29], v[28:29], v[12:13] op_sel_hi:[1,1,0]
	v_mul_f32_e32 v12, v30, v30
	v_pk_add_f32 v[64:65], v[64:65], v[64:65] op_sel_hi:[0,1]
	v_pk_add_f32 v[74:75], v[74:75], v[74:75] op_sel_hi:[0,1]
	v_pk_fma_f32 v[78:79], v[30:31], v[30:31], v[12:13] op_sel_hi:[1,1,0]
	v_fmac_f32_e32 v25, 0xba000000, v14
	v_fmac_f32_e32 v27, 0xba000000, v14
	v_fmac_f32_e32 v21, 0xba000000, v14
	v_fmac_f32_e32 v23, 0xba000000, v14
	v_mul_f32_e32 v76, v23, v23
	v_mul_f32_e32 v78, v21, v21
	v_mul_f32_e32 v74, v27, v27
	v_mul_f32_e32 v64, v25, v25
	v_pk_add_f32 v[76:77], v[76:77], v[78:79]
	v_pk_add_f32 v[64:65], v[74:75], v[64:65]
	v_fmac_f32_e32 v72, 0xba000000, v14
	v_pk_add_f32 v[64:65], v[76:77], v[64:65]
	v_fmac_f32_e32 v73, 0xba000000, v14
	v_fmac_f32_e32 v61, 0xba000000, v14
	v_pk_add_f32 v[74:75], v[64:65], v[64:65] op_sel_hi:[0,1]
	v_fmac_f32_e32 v60, 0xba000000, v14
	v_mov_b32_e32 v64, v61
	v_mov_b32_e32 v65, v73
	v_mov_b32_e32 v61, v72
	v_pk_mul_f32 v[76:77], v[64:65], v[64:65]
	v_pk_mul_f32 v[72:73], v[60:61], v[60:61]
	v_fmac_f32_e32 v16, 0xba000000, v14
	v_pk_mov_b32 v[78:79], v[72:73], v[76:77] op_sel:[1,0]
	v_mov_b32_e32 v73, v77
	v_fmac_f32_e32 v17, 0xba000000, v14
	v_fmac_f32_e32 v18, 0xba000000, v14
	v_mul_f32_e32 v12, v16, v16
	v_pk_add_f32 v[72:73], v[78:79], v[72:73]
	v_fmac_f32_e32 v19, 0xba000000, v14
	v_pk_fma_f32 v[76:77], v[16:17], v[16:17], v[12:13] op_sel_hi:[1,1,0]
	v_mul_f32_e32 v12, v18, v18
	v_pk_add_f32 v[72:73], v[72:73], v[72:73] op_sel_hi:[0,1]
	v_pk_fma_f32 v[78:79], v[18:19], v[18:19], v[12:13] op_sel_hi:[1,1,0]
	v_fmac_f32_e32 v13, 0xba000000, v14
	v_fmac_f32_e32 v15, 0xba000000, v14
	v_fmac_f32_e32 v11, 0xba000000, v14
	v_fmac_f32_e32 v10, 0xba000000, v14
	v_mul_f32_e32 v72, v15, v15
	v_mul_f32_e32 v74, v13, v13
	v_mul_f32_e32 v76, v10, v10
	v_mul_f32_e32 v78, v11, v11
	v_pk_add_f32 v[72:73], v[72:73], v[74:75]
	v_lshlrev_b32_e32 v74, 2, v1
	v_pk_add_f32 v[76:77], v[76:77], v[78:79]
	v_ashrrev_i32_e32 v75, 31, v74
	v_pk_add_f32 v[72:73], v[76:77], v[72:73]
	v_lshlrev_b64 v[76:77], 2, v[74:75]
	v_lshl_add_u64 v[80:81], s[12:13], 0, v[76:77]
	v_lshl_add_u64 v[78:79], s[14:15], 0, v[76:77]
	s_nop 1
	v_mov_b64_e32 v[84:85], v[180:181]
	v_mov_b64_e32 v[86:87], v[182:183]
	s_nop 1
	v_mov_b64_e32 v[96:97], v[212:213]
	v_mov_b64_e32 v[98:99], v[214:215]
	v_add_f32_e32 v12, v72, v73
	ds_bpermute_b32 v14, v90, v12
	s_waitcnt lgkmcnt(0)
	v_add_f32_e32 v12, v12, v14
	ds_bpermute_b32 v14, v91, v12
	s_waitcnt lgkmcnt(0)
	v_add_f32_e32 v12, v12, v14
	ds_bpermute_b32 v14, v92, v12
	s_waitcnt lgkmcnt(0)
	v_add_f32_e32 v12, v12, v14
	ds_bpermute_b32 v14, v93, v12
	s_waitcnt lgkmcnt(0)
	v_add_f32_e32 v12, v12, v14
	ds_bpermute_b32 v14, v94, v12
	s_waitcnt lgkmcnt(0)
	v_add_f32_e32 v12, v12, v14
	ds_bpermute_b32 v14, v95, v12
	s_waitcnt lgkmcnt(0)
	v_add_f32_e32 v12, v12, v14
	v_fmamk_f32 v12, v12, 0x3a000000, v250
	v_cmp_gt_f32_e32 vcc, s96, v12
	v_mul_f32_e32 v14, 0x4f800000, v12
	s_nop 0
	v_cndmask_b32_e32 v12, v12, v14, vcc
	v_sqrt_f32_e32 v14, v12
	s_nop 0
	v_add_u32_e32 v20, -1, v14
	v_fma_f32 v22, -v20, v14, v12
	v_cmp_ge_f32_e64 s[10:11], 0, v22
	v_add_u32_e32 v22, 1, v14
	s_nop 0
	v_cndmask_b32_e64 v20, v14, v20, s[10:11]
	v_fma_f32 v14, -v22, v14, v12
	v_cmp_lt_f32_e64 s[10:11], 0, v14
	s_nop 1
	v_cndmask_b32_e64 v14, v20, v22, s[10:11]
	v_mul_f32_e32 v20, 0x37800000, v14
	v_cndmask_b32_e32 v14, v14, v20, vcc
	v_cmp_class_f32_e32 vcc, v12, v251
	s_nop 1
	v_cndmask_b32_e32 v12, v14, v12, vcc
	v_div_scale_f32 v14, s[8:9], v12, v12, 1.0
	v_rcp_f32_e32 v20, v14
	s_mov_b64 s[8:9], 0x25d1e000
	v_fma_f32 v22, -v14, v20, 1.0
	v_fmac_f32_e32 v20, v22, v20
	v_div_scale_f32 v22, vcc, 1.0, v12, 1.0
	v_mul_f32_e32 v24, v22, v20
	v_fma_f32 v26, -v14, v24, v22
	v_fmac_f32_e32 v24, v26, v20
	v_fma_f32 v14, -v14, v24, v22
	v_div_fmas_f32 v14, v14, v20, v24
	v_div_fixup_f32 v14, v14, v12, 1.0
	v_pk_mul_f32 v[56:57], v[56:57], v[14:15] op_sel_hi:[1,0]
	v_pk_mul_f32 v[58:59], v[58:59], v[14:15] op_sel_hi:[1,0]
	v_pk_fma_f32 v[96:97], v[84:85], v[56:57], v[96:97]
	v_lshl_add_u64 v[56:57], s[40:41], 0, v[76:77]
	v_pk_fma_f32 v[98:99], v[86:87], v[58:59], v[98:99]
	v_lshl_add_u64 v[86:87], v[56:57], 0, s[8:9]
	s_mov_b32 s8, 0x25d1f000
	v_add_co_u32_e32 v72, vcc, s8, v56
	v_lshl_add_u64 v[84:85], s[20:21], 0, v[76:77]
	s_nop 0
	v_addc_co_u32_e32 v73, vcc, 0, v57, vcc
	ds_read_b128 v[56:59], v127
	v_lshl_add_u64 v[76:77], s[18:19], 0, v[76:77]
	ds_read_b128 v[100:103], v127 offset:8192
	s_mov_b64 s[8:9], 0xcc1b000
	global_store_dwordx4 v[72:73], v[96:99], off offset:-4096
	v_pk_mul_f32 v[66:67], v[66:67], v[14:15] op_sel_hi:[1,0]
	v_pk_mul_f32 v[62:63], v[62:63], v[14:15] op_sel_hi:[1,0]
	v_pk_mul_f32 v[70:71], v[70:71], v[14:15] op_sel_hi:[1,0]
	v_pk_mul_f32 v[68:69], v[68:69], v[14:15] op_sel_hi:[1,0]
	v_pk_mul_f32 v[30:31], v[30:31], v[14:15] op_sel_hi:[1,0]
	v_pk_mul_f32 v[28:29], v[28:29], v[14:15] op_sel_hi:[1,0]
	v_mov_b32_e32 v24, v27
	v_pk_mul_f32 v[24:25], v[24:25], v[14:15] op_sel_hi:[1,0]
	v_pk_mul_f32 v[64:65], v[64:65], v[14:15] op_sel_hi:[1,0]
	v_pk_mul_f32 v[60:61], v[60:61], v[14:15] op_sel_hi:[1,0]
	v_pk_mul_f32 v[18:19], v[18:19], v[14:15] op_sel_hi:[1,0]
	v_pk_mul_f32 v[16:17], v[16:17], v[14:15] op_sel_hi:[1,0]
	v_pk_mul_f32 v[10:11], v[10:11], v[14:15] op_sel_hi:[1,0]
	s_waitcnt lgkmcnt(0)
	v_pk_add_f32 v[58:59], v[58:59], 1.0 op_sel_hi:[1,0]
	v_pk_add_f32 v[88:89], v[56:57], 1.0 op_sel_hi:[1,0]
	s_nop 0
	v_pk_fma_f32 v[56:57], v[58:59], v[98:99], v[102:103]
	v_pk_fma_f32 v[58:59], v[88:89], v[96:97], v[100:101]
	v_lshl_add_u64 v[96:97], v[74:75], 1, s[16:17]
	s_nop 0
	s_nop 0
	s_nop 0
	s_nop 0
	s_nop 0
	v_cvt_pk_bf16_f32 v88, v58, v59
	s_nop 0
	s_nop 0
	s_nop 0
	s_nop 0
	s_nop 0
	v_lshl_add_u64 v[74:75], v[96:97], 0, s[8:9]
	v_add_co_u32_e32 v96, vcc, s61, v96
	v_cvt_pk_bf16_f32 v89, v56, v57
	s_nop 0
	v_addc_co_u32_e32 v97, vcc, 0, v97, vcc
	global_store_dwordx2 v[96:97], v[88:89], off
	s_nop 1
	v_mov_b64_e32 v[96:97], v[184:185]
	v_mov_b64_e32 v[98:99], v[186:187]
	s_nop 0
	s_nop 1
	v_mov_b64_e32 v[100:101], v[216:217]
	v_mov_b64_e32 v[102:103], v[218:219]
	v_pk_fma_f32 v[96:97], v[96:97], v[62:63], v[100:101]
	v_pk_fma_f32 v[98:99], v[98:99], v[66:67], v[102:103]
	global_store_dwordx4 v[86:87], v[96:99], off offset:1024
	ds_read_b128 v[100:103], v127 offset:1024
	ds_read_b128 v[104:107], v127 offset:9216
	s_waitcnt lgkmcnt(0)
	v_pk_add_f32 v[66:67], v[100:101], 1.0 op_sel_hi:[1,0]
	s_nop 0
	v_pk_fma_f32 v[66:67], v[66:67], v[96:97], v[104:105]
	v_pk_add_f32 v[62:63], v[102:103], 1.0 op_sel_hi:[1,0]
	v_pk_fma_f32 v[62:63], v[62:63], v[98:99], v[106:107]
	v_cvt_pk_bf16_f32 v88, v66, v67
	v_cvt_pk_bf16_f32 v89, v62, v63
	global_store_dwordx2 v[74:75], v[88:89], off offset:512
	s_nop 1
	v_mov_b64_e32 v[96:97], v[188:189]
	v_mov_b64_e32 v[98:99], v[190:191]
	s_nop 1
	v_mov_b64_e32 v[100:101], v[220:221]
	v_mov_b64_e32 v[102:103], v[222:223]
	v_pk_fma_f32 v[96:97], v[96:97], v[68:69], v[100:101]
	v_pk_fma_f32 v[98:99], v[98:99], v[70:71], v[102:103]
	global_store_dwordx4 v[86:87], v[96:99], off offset:2048
	ds_read_b128 v[68:71], v127 offset:2048
	ds_read_b128 v[100:103], v127 offset:10240
	s_waitcnt lgkmcnt(0)
	v_pk_add_f32 v[70:71], v[70:71], 1.0 op_sel_hi:[1,0]
	v_pk_add_f32 v[88:89], v[68:69], 1.0 op_sel_hi:[1,0]
	s_nop 0
	v_pk_fma_f32 v[68:69], v[70:71], v[98:99], v[102:103]
	v_pk_fma_f32 v[70:71], v[88:89], v[96:97], v[100:101]
	s_nop 0
	s_nop 0
	s_nop 0
	s_nop 0
	s_nop 0
	s_nop 0
	v_cvt_pk_bf16_f32 v88, v70, v71
	s_nop 0
	s_nop 0
	s_nop 0
	s_nop 0
	s_nop 0
	v_cvt_pk_bf16_f32 v89, v68, v69
	global_store_dwordx2 v[74:75], v[88:89], off offset:1024
	s_nop 1
	v_mov_b64_e32 v[96:97], v[192:193]
	v_mov_b64_e32 v[98:99], v[194:195]
	s_nop 1
	v_mov_b64_e32 v[100:101], v[236:237]
	v_mov_b64_e32 v[102:103], v[238:239]
	v_add_co_u32_e32 v80, vcc, s82, v80
	v_pk_fma_f32 v[96:97], v[96:97], v[28:29], v[100:101]
	v_pk_fma_f32 v[98:99], v[98:99], v[30:31], v[102:103]
	global_store_dwordx4 v[86:87], v[96:99], off offset:3072
	ds_read_b128 v[28:31], v127 offset:3072
	s_nop 0
	ds_read_b128 v[86:89], v127 offset:11264
	v_addc_co_u32_e32 v81, vcc, 0, v81, vcc
	v_add_co_u32_e32 v78, vcc, s82, v78
	s_waitcnt lgkmcnt(0)
	v_pk_add_f32 v[30:31], v[30:31], 1.0 op_sel_hi:[1,0]
	v_pk_add_f32 v[100:101], v[28:29], 1.0 op_sel_hi:[1,0]
	s_nop 0
	v_pk_fma_f32 v[28:29], v[30:31], v[98:99], v[88:89]
	v_pk_fma_f32 v[30:31], v[100:101], v[96:97], v[86:87]
	v_addc_co_u32_e32 v79, vcc, 0, v79, vcc
	s_nop 0
	s_nop 0
	s_nop 0
	s_nop 0
	s_nop 0
	v_cvt_pk_bf16_f32 v86, v30, v31
	s_nop 0
	s_nop 0
	s_nop 0
	s_nop 0
	s_nop 0
	v_cvt_pk_bf16_f32 v87, v28, v29
	global_store_dwordx2 v[74:75], v[86:87], off offset:1536
	s_nop 1
	v_mov_b64_e32 v[86:87], v[196:197]
	v_mov_b64_e32 v[88:89], v[198:199]
	s_nop 1
	v_mov_b64_e32 v[96:97], v[240:241]
	v_mov_b64_e32 v[98:99], v[242:243]
	v_add_co_u32_e32 v84, vcc, s82, v84
	v_mov_b32_e32 v20, v23
	s_nop 0
	v_addc_co_u32_e32 v85, vcc, 0, v85, vcc
	v_pk_mul_f32 v[20:21], v[20:21], v[14:15] op_sel_hi:[1,0]
	v_add_co_u32_e32 v76, vcc, s82, v76
	v_pk_fma_f32 v[22:23], v[20:21], v[86:87], v[96:97]
	v_pk_fma_f32 v[24:25], v[24:25], v[88:89], v[98:99]
	ds_read_b128 v[86:89], v127 offset:4096
	v_addc_co_u32_e32 v77, vcc, 0, v77, vcc
	ds_read_b128 v[96:99], v127 offset:12288
	s_waitcnt lgkmcnt(0)
	v_pk_add_f32 v[26:27], v[86:87], 1.0 op_sel_hi:[1,0]
	global_store_dwordx4 v[72:73], v[22:25], off
	v_pk_add_f32 v[20:21], v[88:89], 1.0 op_sel_hi:[1,0]
	s_nop 0
	v_pk_fma_f32 v[22:23], v[22:23], v[26:27], v[96:97]
	v_pk_fma_f32 v[20:21], v[24:25], v[20:21], v[98:99]
	v_cvt_pk_bf16_f32 v24, v22, v23
	v_cvt_pk_bf16_f32 v25, v20, v21
	global_store_dwordx2 v[74:75], v[24:25], off offset:2048
	s_nop 1
	v_mov_b64_e32 v[24:25], v[200:201]
	v_mov_b64_e32 v[26:27], v[202:203]
	s_nop 0
	s_nop 1
	v_mov_b64_e32 v[86:87], v[128:129]
	v_mov_b64_e32 v[88:89], v[130:131]
	v_pk_fma_f32 v[86:87], v[60:61], v[24:25], v[86:87]
	v_pk_fma_f32 v[88:89], v[64:65], v[26:27], v[88:89]
	global_store_dwordx4 v[72:73], v[86:89], off offset:1024
	ds_read_b128 v[24:27], v127 offset:5120
	ds_read_b128 v[96:99], v127 offset:13312
	s_waitcnt lgkmcnt(0)
	v_pk_add_f32 v[26:27], v[26:27], 1.0 op_sel_hi:[1,0]
	v_pk_add_f32 v[60:61], v[24:25], 1.0 op_sel_hi:[1,0]
	s_nop 0
	v_pk_fma_f32 v[24:25], v[88:89], v[26:27], v[98:99]
	v_pk_fma_f32 v[26:27], v[86:87], v[60:61], v[96:97]
	v_cvt_pk_bf16_f32 v60, v26, v27
	v_cvt_pk_bf16_f32 v61, v24, v25
	global_store_dwordx2 v[74:75], v[60:61], off offset:2560
	s_nop 1
	v_mov_b64_e32 v[86:87], v[204:205]
	v_mov_b64_e32 v[88:89], v[206:207]
	s_nop 1
	v_mov_b64_e32 v[96:97], v[132:133]
	v_mov_b64_e32 v[98:99], v[134:135]
	v_pk_fma_f32 v[86:87], v[16:17], v[86:87], v[96:97]
	v_pk_fma_f32 v[88:89], v[18:19], v[88:89], v[98:99]
	global_store_dwordx4 v[72:73], v[86:89], off offset:2048
	ds_read_b128 v[16:19], v127 offset:6144
	ds_read_b128 v[96:99], v127 offset:14336
	s_waitcnt lgkmcnt(0)
	v_pk_add_f32 v[18:19], v[18:19], 1.0 op_sel_hi:[1,0]
	v_pk_add_f32 v[60:61], v[16:17], 1.0 op_sel_hi:[1,0]
	s_nop 0
	v_pk_fma_f32 v[16:17], v[88:89], v[18:19], v[98:99]
	v_pk_fma_f32 v[18:19], v[86:87], v[60:61], v[96:97]
	v_cvt_pk_bf16_f32 v60, v18, v19
	v_cvt_pk_bf16_f32 v61, v16, v17
	global_store_dwordx2 v[74:75], v[60:61], off offset:3072
	s_nop 1
	v_mov_b64_e32 v[86:87], v[208:209]
	v_mov_b64_e32 v[88:89], v[210:211]
	s_nop 0
	s_nop 1
	v_mov_b64_e32 v[78:79], v[140:141]
	v_mov_b64_e32 v[80:81], v[142:143]
	v_mov_b32_e32 v12, v15
	v_pk_mul_f32 v[60:61], v[12:13], v[14:15] op_sel_hi:[1,0]
	v_pk_fma_f32 v[12:13], v[10:11], v[86:87], v[78:79]
	v_pk_fma_f32 v[14:15], v[60:61], v[88:89], v[80:81]
	global_store_dwordx4 v[72:73], v[12:15], off offset:3072
	ds_read_b128 v[78:81], v127 offset:7168
	s_nop 0
	global_load_dwordx4 v[84:87], v[76:77], off offset:3072
	s_waitcnt vmcnt(0) lgkmcnt(0)
	v_pk_add_f32 v[60:61], v[78:79], 1.0 op_sel_hi:[1,0]
	v_pk_add_f32 v[10:11], v[80:81], 1.0 op_sel_hi:[1,0]
	s_nop 0
	v_pk_fma_f32 v[12:13], v[12:13], v[60:61], v[84:85]
	v_pk_fma_f32 v[10:11], v[14:15], v[10:11], v[86:87]
	v_cvt_pk_bf16_f32 v14, v12, v13
	s_nop 0
	s_nop 0
	s_nop 0
	s_nop 0
	s_nop 0
	v_cvt_pk_bf16_f32 v15, v10, v11
	global_store_dwordx2 v[74:75], v[14:15], off offset:3584
	s_nop 0
	v_lshl_add_u32 v103, v1, 4, 0
	ds_read_b128 v[72:75], v103
	v_add_u32_e32 v80, 0x18400, v103
	s_waitcnt lgkmcnt(0)
	v_pk_fma_f32 v[14:15], v[4:5], v[72:73], 0 op_sel_hi:[1,1,0]
	v_pk_fma_f32 v[60:61], v[58:59], v[72:73], 0 op_sel_hi:[1,1,0]
	v_pk_fma_f32 v[14:15], v[2:3], v[74:75], v[14:15]
	v_pk_fma_f32 v[60:61], v[56:57], v[74:75], v[60:61]
	ds_read_b128 v[72:75], v103 offset:1024
	s_waitcnt lgkmcnt(0)
	v_pk_fma_f32 v[14:15], v[8:9], v[72:73], v[14:15]
	v_pk_fma_f32 v[60:61], v[66:67], v[72:73], v[60:61]
	v_pk_fma_f32 v[14:15], v[6:7], v[74:75], v[14:15]
	v_pk_fma_f32 v[60:61], v[62:63], v[74:75], v[60:61]
	ds_read_b128 v[72:75], v103 offset:2048
	s_waitcnt lgkmcnt(0)
	v_pk_fma_f32 v[14:15], v[34:35], v[72:73], v[14:15]
	v_pk_fma_f32 v[60:61], v[70:71], v[72:73], v[60:61]
	v_pk_fma_f32 v[14:15], v[32:33], v[74:75], v[14:15]
	v_pk_fma_f32 v[60:61], v[68:69], v[74:75], v[60:61]
	ds_read_b128 v[72:75], v103 offset:3072
	s_waitcnt lgkmcnt(0)
	v_pk_fma_f32 v[14:15], v[38:39], v[72:73], v[14:15]
	v_pk_fma_f32 v[60:61], v[30:31], v[72:73], v[60:61]
	v_pk_fma_f32 v[14:15], v[36:37], v[74:75], v[14:15]
	v_pk_fma_f32 v[60:61], v[28:29], v[74:75], v[60:61]
	ds_read_b128 v[72:75], v103 offset:4096
	s_waitcnt lgkmcnt(0)
	v_pk_fma_f32 v[14:15], v[42:43], v[72:73], v[14:15]
	v_pk_fma_f32 v[60:61], v[22:23], v[72:73], v[60:61]
	v_pk_fma_f32 v[14:15], v[40:41], v[74:75], v[14:15]
	v_pk_fma_f32 v[60:61], v[20:21], v[74:75], v[60:61]
	ds_read_b128 v[72:75], v103 offset:5120
	s_waitcnt lgkmcnt(0)
	v_pk_fma_f32 v[14:15], v[46:47], v[72:73], v[14:15]
	v_pk_fma_f32 v[60:61], v[26:27], v[72:73], v[60:61]
	v_pk_fma_f32 v[14:15], v[44:45], v[74:75], v[14:15]
	v_pk_fma_f32 v[60:61], v[24:25], v[74:75], v[60:61]
	ds_read_b128 v[72:75], v103 offset:6144
	s_waitcnt lgkmcnt(0)
	v_pk_fma_f32 v[14:15], v[50:51], v[72:73], v[14:15]
	v_pk_fma_f32 v[60:61], v[18:19], v[72:73], v[60:61]
	v_pk_fma_f32 v[14:15], v[48:49], v[74:75], v[14:15]
	v_pk_fma_f32 v[60:61], v[16:17], v[74:75], v[60:61]
	ds_read_b128 v[72:75], v103 offset:7168
	s_waitcnt lgkmcnt(0)
	v_pk_fma_f32 v[14:15], v[54:55], v[72:73], v[14:15]
	v_pk_fma_f32 v[60:61], v[12:13], v[72:73], v[60:61]
	v_pk_fma_f32 v[14:15], v[52:53], v[74:75], v[14:15]
	v_pk_fma_f32 v[60:61], v[10:11], v[74:75], v[60:61]
	v_add_f32_e32 v81, v14, v15
	v_add_f32_e32 v14, v60, v61
	ds_read_b128 v[72:75], v103 offset:8192
	s_waitcnt lgkmcnt(0)
	v_pk_fma_f32 v[60:61], v[4:5], v[72:73], 0 op_sel_hi:[1,1,0]
	v_pk_fma_f32 v[64:65], v[58:59], v[72:73], 0 op_sel_hi:[1,1,0]
	v_pk_fma_f32 v[60:61], v[2:3], v[74:75], v[60:61]
	v_pk_fma_f32 v[64:65], v[56:57], v[74:75], v[64:65]
	ds_read_b128 v[72:75], v103 offset:9216
	s_waitcnt lgkmcnt(0)
	v_pk_fma_f32 v[60:61], v[8:9], v[72:73], v[60:61]
	v_pk_fma_f32 v[64:65], v[66:67], v[72:73], v[64:65]
	v_pk_fma_f32 v[60:61], v[6:7], v[74:75], v[60:61]
	v_pk_fma_f32 v[64:65], v[62:63], v[74:75], v[64:65]
	ds_read_b128 v[72:75], v103 offset:10240
	s_waitcnt lgkmcnt(0)
	v_pk_fma_f32 v[60:61], v[34:35], v[72:73], v[60:61]
	v_pk_fma_f32 v[64:65], v[70:71], v[72:73], v[64:65]
	v_pk_fma_f32 v[60:61], v[32:33], v[74:75], v[60:61]
	v_pk_fma_f32 v[64:65], v[68:69], v[74:75], v[64:65]
	ds_read_b128 v[72:75], v103 offset:11264
	s_waitcnt lgkmcnt(0)
	v_pk_fma_f32 v[60:61], v[38:39], v[72:73], v[60:61]
	v_pk_fma_f32 v[64:65], v[30:31], v[72:73], v[64:65]
	v_pk_fma_f32 v[60:61], v[36:37], v[74:75], v[60:61]
	v_pk_fma_f32 v[64:65], v[28:29], v[74:75], v[64:65]
	ds_read_b128 v[72:75], v103 offset:12288
	s_waitcnt lgkmcnt(0)
	v_pk_fma_f32 v[60:61], v[42:43], v[72:73], v[60:61]
	v_pk_fma_f32 v[64:65], v[22:23], v[72:73], v[64:65]
	v_pk_fma_f32 v[60:61], v[40:41], v[74:75], v[60:61]
	v_pk_fma_f32 v[64:65], v[20:21], v[74:75], v[64:65]
	ds_read_b128 v[72:75], v103 offset:13312
	s_waitcnt lgkmcnt(0)
	v_pk_fma_f32 v[60:61], v[46:47], v[72:73], v[60:61]
	v_pk_fma_f32 v[64:65], v[26:27], v[72:73], v[64:65]
	v_pk_fma_f32 v[60:61], v[44:45], v[74:75], v[60:61]
	v_pk_fma_f32 v[64:65], v[24:25], v[74:75], v[64:65]
	ds_read_b128 v[72:75], v103 offset:14336
	s_waitcnt lgkmcnt(0)
	v_pk_fma_f32 v[60:61], v[50:51], v[72:73], v[60:61]
	v_pk_fma_f32 v[64:65], v[18:19], v[72:73], v[64:65]
	v_pk_fma_f32 v[60:61], v[48:49], v[74:75], v[60:61]
	v_pk_fma_f32 v[64:65], v[16:17], v[74:75], v[64:65]
	ds_read_b128 v[72:75], v103 offset:15360
	s_waitcnt lgkmcnt(0)
	v_pk_fma_f32 v[60:61], v[54:55], v[72:73], v[60:61]
	v_pk_fma_f32 v[64:65], v[12:13], v[72:73], v[64:65]
	v_pk_fma_f32 v[60:61], v[52:53], v[74:75], v[60:61]
	v_pk_fma_f32 v[64:65], v[10:11], v[74:75], v[64:65]
	v_add_f32_e32 v82, v60, v61
	v_add_f32_e32 v15, v64, v65
	ds_read_b128 v[72:75], v103 offset:16384
	s_waitcnt lgkmcnt(0)
	v_pk_fma_f32 v[60:61], v[4:5], v[72:73], 0 op_sel_hi:[1,1,0]
	v_pk_fma_f32 v[64:65], v[58:59], v[72:73], 0 op_sel_hi:[1,1,0]
	v_pk_fma_f32 v[60:61], v[2:3], v[74:75], v[60:61]
	v_pk_fma_f32 v[64:65], v[56:57], v[74:75], v[64:65]
	ds_read_b128 v[72:75], v103 offset:17408
	s_waitcnt lgkmcnt(0)
	v_pk_fma_f32 v[60:61], v[8:9], v[72:73], v[60:61]
	v_pk_fma_f32 v[64:65], v[66:67], v[72:73], v[64:65]
	v_pk_fma_f32 v[60:61], v[6:7], v[74:75], v[60:61]
	v_pk_fma_f32 v[64:65], v[62:63], v[74:75], v[64:65]
	ds_read_b128 v[72:75], v103 offset:18432
	s_waitcnt lgkmcnt(0)
	v_pk_fma_f32 v[60:61], v[34:35], v[72:73], v[60:61]
	v_pk_fma_f32 v[64:65], v[70:71], v[72:73], v[64:65]
	v_pk_fma_f32 v[60:61], v[32:33], v[74:75], v[60:61]
	v_pk_fma_f32 v[64:65], v[68:69], v[74:75], v[64:65]
	ds_read_b128 v[72:75], v103 offset:19456
	s_waitcnt lgkmcnt(0)
	v_pk_fma_f32 v[60:61], v[38:39], v[72:73], v[60:61]
	v_pk_fma_f32 v[64:65], v[30:31], v[72:73], v[64:65]
	v_pk_fma_f32 v[60:61], v[36:37], v[74:75], v[60:61]
	v_pk_fma_f32 v[64:65], v[28:29], v[74:75], v[64:65]
	ds_read_b128 v[72:75], v103 offset:20480
	s_waitcnt lgkmcnt(0)
	v_pk_fma_f32 v[60:61], v[42:43], v[72:73], v[60:61]
	v_pk_fma_f32 v[64:65], v[22:23], v[72:73], v[64:65]
	v_pk_fma_f32 v[60:61], v[40:41], v[74:75], v[60:61]
	v_pk_fma_f32 v[64:65], v[20:21], v[74:75], v[64:65]
	ds_read_b128 v[72:75], v103 offset:21504
	s_waitcnt lgkmcnt(0)
	v_pk_fma_f32 v[60:61], v[46:47], v[72:73], v[60:61]
	v_pk_fma_f32 v[64:65], v[26:27], v[72:73], v[64:65]
	v_pk_fma_f32 v[60:61], v[44:45], v[74:75], v[60:61]
	v_pk_fma_f32 v[64:65], v[24:25], v[74:75], v[64:65]
	ds_read_b128 v[72:75], v103 offset:22528
	s_waitcnt lgkmcnt(0)
	v_pk_fma_f32 v[60:61], v[50:51], v[72:73], v[60:61]
	v_pk_fma_f32 v[64:65], v[18:19], v[72:73], v[64:65]
	v_pk_fma_f32 v[60:61], v[48:49], v[74:75], v[60:61]
	v_pk_fma_f32 v[64:65], v[16:17], v[74:75], v[64:65]
	ds_read_b128 v[72:75], v103 offset:23552
	s_waitcnt lgkmcnt(0)
	v_pk_fma_f32 v[60:61], v[54:55], v[72:73], v[60:61]
	v_pk_fma_f32 v[64:65], v[12:13], v[72:73], v[64:65]
	v_pk_fma_f32 v[60:61], v[52:53], v[74:75], v[60:61]
	v_pk_fma_f32 v[64:65], v[10:11], v[74:75], v[64:65]
	v_add_f32_e32 v84, v60, v61
	v_add_f32_e32 v60, v64, v65
	ds_read_b128 v[72:75], v103 offset:24576
	s_waitcnt lgkmcnt(0)
	v_pk_fma_f32 v[64:65], v[4:5], v[72:73], 0 op_sel_hi:[1,1,0]
	v_pk_fma_f32 v[72:73], v[58:59], v[72:73], 0 op_sel_hi:[1,1,0]
	v_pk_fma_f32 v[64:65], v[2:3], v[74:75], v[64:65]
	v_pk_fma_f32 v[76:77], v[56:57], v[74:75], v[72:73]
	ds_read_b128 v[72:75], v103 offset:25600
	s_waitcnt lgkmcnt(0)
	v_pk_fma_f32 v[64:65], v[8:9], v[72:73], v[64:65]
	v_pk_fma_f32 v[72:73], v[66:67], v[72:73], v[76:77]
	v_pk_fma_f32 v[64:65], v[6:7], v[74:75], v[64:65]
	v_pk_fma_f32 v[76:77], v[62:63], v[74:75], v[72:73]
	ds_read_b128 v[72:75], v103 offset:26624
	s_waitcnt lgkmcnt(0)
	v_pk_fma_f32 v[64:65], v[34:35], v[72:73], v[64:65]
	v_pk_fma_f32 v[72:73], v[70:71], v[72:73], v[76:77]
	v_pk_fma_f32 v[64:65], v[32:33], v[74:75], v[64:65]
	v_pk_fma_f32 v[76:77], v[68:69], v[74:75], v[72:73]
	ds_read_b128 v[72:75], v103 offset:27648
	s_waitcnt lgkmcnt(0)
	v_pk_fma_f32 v[64:65], v[38:39], v[72:73], v[64:65]
	v_pk_fma_f32 v[72:73], v[30:31], v[72:73], v[76:77]
	v_pk_fma_f32 v[64:65], v[36:37], v[74:75], v[64:65]
	v_pk_fma_f32 v[76:77], v[28:29], v[74:75], v[72:73]
	ds_read_b128 v[72:75], v103 offset:28672
	s_waitcnt lgkmcnt(0)
	v_pk_fma_f32 v[64:65], v[42:43], v[72:73], v[64:65]
	v_pk_fma_f32 v[72:73], v[22:23], v[72:73], v[76:77]
	v_pk_fma_f32 v[64:65], v[40:41], v[74:75], v[64:65]
	v_pk_fma_f32 v[76:77], v[20:21], v[74:75], v[72:73]
	ds_read_b128 v[72:75], v103 offset:29696
	s_waitcnt lgkmcnt(0)
	v_pk_fma_f32 v[64:65], v[46:47], v[72:73], v[64:65]
	v_pk_fma_f32 v[72:73], v[26:27], v[72:73], v[76:77]
	v_pk_fma_f32 v[64:65], v[44:45], v[74:75], v[64:65]
	v_pk_fma_f32 v[76:77], v[24:25], v[74:75], v[72:73]
	ds_read_b128 v[72:75], v103 offset:30720
	s_waitcnt lgkmcnt(0)
	v_pk_fma_f32 v[64:65], v[50:51], v[72:73], v[64:65]
	v_pk_fma_f32 v[72:73], v[18:19], v[72:73], v[76:77]
	v_pk_fma_f32 v[64:65], v[48:49], v[74:75], v[64:65]
	v_pk_fma_f32 v[76:77], v[16:17], v[74:75], v[72:73]
	ds_read_b128 v[72:75], v103 offset:31744
	s_waitcnt lgkmcnt(0)
	v_pk_fma_f32 v[64:65], v[54:55], v[72:73], v[64:65]
	v_pk_fma_f32 v[72:73], v[12:13], v[72:73], v[76:77]
	v_pk_fma_f32 v[64:65], v[52:53], v[74:75], v[64:65]
	v_pk_fma_f32 v[72:73], v[10:11], v[74:75], v[72:73]
	v_add_f32_e32 v85, v64, v65
	v_add_f32_e32 v61, v72, v73
	ds_read_b128 v[72:75], v103 offset:32768
	s_waitcnt lgkmcnt(0)
	v_pk_fma_f32 v[64:65], v[4:5], v[72:73], 0 op_sel_hi:[1,1,0]
	v_pk_fma_f32 v[72:73], v[58:59], v[72:73], 0 op_sel_hi:[1,1,0]
	v_pk_fma_f32 v[64:65], v[2:3], v[74:75], v[64:65]
	v_pk_fma_f32 v[76:77], v[56:57], v[74:75], v[72:73]
	ds_read_b128 v[72:75], v103 offset:33792
	s_waitcnt lgkmcnt(0)
	v_pk_fma_f32 v[64:65], v[8:9], v[72:73], v[64:65]
	v_pk_fma_f32 v[72:73], v[66:67], v[72:73], v[76:77]
	v_pk_fma_f32 v[64:65], v[6:7], v[74:75], v[64:65]
	v_pk_fma_f32 v[76:77], v[62:63], v[74:75], v[72:73]
	ds_read_b128 v[72:75], v103 offset:34816
	s_waitcnt lgkmcnt(0)
	v_pk_fma_f32 v[64:65], v[34:35], v[72:73], v[64:65]
	v_pk_fma_f32 v[72:73], v[70:71], v[72:73], v[76:77]
	v_pk_fma_f32 v[64:65], v[32:33], v[74:75], v[64:65]
	v_pk_fma_f32 v[76:77], v[68:69], v[74:75], v[72:73]
	ds_read_b128 v[72:75], v103 offset:35840
	s_waitcnt lgkmcnt(0)
	v_pk_fma_f32 v[64:65], v[38:39], v[72:73], v[64:65]
	v_pk_fma_f32 v[72:73], v[30:31], v[72:73], v[76:77]
	v_pk_fma_f32 v[64:65], v[36:37], v[74:75], v[64:65]
	v_pk_fma_f32 v[76:77], v[28:29], v[74:75], v[72:73]
	ds_read_b128 v[72:75], v103 offset:36864
	s_waitcnt lgkmcnt(0)
	v_pk_fma_f32 v[64:65], v[42:43], v[72:73], v[64:65]
	v_pk_fma_f32 v[72:73], v[22:23], v[72:73], v[76:77]
	v_pk_fma_f32 v[64:65], v[40:41], v[74:75], v[64:65]
	v_pk_fma_f32 v[76:77], v[20:21], v[74:75], v[72:73]
	ds_read_b128 v[72:75], v103 offset:37888
	s_waitcnt lgkmcnt(0)
	v_pk_fma_f32 v[64:65], v[46:47], v[72:73], v[64:65]
	v_pk_fma_f32 v[72:73], v[26:27], v[72:73], v[76:77]
	v_pk_fma_f32 v[64:65], v[44:45], v[74:75], v[64:65]
	v_pk_fma_f32 v[76:77], v[24:25], v[74:75], v[72:73]
	ds_read_b128 v[72:75], v103 offset:38912
	s_waitcnt lgkmcnt(0)
	v_pk_fma_f32 v[64:65], v[50:51], v[72:73], v[64:65]
	v_pk_fma_f32 v[72:73], v[18:19], v[72:73], v[76:77]
	v_pk_fma_f32 v[64:65], v[48:49], v[74:75], v[64:65]
	v_pk_fma_f32 v[76:77], v[16:17], v[74:75], v[72:73]
	ds_read_b128 v[72:75], v103 offset:39936
	s_waitcnt lgkmcnt(0)
	v_pk_fma_f32 v[64:65], v[54:55], v[72:73], v[64:65]
	v_pk_fma_f32 v[72:73], v[12:13], v[72:73], v[76:77]
	v_pk_fma_f32 v[64:65], v[52:53], v[74:75], v[64:65]
	v_pk_fma_f32 v[72:73], v[10:11], v[74:75], v[72:73]
	v_add_f32_e32 v86, v64, v65
	v_add_f32_e32 v64, v72, v73
	ds_read_b128 v[72:75], v103 offset:40960
	s_waitcnt lgkmcnt(0)
	v_pk_fma_f32 v[76:77], v[4:5], v[72:73], 0 op_sel_hi:[1,1,0]
	v_pk_fma_f32 v[72:73], v[58:59], v[72:73], 0 op_sel_hi:[1,1,0]
	v_pk_fma_f32 v[76:77], v[2:3], v[74:75], v[76:77]
	v_pk_fma_f32 v[78:79], v[56:57], v[74:75], v[72:73]
	ds_read_b128 v[72:75], v103 offset:41984
	s_waitcnt lgkmcnt(0)
	v_pk_fma_f32 v[76:77], v[8:9], v[72:73], v[76:77]
	v_pk_fma_f32 v[72:73], v[66:67], v[72:73], v[78:79]
	v_pk_fma_f32 v[76:77], v[6:7], v[74:75], v[76:77]
	v_pk_fma_f32 v[78:79], v[62:63], v[74:75], v[72:73]
	ds_read_b128 v[72:75], v103 offset:43008
	s_waitcnt lgkmcnt(0)
	v_pk_fma_f32 v[76:77], v[34:35], v[72:73], v[76:77]
	v_pk_fma_f32 v[72:73], v[70:71], v[72:73], v[78:79]
	v_pk_fma_f32 v[76:77], v[32:33], v[74:75], v[76:77]
	v_pk_fma_f32 v[78:79], v[68:69], v[74:75], v[72:73]
	ds_read_b128 v[72:75], v103 offset:44032
	s_waitcnt lgkmcnt(0)
	v_pk_fma_f32 v[76:77], v[38:39], v[72:73], v[76:77]
	v_pk_fma_f32 v[72:73], v[30:31], v[72:73], v[78:79]
	v_pk_fma_f32 v[76:77], v[36:37], v[74:75], v[76:77]
	v_pk_fma_f32 v[78:79], v[28:29], v[74:75], v[72:73]
	ds_read_b128 v[72:75], v103 offset:45056
	s_waitcnt lgkmcnt(0)
	v_pk_fma_f32 v[76:77], v[42:43], v[72:73], v[76:77]
	v_pk_fma_f32 v[72:73], v[22:23], v[72:73], v[78:79]
	v_pk_fma_f32 v[76:77], v[40:41], v[74:75], v[76:77]
	v_pk_fma_f32 v[78:79], v[20:21], v[74:75], v[72:73]
	ds_read_b128 v[72:75], v103 offset:46080
	s_waitcnt lgkmcnt(0)
	v_pk_fma_f32 v[76:77], v[46:47], v[72:73], v[76:77]
	v_pk_fma_f32 v[72:73], v[26:27], v[72:73], v[78:79]
	v_pk_fma_f32 v[76:77], v[44:45], v[74:75], v[76:77]
	v_pk_fma_f32 v[78:79], v[24:25], v[74:75], v[72:73]
	ds_read_b128 v[72:75], v103 offset:47104
	s_waitcnt lgkmcnt(0)
	v_pk_fma_f32 v[76:77], v[50:51], v[72:73], v[76:77]
	v_pk_fma_f32 v[72:73], v[18:19], v[72:73], v[78:79]
	v_pk_fma_f32 v[76:77], v[48:49], v[74:75], v[76:77]
	v_pk_fma_f32 v[78:79], v[16:17], v[74:75], v[72:73]
	ds_read_b128 v[72:75], v103 offset:48128
	s_waitcnt lgkmcnt(0)
	v_pk_fma_f32 v[76:77], v[54:55], v[72:73], v[76:77]
	v_pk_fma_f32 v[72:73], v[12:13], v[72:73], v[78:79]
	v_pk_fma_f32 v[76:77], v[52:53], v[74:75], v[76:77]
	v_pk_fma_f32 v[72:73], v[10:11], v[74:75], v[72:73]
	v_add_f32_e32 v87, v76, v77
	v_add_f32_e32 v65, v72, v73
	ds_read_b128 v[72:75], v103 offset:49152
	s_waitcnt lgkmcnt(0)
	v_pk_fma_f32 v[76:77], v[4:5], v[72:73], 0 op_sel_hi:[1,1,0]
	v_pk_fma_f32 v[72:73], v[58:59], v[72:73], 0 op_sel_hi:[1,1,0]
	v_pk_fma_f32 v[76:77], v[2:3], v[74:75], v[76:77]
	v_pk_fma_f32 v[78:79], v[56:57], v[74:75], v[72:73]
	ds_read_b128 v[72:75], v103 offset:50176
	s_waitcnt lgkmcnt(0)
	v_pk_fma_f32 v[76:77], v[8:9], v[72:73], v[76:77]
	v_pk_fma_f32 v[72:73], v[66:67], v[72:73], v[78:79]
	v_pk_fma_f32 v[76:77], v[6:7], v[74:75], v[76:77]
	v_pk_fma_f32 v[78:79], v[62:63], v[74:75], v[72:73]
	ds_read_b128 v[72:75], v103 offset:51200
	s_waitcnt lgkmcnt(0)
	v_pk_fma_f32 v[76:77], v[34:35], v[72:73], v[76:77]
	v_pk_fma_f32 v[72:73], v[70:71], v[72:73], v[78:79]
	v_pk_fma_f32 v[76:77], v[32:33], v[74:75], v[76:77]
	v_pk_fma_f32 v[78:79], v[68:69], v[74:75], v[72:73]
	ds_read_b128 v[72:75], v103 offset:52224
	s_waitcnt lgkmcnt(0)
	v_pk_fma_f32 v[76:77], v[38:39], v[72:73], v[76:77]
	v_pk_fma_f32 v[72:73], v[30:31], v[72:73], v[78:79]
	v_pk_fma_f32 v[76:77], v[36:37], v[74:75], v[76:77]
	v_pk_fma_f32 v[78:79], v[28:29], v[74:75], v[72:73]
	ds_read_b128 v[72:75], v103 offset:53248
	s_waitcnt lgkmcnt(0)
	v_pk_fma_f32 v[76:77], v[42:43], v[72:73], v[76:77]
	v_pk_fma_f32 v[72:73], v[22:23], v[72:73], v[78:79]
	v_pk_fma_f32 v[76:77], v[40:41], v[74:75], v[76:77]
	v_pk_fma_f32 v[78:79], v[20:21], v[74:75], v[72:73]
	ds_read_b128 v[72:75], v103 offset:54272
	s_waitcnt lgkmcnt(0)
	v_pk_fma_f32 v[76:77], v[46:47], v[72:73], v[76:77]
	v_pk_fma_f32 v[72:73], v[26:27], v[72:73], v[78:79]
	v_pk_fma_f32 v[76:77], v[44:45], v[74:75], v[76:77]
	v_pk_fma_f32 v[78:79], v[24:25], v[74:75], v[72:73]
	ds_read_b128 v[72:75], v103 offset:55296
	s_waitcnt lgkmcnt(0)
	v_pk_fma_f32 v[76:77], v[50:51], v[72:73], v[76:77]
	v_pk_fma_f32 v[72:73], v[18:19], v[72:73], v[78:79]
	v_pk_fma_f32 v[76:77], v[48:49], v[74:75], v[76:77]
	v_pk_fma_f32 v[78:79], v[16:17], v[74:75], v[72:73]
	ds_read_b128 v[72:75], v103 offset:56320
	s_waitcnt lgkmcnt(0)
	v_pk_fma_f32 v[76:77], v[54:55], v[72:73], v[76:77]
	v_pk_fma_f32 v[72:73], v[12:13], v[72:73], v[78:79]
	v_pk_fma_f32 v[76:77], v[52:53], v[74:75], v[76:77]
	v_pk_fma_f32 v[72:73], v[10:11], v[74:75], v[72:73]
	v_add_f32_e32 v88, v76, v77
	v_add_f32_e32 v72, v72, v73
	ds_read_b128 v[74:77], v103 offset:57344
	s_waitcnt lgkmcnt(0)
	v_pk_fma_f32 v[78:79], v[4:5], v[74:75], 0 op_sel_hi:[1,1,0]
	v_pk_fma_f32 v[74:75], v[58:59], v[74:75], 0 op_sel_hi:[1,1,0]
	v_pk_fma_f32 v[78:79], v[2:3], v[76:77], v[78:79]
	v_pk_fma_f32 v[96:97], v[56:57], v[76:77], v[74:75]
	ds_read_b128 v[74:77], v103 offset:58368
	s_waitcnt lgkmcnt(0)
	v_pk_fma_f32 v[78:79], v[8:9], v[74:75], v[78:79]
	v_pk_fma_f32 v[74:75], v[66:67], v[74:75], v[96:97]
	v_pk_fma_f32 v[78:79], v[6:7], v[76:77], v[78:79]
	v_pk_fma_f32 v[96:97], v[62:63], v[76:77], v[74:75]
	ds_read_b128 v[74:77], v103 offset:59392
	s_waitcnt lgkmcnt(0)
	v_pk_fma_f32 v[78:79], v[34:35], v[74:75], v[78:79]
	v_pk_fma_f32 v[74:75], v[70:71], v[74:75], v[96:97]
	v_pk_fma_f32 v[78:79], v[32:33], v[76:77], v[78:79]
	v_pk_fma_f32 v[96:97], v[68:69], v[76:77], v[74:75]
	ds_read_b128 v[74:77], v103 offset:60416
	s_waitcnt lgkmcnt(0)
	v_pk_fma_f32 v[78:79], v[38:39], v[74:75], v[78:79]
	v_pk_fma_f32 v[74:75], v[30:31], v[74:75], v[96:97]
	v_pk_fma_f32 v[78:79], v[36:37], v[76:77], v[78:79]
	v_pk_fma_f32 v[96:97], v[28:29], v[76:77], v[74:75]
	ds_read_b128 v[74:77], v103 offset:61440
	s_waitcnt lgkmcnt(0)
	v_pk_fma_f32 v[78:79], v[42:43], v[74:75], v[78:79]
	v_pk_fma_f32 v[74:75], v[22:23], v[74:75], v[96:97]
	v_pk_fma_f32 v[78:79], v[40:41], v[76:77], v[78:79]
	v_pk_fma_f32 v[96:97], v[20:21], v[76:77], v[74:75]
	ds_read_b128 v[74:77], v103 offset:62464
	s_waitcnt lgkmcnt(0)
	v_pk_fma_f32 v[78:79], v[46:47], v[74:75], v[78:79]
	v_pk_fma_f32 v[74:75], v[26:27], v[74:75], v[96:97]
	v_pk_fma_f32 v[78:79], v[44:45], v[76:77], v[78:79]
	v_pk_fma_f32 v[96:97], v[24:25], v[76:77], v[74:75]
	ds_read_b128 v[74:77], v103 offset:63488
	s_waitcnt lgkmcnt(0)
	v_pk_fma_f32 v[78:79], v[50:51], v[74:75], v[78:79]
	v_pk_fma_f32 v[74:75], v[18:19], v[74:75], v[96:97]
	v_pk_fma_f32 v[78:79], v[48:49], v[76:77], v[78:79]
	v_pk_fma_f32 v[96:97], v[16:17], v[76:77], v[74:75]
	ds_read_b128 v[74:77], v103 offset:64512
	s_waitcnt lgkmcnt(0)
	v_pk_fma_f32 v[78:79], v[54:55], v[74:75], v[78:79]
	v_pk_fma_f32 v[74:75], v[12:13], v[74:75], v[96:97]
	v_pk_fma_f32 v[78:79], v[52:53], v[76:77], v[78:79]
	v_pk_fma_f32 v[74:75], v[10:11], v[76:77], v[74:75]
	v_add_f32_e32 v89, v78, v79
	v_add_f32_e32 v73, v74, v75
	v_add_u32_e32 v74, 0x10000, v103
	ds_read_b128 v[74:77], v74
	s_waitcnt lgkmcnt(0)
	v_pk_fma_f32 v[78:79], v[4:5], v[74:75], 0 op_sel_hi:[1,1,0]
	v_pk_fma_f32 v[74:75], v[58:59], v[74:75], 0 op_sel_hi:[1,1,0]
	v_pk_fma_f32 v[78:79], v[2:3], v[76:77], v[78:79]
	v_pk_fma_f32 v[96:97], v[56:57], v[76:77], v[74:75]
	v_add_u32_e32 v74, 0x10400, v103
	ds_read_b128 v[74:77], v74
	s_waitcnt lgkmcnt(0)
	v_pk_fma_f32 v[78:79], v[8:9], v[74:75], v[78:79]
	v_pk_fma_f32 v[74:75], v[66:67], v[74:75], v[96:97]
	v_pk_fma_f32 v[78:79], v[6:7], v[76:77], v[78:79]
	v_pk_fma_f32 v[96:97], v[62:63], v[76:77], v[74:75]
	v_add_u32_e32 v74, 0x10800, v103
	ds_read_b128 v[74:77], v74
	s_waitcnt lgkmcnt(0)
	v_pk_fma_f32 v[78:79], v[34:35], v[74:75], v[78:79]
	v_pk_fma_f32 v[74:75], v[70:71], v[74:75], v[96:97]
	v_pk_fma_f32 v[78:79], v[32:33], v[76:77], v[78:79]
	v_pk_fma_f32 v[96:97], v[68:69], v[76:77], v[74:75]
	v_add_u32_e32 v74, 0x10c00, v103
	ds_read_b128 v[74:77], v74
	s_waitcnt lgkmcnt(0)
	v_pk_fma_f32 v[78:79], v[38:39], v[74:75], v[78:79]
	v_pk_fma_f32 v[74:75], v[30:31], v[74:75], v[96:97]
	v_pk_fma_f32 v[78:79], v[36:37], v[76:77], v[78:79]
	v_pk_fma_f32 v[96:97], v[28:29], v[76:77], v[74:75]
	v_add_u32_e32 v74, 0x11000, v103
	ds_read_b128 v[74:77], v74
	s_waitcnt lgkmcnt(0)
	v_pk_fma_f32 v[78:79], v[42:43], v[74:75], v[78:79]
	v_pk_fma_f32 v[74:75], v[22:23], v[74:75], v[96:97]
	v_pk_fma_f32 v[78:79], v[40:41], v[76:77], v[78:79]
	v_pk_fma_f32 v[96:97], v[20:21], v[76:77], v[74:75]
	v_add_u32_e32 v74, 0x11400, v103
	ds_read_b128 v[74:77], v74
	s_waitcnt lgkmcnt(0)
	v_pk_fma_f32 v[78:79], v[46:47], v[74:75], v[78:79]
	v_pk_fma_f32 v[74:75], v[26:27], v[74:75], v[96:97]
	v_pk_fma_f32 v[78:79], v[44:45], v[76:77], v[78:79]
	v_pk_fma_f32 v[96:97], v[24:25], v[76:77], v[74:75]
	v_add_u32_e32 v74, 0x11800, v103
	ds_read_b128 v[74:77], v74
	s_waitcnt lgkmcnt(0)
	v_pk_fma_f32 v[78:79], v[50:51], v[74:75], v[78:79]
	v_pk_fma_f32 v[74:75], v[18:19], v[74:75], v[96:97]
	v_pk_fma_f32 v[78:79], v[48:49], v[76:77], v[78:79]
	v_pk_fma_f32 v[96:97], v[16:17], v[76:77], v[74:75]
	v_add_u32_e32 v74, 0x11c00, v103
	ds_read_b128 v[74:77], v74
	s_waitcnt lgkmcnt(0)
	v_pk_fma_f32 v[78:79], v[54:55], v[74:75], v[78:79]
	v_pk_fma_f32 v[74:75], v[12:13], v[74:75], v[96:97]
	v_pk_fma_f32 v[78:79], v[52:53], v[76:77], v[78:79]
	v_pk_fma_f32 v[74:75], v[10:11], v[76:77], v[74:75]
	v_add_f32_e32 v96, v78, v79
	v_add_f32_e32 v74, v74, v75
	v_add_u32_e32 v75, 0x12000, v103
	ds_read_b128 v[76:79], v75
	v_add_u32_e32 v75, 0x12400, v103
	s_waitcnt lgkmcnt(0)
	v_pk_fma_f32 v[98:99], v[4:5], v[76:77], 0 op_sel_hi:[1,1,0]
	v_pk_fma_f32 v[76:77], v[58:59], v[76:77], 0 op_sel_hi:[1,1,0]
	v_pk_fma_f32 v[98:99], v[2:3], v[78:79], v[98:99]
	v_pk_fma_f32 v[100:101], v[56:57], v[78:79], v[76:77]
	ds_read_b128 v[76:79], v75
	v_add_u32_e32 v75, 0x12800, v103
	s_waitcnt lgkmcnt(0)
	v_pk_fma_f32 v[98:99], v[8:9], v[76:77], v[98:99]
	v_pk_fma_f32 v[76:77], v[66:67], v[76:77], v[100:101]
	v_pk_fma_f32 v[98:99], v[6:7], v[78:79], v[98:99]
	v_pk_fma_f32 v[100:101], v[62:63], v[78:79], v[76:77]
	ds_read_b128 v[76:79], v75
	v_add_u32_e32 v75, 0x12c00, v103
	s_waitcnt lgkmcnt(0)
	v_pk_fma_f32 v[98:99], v[34:35], v[76:77], v[98:99]
	v_pk_fma_f32 v[76:77], v[70:71], v[76:77], v[100:101]
	v_pk_fma_f32 v[98:99], v[32:33], v[78:79], v[98:99]
	v_pk_fma_f32 v[100:101], v[68:69], v[78:79], v[76:77]
	ds_read_b128 v[76:79], v75
	v_add_u32_e32 v75, 0x13000, v103
	s_waitcnt lgkmcnt(0)
	v_pk_fma_f32 v[98:99], v[38:39], v[76:77], v[98:99]
	v_pk_fma_f32 v[76:77], v[30:31], v[76:77], v[100:101]
	v_pk_fma_f32 v[98:99], v[36:37], v[78:79], v[98:99]
	v_pk_fma_f32 v[100:101], v[28:29], v[78:79], v[76:77]
	ds_read_b128 v[76:79], v75
	v_add_u32_e32 v75, 0x13400, v103
	s_waitcnt lgkmcnt(0)
	v_pk_fma_f32 v[98:99], v[42:43], v[76:77], v[98:99]
	v_pk_fma_f32 v[76:77], v[22:23], v[76:77], v[100:101]
	v_pk_fma_f32 v[98:99], v[40:41], v[78:79], v[98:99]
	v_pk_fma_f32 v[100:101], v[20:21], v[78:79], v[76:77]
	ds_read_b128 v[76:79], v75
	v_add_u32_e32 v75, 0x13800, v103
	s_waitcnt lgkmcnt(0)
	v_pk_fma_f32 v[98:99], v[46:47], v[76:77], v[98:99]
	v_pk_fma_f32 v[76:77], v[26:27], v[76:77], v[100:101]
	v_pk_fma_f32 v[98:99], v[44:45], v[78:79], v[98:99]
	v_pk_fma_f32 v[100:101], v[24:25], v[78:79], v[76:77]
	ds_read_b128 v[76:79], v75
	v_add_u32_e32 v75, 0x13c00, v103
	s_waitcnt lgkmcnt(0)
	v_pk_fma_f32 v[98:99], v[50:51], v[76:77], v[98:99]
	v_pk_fma_f32 v[76:77], v[18:19], v[76:77], v[100:101]
	v_pk_fma_f32 v[98:99], v[48:49], v[78:79], v[98:99]
	v_pk_fma_f32 v[100:101], v[16:17], v[78:79], v[76:77]
	ds_read_b128 v[76:79], v75
	s_waitcnt lgkmcnt(0)
	v_pk_fma_f32 v[98:99], v[54:55], v[76:77], v[98:99]
	v_pk_fma_f32 v[76:77], v[12:13], v[76:77], v[100:101]
	v_pk_fma_f32 v[98:99], v[52:53], v[78:79], v[98:99]
	v_pk_fma_f32 v[76:77], v[10:11], v[78:79], v[76:77]
	v_add_f32_e32 v97, v98, v99
	v_add_f32_e32 v75, v76, v77
	v_add_u32_e32 v76, 0x14000, v103
	ds_read_b128 v[76:79], v76
	s_waitcnt lgkmcnt(0)
	v_pk_fma_f32 v[98:99], v[4:5], v[76:77], 0 op_sel_hi:[1,1,0]
	v_pk_fma_f32 v[76:77], v[58:59], v[76:77], 0 op_sel_hi:[1,1,0]
	v_pk_fma_f32 v[98:99], v[2:3], v[78:79], v[98:99]
	v_pk_fma_f32 v[100:101], v[56:57], v[78:79], v[76:77]
	v_add_u32_e32 v76, 0x14400, v103
	ds_read_b128 v[76:79], v76
	s_waitcnt lgkmcnt(0)
	v_pk_fma_f32 v[98:99], v[8:9], v[76:77], v[98:99]
	v_pk_fma_f32 v[76:77], v[66:67], v[76:77], v[100:101]
	v_pk_fma_f32 v[98:99], v[6:7], v[78:79], v[98:99]
	v_pk_fma_f32 v[100:101], v[62:63], v[78:79], v[76:77]
	v_add_u32_e32 v76, 0x14800, v103
	ds_read_b128 v[76:79], v76
	s_waitcnt lgkmcnt(0)
	v_pk_fma_f32 v[98:99], v[34:35], v[76:77], v[98:99]
	v_pk_fma_f32 v[76:77], v[70:71], v[76:77], v[100:101]
	v_pk_fma_f32 v[98:99], v[32:33], v[78:79], v[98:99]
	v_pk_fma_f32 v[100:101], v[68:69], v[78:79], v[76:77]
	v_add_u32_e32 v76, 0x14c00, v103
	ds_read_b128 v[76:79], v76
	s_waitcnt lgkmcnt(0)
	v_pk_fma_f32 v[98:99], v[38:39], v[76:77], v[98:99]
	v_pk_fma_f32 v[76:77], v[30:31], v[76:77], v[100:101]
	v_pk_fma_f32 v[98:99], v[36:37], v[78:79], v[98:99]
	v_pk_fma_f32 v[100:101], v[28:29], v[78:79], v[76:77]
	v_add_u32_e32 v76, 0x15000, v103
	ds_read_b128 v[76:79], v76
	s_waitcnt lgkmcnt(0)
	v_pk_fma_f32 v[98:99], v[42:43], v[76:77], v[98:99]
	v_pk_fma_f32 v[76:77], v[22:23], v[76:77], v[100:101]
	v_pk_fma_f32 v[98:99], v[40:41], v[78:79], v[98:99]
	v_pk_fma_f32 v[100:101], v[20:21], v[78:79], v[76:77]
	v_add_u32_e32 v76, 0x15400, v103
	ds_read_b128 v[76:79], v76
	s_waitcnt lgkmcnt(0)
	v_pk_fma_f32 v[98:99], v[46:47], v[76:77], v[98:99]
	v_pk_fma_f32 v[76:77], v[26:27], v[76:77], v[100:101]
	v_pk_fma_f32 v[98:99], v[44:45], v[78:79], v[98:99]
	v_pk_fma_f32 v[100:101], v[24:25], v[78:79], v[76:77]
	v_add_u32_e32 v76, 0x15800, v103
	ds_read_b128 v[76:79], v76
	s_waitcnt lgkmcnt(0)
	v_pk_fma_f32 v[98:99], v[50:51], v[76:77], v[98:99]
	v_pk_fma_f32 v[76:77], v[18:19], v[76:77], v[100:101]
	v_pk_fma_f32 v[98:99], v[48:49], v[78:79], v[98:99]
	v_pk_fma_f32 v[100:101], v[16:17], v[78:79], v[76:77]
	v_add_u32_e32 v76, 0x15c00, v103
	ds_read_b128 v[76:79], v76
	s_waitcnt lgkmcnt(0)
	v_pk_fma_f32 v[98:99], v[54:55], v[76:77], v[98:99]
	v_pk_fma_f32 v[76:77], v[12:13], v[76:77], v[100:101]
	v_pk_fma_f32 v[98:99], v[52:53], v[78:79], v[98:99]
	v_pk_fma_f32 v[76:77], v[10:11], v[78:79], v[76:77]
	v_add_f32_e32 v98, v98, v99
	v_add_f32_e32 v76, v76, v77
	v_add_u32_e32 v77, 0x16000, v103
	ds_read_b128 v[104:107], v77
	v_add_u32_e32 v77, 0x16400, v103
	s_waitcnt lgkmcnt(0)
	v_pk_fma_f32 v[78:79], v[4:5], v[104:105], 0 op_sel_hi:[1,1,0]
	v_pk_fma_f32 v[100:101], v[58:59], v[104:105], 0 op_sel_hi:[1,1,0]
	v_pk_fma_f32 v[78:79], v[2:3], v[106:107], v[78:79]
	v_pk_fma_f32 v[100:101], v[56:57], v[106:107], v[100:101]
	ds_read_b128 v[104:107], v77
	v_add_u32_e32 v77, 0x16800, v103
	s_waitcnt lgkmcnt(0)
	v_pk_fma_f32 v[78:79], v[8:9], v[104:105], v[78:79]
	v_pk_fma_f32 v[100:101], v[66:67], v[104:105], v[100:101]
	v_pk_fma_f32 v[78:79], v[6:7], v[106:107], v[78:79]
	v_pk_fma_f32 v[100:101], v[62:63], v[106:107], v[100:101]
	ds_read_b128 v[104:107], v77
	v_add_u32_e32 v77, 0x16c00, v103
	s_waitcnt lgkmcnt(0)
	v_pk_fma_f32 v[78:79], v[34:35], v[104:105], v[78:79]
	v_pk_fma_f32 v[100:101], v[70:71], v[104:105], v[100:101]
	v_pk_fma_f32 v[78:79], v[32:33], v[106:107], v[78:79]
	v_pk_fma_f32 v[100:101], v[68:69], v[106:107], v[100:101]
	ds_read_b128 v[104:107], v77
	v_add_u32_e32 v77, 0x17000, v103
	s_waitcnt lgkmcnt(0)
	v_pk_fma_f32 v[78:79], v[38:39], v[104:105], v[78:79]
	v_pk_fma_f32 v[100:101], v[30:31], v[104:105], v[100:101]
	v_pk_fma_f32 v[78:79], v[36:37], v[106:107], v[78:79]
	v_pk_fma_f32 v[100:101], v[28:29], v[106:107], v[100:101]
	ds_read_b128 v[104:107], v77
	v_add_u32_e32 v77, 0x17400, v103
	s_waitcnt lgkmcnt(0)
	v_pk_fma_f32 v[78:79], v[42:43], v[104:105], v[78:79]
	v_pk_fma_f32 v[100:101], v[22:23], v[104:105], v[100:101]
	v_pk_fma_f32 v[78:79], v[40:41], v[106:107], v[78:79]
	v_pk_fma_f32 v[100:101], v[20:21], v[106:107], v[100:101]
	ds_read_b128 v[104:107], v77
	v_add_u32_e32 v77, 0x17800, v103
	s_waitcnt lgkmcnt(0)
	v_pk_fma_f32 v[78:79], v[46:47], v[104:105], v[78:79]
	v_pk_fma_f32 v[100:101], v[26:27], v[104:105], v[100:101]
	v_pk_fma_f32 v[78:79], v[44:45], v[106:107], v[78:79]
	v_pk_fma_f32 v[100:101], v[24:25], v[106:107], v[100:101]
	ds_read_b128 v[104:107], v77
	v_add_u32_e32 v77, 0x17c00, v103
	s_waitcnt lgkmcnt(0)
	v_pk_fma_f32 v[78:79], v[50:51], v[104:105], v[78:79]
	v_pk_fma_f32 v[100:101], v[18:19], v[104:105], v[100:101]
	v_pk_fma_f32 v[78:79], v[48:49], v[106:107], v[78:79]
	v_pk_fma_f32 v[100:101], v[16:17], v[106:107], v[100:101]
	ds_read_b128 v[104:107], v77
	s_waitcnt lgkmcnt(0)
	v_pk_fma_f32 v[78:79], v[54:55], v[104:105], v[78:79]
	v_pk_fma_f32 v[100:101], v[12:13], v[104:105], v[100:101]
	v_pk_fma_f32 v[78:79], v[52:53], v[106:107], v[78:79]
	v_pk_fma_f32 v[100:101], v[10:11], v[106:107], v[100:101]
	v_add_f32_e32 v99, v78, v79
	v_add_f32_e32 v77, v100, v101
	v_add_u32_e32 v78, 0x18000, v103
	ds_read_b128 v[104:107], v78
	s_waitcnt lgkmcnt(0)
	v_pk_fma_f32 v[78:79], v[4:5], v[104:105], 0 op_sel_hi:[1,1,0]
	v_pk_fma_f32 v[100:101], v[58:59], v[104:105], 0 op_sel_hi:[1,1,0]
	v_pk_fma_f32 v[78:79], v[2:3], v[106:107], v[78:79]
	v_pk_fma_f32 v[100:101], v[56:57], v[106:107], v[100:101]
	ds_read_b128 v[104:107], v80
	v_add_u32_e32 v80, 0x18800, v103
	s_waitcnt lgkmcnt(0)
	v_pk_fma_f32 v[78:79], v[8:9], v[104:105], v[78:79]
	v_pk_fma_f32 v[100:101], v[66:67], v[104:105], v[100:101]
	v_pk_fma_f32 v[78:79], v[6:7], v[106:107], v[78:79]
	v_pk_fma_f32 v[100:101], v[62:63], v[106:107], v[100:101]
	ds_read_b128 v[104:107], v80
	v_add_u32_e32 v80, 0x18c00, v103
	s_waitcnt lgkmcnt(0)
	v_pk_fma_f32 v[78:79], v[34:35], v[104:105], v[78:79]
	v_pk_fma_f32 v[100:101], v[70:71], v[104:105], v[100:101]
	v_pk_fma_f32 v[78:79], v[32:33], v[106:107], v[78:79]
	v_pk_fma_f32 v[100:101], v[68:69], v[106:107], v[100:101]
	ds_read_b128 v[104:107], v80
	v_add_u32_e32 v80, 0x19000, v103
	s_waitcnt lgkmcnt(0)
	v_pk_fma_f32 v[78:79], v[38:39], v[104:105], v[78:79]
	v_pk_fma_f32 v[100:101], v[30:31], v[104:105], v[100:101]
	v_pk_fma_f32 v[78:79], v[36:37], v[106:107], v[78:79]
	v_pk_fma_f32 v[100:101], v[28:29], v[106:107], v[100:101]
	ds_read_b128 v[104:107], v80
	v_add_u32_e32 v80, 0x19400, v103
	s_waitcnt lgkmcnt(0)
	v_pk_fma_f32 v[78:79], v[42:43], v[104:105], v[78:79]
	v_pk_fma_f32 v[100:101], v[22:23], v[104:105], v[100:101]
	v_pk_fma_f32 v[78:79], v[40:41], v[106:107], v[78:79]
	v_pk_fma_f32 v[100:101], v[20:21], v[106:107], v[100:101]
	ds_read_b128 v[104:107], v80
	v_add_u32_e32 v80, 0x19800, v103
	s_waitcnt lgkmcnt(0)
	v_pk_fma_f32 v[78:79], v[46:47], v[104:105], v[78:79]
	v_pk_fma_f32 v[100:101], v[26:27], v[104:105], v[100:101]
	v_pk_fma_f32 v[78:79], v[44:45], v[106:107], v[78:79]
	v_pk_fma_f32 v[100:101], v[24:25], v[106:107], v[100:101]
	ds_read_b128 v[104:107], v80
	v_add_u32_e32 v80, 0x19c00, v103
	s_waitcnt lgkmcnt(0)
	v_pk_fma_f32 v[78:79], v[50:51], v[104:105], v[78:79]
	v_pk_fma_f32 v[100:101], v[18:19], v[104:105], v[100:101]
	v_pk_fma_f32 v[78:79], v[48:49], v[106:107], v[78:79]
	v_pk_fma_f32 v[100:101], v[16:17], v[106:107], v[100:101]
	ds_read_b128 v[104:107], v80
	v_add_u32_e32 v80, 0x1c000, v103
	s_waitcnt lgkmcnt(0)
	v_pk_fma_f32 v[78:79], v[54:55], v[104:105], v[78:79]
	v_pk_fma_f32 v[100:101], v[12:13], v[104:105], v[100:101]
	v_pk_fma_f32 v[78:79], v[52:53], v[106:107], v[78:79]
	v_pk_fma_f32 v[104:105], v[10:11], v[106:107], v[100:101]
	v_add_f32_e32 v100, v78, v79
	v_add_f32_e32 v78, v104, v105
	v_add_u32_e32 v79, 0x1a000, v103
	ds_read_b128 v[104:107], v79
	v_add_u32_e32 v79, 0x1a400, v103
	s_waitcnt lgkmcnt(0)
	v_pk_fma_f32 v[108:109], v[4:5], v[104:105], 0 op_sel_hi:[1,1,0]
	v_pk_fma_f32 v[104:105], v[58:59], v[104:105], 0 op_sel_hi:[1,1,0]
	v_pk_fma_f32 v[108:109], v[2:3], v[106:107], v[108:109]
	v_pk_fma_f32 v[110:111], v[56:57], v[106:107], v[104:105]
	ds_read_b128 v[104:107], v79
	v_add_u32_e32 v79, 0x1a800, v103
	s_waitcnt lgkmcnt(0)
	v_pk_fma_f32 v[108:109], v[8:9], v[104:105], v[108:109]
	v_pk_fma_f32 v[104:105], v[66:67], v[104:105], v[110:111]
	v_pk_fma_f32 v[108:109], v[6:7], v[106:107], v[108:109]
	v_pk_fma_f32 v[110:111], v[62:63], v[106:107], v[104:105]
	ds_read_b128 v[104:107], v79
	v_add_u32_e32 v79, 0x1ac00, v103
	s_waitcnt lgkmcnt(0)
	v_pk_fma_f32 v[108:109], v[34:35], v[104:105], v[108:109]
	v_pk_fma_f32 v[104:105], v[70:71], v[104:105], v[110:111]
	v_pk_fma_f32 v[108:109], v[32:33], v[106:107], v[108:109]
	v_pk_fma_f32 v[110:111], v[68:69], v[106:107], v[104:105]
	ds_read_b128 v[104:107], v79
	v_add_u32_e32 v79, 0x1b000, v103
	s_waitcnt lgkmcnt(0)
	v_pk_fma_f32 v[108:109], v[38:39], v[104:105], v[108:109]
	v_pk_fma_f32 v[104:105], v[30:31], v[104:105], v[110:111]
	v_pk_fma_f32 v[108:109], v[36:37], v[106:107], v[108:109]
	v_pk_fma_f32 v[110:111], v[28:29], v[106:107], v[104:105]
	ds_read_b128 v[104:107], v79
	v_add_u32_e32 v79, 0x1b400, v103
	s_waitcnt lgkmcnt(0)
	v_pk_fma_f32 v[108:109], v[42:43], v[104:105], v[108:109]
	v_pk_fma_f32 v[104:105], v[22:23], v[104:105], v[110:111]
	v_pk_fma_f32 v[108:109], v[40:41], v[106:107], v[108:109]
	v_pk_fma_f32 v[110:111], v[20:21], v[106:107], v[104:105]
	ds_read_b128 v[104:107], v79
	v_add_u32_e32 v79, 0x1b800, v103
	s_waitcnt lgkmcnt(0)
	v_pk_fma_f32 v[108:109], v[46:47], v[104:105], v[108:109]
	v_pk_fma_f32 v[104:105], v[26:27], v[104:105], v[110:111]
	v_pk_fma_f32 v[108:109], v[44:45], v[106:107], v[108:109]
	v_pk_fma_f32 v[110:111], v[24:25], v[106:107], v[104:105]
	ds_read_b128 v[104:107], v79
	v_add_u32_e32 v79, 0x1bc00, v103
	s_waitcnt lgkmcnt(0)
	v_pk_fma_f32 v[108:109], v[50:51], v[104:105], v[108:109]
	v_pk_fma_f32 v[104:105], v[18:19], v[104:105], v[110:111]
	v_pk_fma_f32 v[108:109], v[48:49], v[106:107], v[108:109]
	v_pk_fma_f32 v[110:111], v[16:17], v[106:107], v[104:105]
	ds_read_b128 v[104:107], v79
	s_waitcnt lgkmcnt(0)
	v_pk_fma_f32 v[108:109], v[54:55], v[104:105], v[108:109]
	v_pk_fma_f32 v[104:105], v[12:13], v[104:105], v[110:111]
	v_pk_fma_f32 v[108:109], v[52:53], v[106:107], v[108:109]
	v_pk_fma_f32 v[104:105], v[10:11], v[106:107], v[104:105]
	v_add_f32_e32 v101, v108, v109
	v_add_f32_e32 v79, v104, v105
	ds_read_b128 v[104:107], v80
	v_add_u32_e32 v80, 0x1c400, v103
	s_waitcnt lgkmcnt(0)
	v_pk_fma_f32 v[108:109], v[4:5], v[104:105], 0 op_sel_hi:[1,1,0]
	v_pk_fma_f32 v[104:105], v[58:59], v[104:105], 0 op_sel_hi:[1,1,0]
	v_pk_fma_f32 v[108:109], v[2:3], v[106:107], v[108:109]
	v_pk_fma_f32 v[110:111], v[56:57], v[106:107], v[104:105]
	ds_read_b128 v[104:107], v80
	v_add_u32_e32 v80, 0x1c800, v103
	s_waitcnt lgkmcnt(0)
	v_pk_fma_f32 v[108:109], v[8:9], v[104:105], v[108:109]
	v_pk_fma_f32 v[104:105], v[66:67], v[104:105], v[110:111]
	v_pk_fma_f32 v[108:109], v[6:7], v[106:107], v[108:109]
	v_pk_fma_f32 v[110:111], v[62:63], v[106:107], v[104:105]
	ds_read_b128 v[104:107], v80
	v_add_u32_e32 v80, 0x1cc00, v103
	s_waitcnt lgkmcnt(0)
	v_pk_fma_f32 v[108:109], v[34:35], v[104:105], v[108:109]
	v_pk_fma_f32 v[104:105], v[70:71], v[104:105], v[110:111]
	v_pk_fma_f32 v[108:109], v[32:33], v[106:107], v[108:109]
	v_pk_fma_f32 v[110:111], v[68:69], v[106:107], v[104:105]
	ds_read_b128 v[104:107], v80
	v_add_u32_e32 v80, 0x1d000, v103
	s_waitcnt lgkmcnt(0)
	v_pk_fma_f32 v[108:109], v[38:39], v[104:105], v[108:109]
	v_pk_fma_f32 v[104:105], v[30:31], v[104:105], v[110:111]
	v_pk_fma_f32 v[108:109], v[36:37], v[106:107], v[108:109]
	v_pk_fma_f32 v[110:111], v[28:29], v[106:107], v[104:105]
	ds_read_b128 v[104:107], v80
	v_add_u32_e32 v80, 0x1d400, v103
	s_waitcnt lgkmcnt(0)
	v_pk_fma_f32 v[108:109], v[42:43], v[104:105], v[108:109]
	v_pk_fma_f32 v[104:105], v[22:23], v[104:105], v[110:111]
	v_pk_fma_f32 v[108:109], v[40:41], v[106:107], v[108:109]
	v_pk_fma_f32 v[110:111], v[20:21], v[106:107], v[104:105]
	ds_read_b128 v[104:107], v80
	v_add_u32_e32 v80, 0x1d800, v103
	s_waitcnt lgkmcnt(0)
	v_pk_fma_f32 v[108:109], v[46:47], v[104:105], v[108:109]
	v_pk_fma_f32 v[104:105], v[26:27], v[104:105], v[110:111]
	v_pk_fma_f32 v[108:109], v[44:45], v[106:107], v[108:109]
	v_pk_fma_f32 v[110:111], v[24:25], v[106:107], v[104:105]
	ds_read_b128 v[104:107], v80
	v_add_u32_e32 v80, 0x1dc00, v103
	s_waitcnt lgkmcnt(0)
	v_pk_fma_f32 v[108:109], v[50:51], v[104:105], v[108:109]
	v_pk_fma_f32 v[104:105], v[18:19], v[104:105], v[110:111]
	v_pk_fma_f32 v[108:109], v[48:49], v[106:107], v[108:109]
	v_pk_fma_f32 v[110:111], v[16:17], v[106:107], v[104:105]
	ds_read_b128 v[104:107], v80
	s_waitcnt lgkmcnt(0)
	v_pk_fma_f32 v[108:109], v[54:55], v[104:105], v[108:109]
	v_pk_fma_f32 v[104:105], v[12:13], v[104:105], v[110:111]
	v_pk_fma_f32 v[108:109], v[52:53], v[106:107], v[108:109]
	v_pk_fma_f32 v[104:105], v[10:11], v[106:107], v[104:105]
	v_add_f32_e32 v102, v108, v109
	v_add_f32_e32 v80, v104, v105
	v_add_u32_e32 v104, 0x1e000, v103
	ds_read_b128 v[104:107], v104
	s_waitcnt lgkmcnt(0)
	v_pk_fma_f32 v[4:5], v[4:5], v[104:105], 0 op_sel_hi:[1,1,0]
	s_nop 0
	v_pk_fma_f32 v[108:109], v[2:3], v[106:107], v[4:5]
	v_pk_fma_f32 v[2:3], v[58:59], v[104:105], 0 op_sel_hi:[1,1,0]
	s_nop 0
	v_pk_fma_f32 v[56:57], v[56:57], v[106:107], v[2:3]
	v_add_u32_e32 v2, 0x1e400, v103
	ds_read_b128 v[2:5], v2
	s_waitcnt lgkmcnt(0)
	v_pk_fma_f32 v[8:9], v[8:9], v[2:3], v[108:109]
	v_pk_fma_f32 v[2:3], v[66:67], v[2:3], v[56:57]
	v_pk_fma_f32 v[6:7], v[6:7], v[4:5], v[8:9]
	v_pk_fma_f32 v[8:9], v[62:63], v[4:5], v[2:3]
	v_add_u32_e32 v2, 0x1e800, v103
	ds_read_b128 v[2:5], v2
	s_waitcnt lgkmcnt(0)
	v_pk_fma_f32 v[6:7], v[34:35], v[2:3], v[6:7]
	v_pk_fma_f32 v[2:3], v[70:71], v[2:3], v[8:9]
	v_pk_fma_f32 v[6:7], v[32:33], v[4:5], v[6:7]
	v_pk_fma_f32 v[8:9], v[68:69], v[4:5], v[2:3]
	v_add_u32_e32 v2, 0x1ec00, v103
	ds_read_b128 v[2:5], v2
	s_waitcnt lgkmcnt(0)
	v_pk_fma_f32 v[6:7], v[38:39], v[2:3], v[6:7]
	v_pk_fma_f32 v[2:3], v[30:31], v[2:3], v[8:9]
	v_pk_fma_f32 v[6:7], v[36:37], v[4:5], v[6:7]
	v_pk_fma_f32 v[8:9], v[28:29], v[4:5], v[2:3]
	v_add_u32_e32 v2, 0x1f000, v103
	ds_read_b128 v[2:5], v2
	s_waitcnt lgkmcnt(0)
	v_pk_fma_f32 v[6:7], v[42:43], v[2:3], v[6:7]
	v_pk_fma_f32 v[2:3], v[22:23], v[2:3], v[8:9]
	v_pk_fma_f32 v[6:7], v[40:41], v[4:5], v[6:7]
	v_pk_fma_f32 v[8:9], v[20:21], v[4:5], v[2:3]
	v_add_u32_e32 v2, 0x1f400, v103
	ds_read_b128 v[2:5], v2
	s_waitcnt lgkmcnt(0)
	v_pk_fma_f32 v[6:7], v[46:47], v[2:3], v[6:7]
	v_pk_fma_f32 v[2:3], v[26:27], v[2:3], v[8:9]
	v_pk_fma_f32 v[6:7], v[44:45], v[4:5], v[6:7]
	v_pk_fma_f32 v[8:9], v[24:25], v[4:5], v[2:3]
	v_add_u32_e32 v2, 0x1f800, v103
	ds_read_b128 v[2:5], v2
	s_waitcnt lgkmcnt(0)
	v_pk_fma_f32 v[6:7], v[50:51], v[2:3], v[6:7]
	v_pk_fma_f32 v[2:3], v[18:19], v[2:3], v[8:9]
	v_pk_fma_f32 v[6:7], v[48:49], v[4:5], v[6:7]
	v_pk_fma_f32 v[8:9], v[16:17], v[4:5], v[2:3]
	v_add_u32_e32 v2, 0x1fc00, v103
	ds_read_b128 v[2:5], v2
	s_waitcnt lgkmcnt(0)
	v_pk_fma_f32 v[6:7], v[54:55], v[2:3], v[6:7]
	v_pk_fma_f32 v[2:3], v[12:13], v[2:3], v[8:9]
	v_pk_fma_f32 v[6:7], v[52:53], v[4:5], v[6:7]
	v_pk_fma_f32 v[4:5], v[10:11], v[4:5], v[2:3]
	v_and_b32_e32 v3, 32, v1
	v_cmp_eq_u32_e32 vcc, 0, v3
	v_add_f32_e32 v4, v4, v5
	v_add_f32_e32 v2, v6, v7
	v_cndmask_b32_e32 v5, v81, v96, vcc
	ds_bpermute_b32 v5, v95, v5
	v_cndmask_b32_e32 v6, v82, v97, vcc
	ds_bpermute_b32 v6, v95, v6
	v_cndmask_b32_e32 v7, v84, v98, vcc
	ds_bpermute_b32 v7, v95, v7
	v_cndmask_b32_e32 v8, v85, v99, vcc
	ds_bpermute_b32 v8, v95, v8
	v_cndmask_b32_e32 v9, v86, v100, vcc
	v_cndmask_b32_e32 v3, v96, v81, vcc
	ds_bpermute_b32 v9, v95, v9
	v_cndmask_b32_e32 v10, v87, v101, vcc
	s_waitcnt lgkmcnt(4)
	v_add_f32_e32 v3, v3, v5
	v_cndmask_b32_e32 v5, v97, v82, vcc
	ds_bpermute_b32 v10, v95, v10
	v_cndmask_b32_e32 v11, v88, v102, vcc
	s_waitcnt lgkmcnt(4)
	v_add_f32_e32 v6, v5, v6
	v_cndmask_b32_e32 v5, v98, v84, vcc
	ds_bpermute_b32 v11, v95, v11
	s_waitcnt lgkmcnt(4)
	v_add_f32_e32 v7, v5, v7
	v_cndmask_b32_e32 v5, v99, v85, vcc
	s_waitcnt lgkmcnt(3)
	v_add_f32_e32 v8, v5, v8
	v_cndmask_b32_e32 v5, v100, v86, vcc
	s_waitcnt lgkmcnt(2)
	v_add_f32_e32 v5, v5, v9
	v_cndmask_b32_e32 v9, v101, v87, vcc
	s_waitcnt lgkmcnt(1)
	v_add_f32_e32 v9, v9, v10
	v_cndmask_b32_e32 v10, v102, v88, vcc
	s_waitcnt lgkmcnt(0)
	v_add_f32_e32 v10, v10, v11
	v_cndmask_b32_e32 v11, v2, v89, vcc
	v_cndmask_b32_e32 v2, v89, v2, vcc
	ds_bpermute_b32 v2, v95, v2
	s_waitcnt lgkmcnt(0)
	v_add_f32_e32 v11, v11, v2
	v_and_b32_e32 v2, 16, v1
	v_cmp_eq_u32_e64 s[10:11], 0, v2
	s_nop 1
	v_cndmask_b32_e64 v2, v5, v3, s[10:11]
	v_cndmask_b32_e64 v3, v3, v5, s[10:11]
	ds_bpermute_b32 v3, v94, v3
	s_waitcnt lgkmcnt(0)
	v_add_f32_e32 v5, v2, v3
	v_cndmask_b32_e64 v3, v6, v9, s[10:11]
	ds_bpermute_b32 v3, v94, v3
	v_cndmask_b32_e64 v2, v9, v6, s[10:11]
	v_cndmask_b32_e64 v6, v7, v10, s[10:11]
	ds_bpermute_b32 v6, v94, v6
	s_waitcnt lgkmcnt(1)
	v_add_f32_e32 v2, v2, v3
	v_cndmask_b32_e64 v3, v10, v7, s[10:11]
	v_cndmask_b32_e64 v7, v8, v11, s[10:11]
	ds_bpermute_b32 v7, v94, v7
	s_waitcnt lgkmcnt(1)
	v_add_f32_e32 v6, v3, v6
	v_cndmask_b32_e64 v3, v11, v8, s[10:11]
	s_waitcnt lgkmcnt(0)
	v_add_f32_e32 v3, v3, v7
	v_and_b32_e32 v7, 8, v1
	v_cmp_eq_u32_e64 s[12:13], 0, v7
	s_nop 1
	v_cndmask_b32_e64 v7, v6, v5, s[12:13]
	v_cndmask_b32_e64 v5, v5, v6, s[12:13]
	v_cndmask_b32_e64 v6, v3, v2, s[12:13]
	v_cndmask_b32_e64 v2, v2, v3, s[12:13]
	ds_bpermute_b32 v5, v93, v5
	ds_bpermute_b32 v2, v93, v2
	v_and_b32_e32 v3, 4, v1
	v_cmp_eq_u32_e64 s[14:15], 0, v3
	s_waitcnt lgkmcnt(1)
	v_add_f32_e32 v5, v7, v5
	s_waitcnt lgkmcnt(0)
	v_add_f32_e32 v2, v6, v2
	v_cndmask_b32_e64 v3, v2, v5, s[14:15]
	v_cndmask_b32_e64 v2, v5, v2, s[14:15]
	ds_bpermute_b32 v2, v92, v2
	v_and_b32_e32 v5, 3, v1
	v_bfe_u32 v1, v1, 2, 4
	v_cmp_eq_u32_e64 s[16:17], 0, v5
	v_lshlrev_b32_e32 v82, 2, v1
	s_waitcnt lgkmcnt(0)
	v_add_f32_e32 v2, v3, v2
	ds_bpermute_b32 v3, v91, v2
	s_waitcnt lgkmcnt(0)
	v_add_f32_e32 v2, v2, v3
	ds_bpermute_b32 v3, v90, v2
	s_and_saveexec_b64 s[40:41], s[16:17]
	s_cbranch_execz .LBB0_1749
	s_waitcnt lgkmcnt(0)
	v_add_f32_e32 v2, v2, v3
	global_load_dword v3, v82, s[38:39] offset:64
	v_cmp_lt_u32_e64 s[18:19], 7, v1
	s_waitcnt vmcnt(0)
	v_add_f32_e32 v5, v2, v3
	s_and_saveexec_b64 s[8:9], s[18:19]
	s_xor_b64 s[54:55], exec, s[8:9]
	s_cbranch_execz .LBB0_1746
	s_mov_b32 s18, 0xbfb8aa3b
	v_mul_f32_e64 v2, |v5|, s18
	v_exp_f32_e32 v6, v2
	s_lshl_b64 s[8:9], s[30:31], 5
	s_add_u32 s8, s58, s8
	s_addc_u32 s9, s59, s9
	v_lshl_add_u64 v[2:3], s[8:9], 0, v[82:83]
	v_add_f32_e32 v6, 1.0, v6
	s_mov_b32 s8, 0x800000
	v_cmp_gt_f32_e64 s[18:19], s8, v6
	s_movk_i32 s8, 0xffe0
	s_mov_b32 s9, -1
	v_cndmask_b32_e64 v7, 0, 32, s[18:19]
	v_ldexp_f32 v6, v6, v7
	v_log_f32_e32 v6, v6
	v_lshl_add_u64 v[2:3], v[2:3], 0, s[8:9]
	s_mov_b32 s8, 0x3f317217
	v_max_f32_e32 v5, v5, v5
	v_mul_f32_e32 v7, 0x3f317217, v6
	v_fma_f32 v7, v6, s8, -v7
	v_fmac_f32_e32 v7, 0x3377d1cf, v6
	s_mov_b32 s8, 0x7f800000
	v_fmac_f32_e32 v7, 0x3f317217, v6
	v_cmp_lt_f32_e64 s[20:21], |v6|, s8
	v_min_f32_e32 v5, 0, v5
	s_nop 0
	v_cndmask_b32_e64 v6, v6, v7, s[20:21]
	v_mov_b32_e32 v7, 0x41b17218
	v_cndmask_b32_e64 v7, 0, v7, s[18:19]
	v_sub_f32_e32 v6, v6, v7
	v_sub_f32_e32 v5, v5, v6
